# attention epilogue loads hoisted, V^T LDS layout for b128 reads, cross-attn query gains loaded once per tile, P3 carry fold loads batched
# speedup vs baseline: 1.0120x; 1.0120x over previous
.LBB0_180:
	s_or_b64 exec, exec, s[0:1]
	v_and_b32_e32 v37, 64, v182
	v_ashrrev_i32_e32 v59, 6, v36
	v_bfe_u32 v51, v36, 4, 2
	v_and_b32_e32 v56, 15, v36
	v_xor_b32_e32 v36, 1, v182
	v_add_u32_e32 v37, 64, v37
	v_cmp_lt_i32_e32 vcc, v36, v37
	v_lshlrev_b32_e32 v2, 4, v59
	v_min_i32_e32 v57, 6, v59
	v_and_b32_e32 v57, -2, v57
	v_cndmask_b32_e32 v61, v182, v36, vcc
	v_xor_b32_e32 v36, 16, v182
	v_cmp_lt_i32_e32 vcc, v36, v37
	v_lshlrev_b32_e32 v111, 2, v51
	v_lshlrev_b32_e32 v68, 4, v57
	v_cndmask_b32_e32 v66, v182, v36, vcc
	v_xor_b32_e32 v36, 32, v182
	v_cmp_lt_i32_e32 vcc, v36, v37
	v_or_b32_e32 v38, v68, v111
	s_movk_i32 s3, 0x7e
	v_cndmask_b32_e32 v67, v182, v36, vcc
	v_cmp_eq_u32_e32 vcc, 1, v51
	v_or_b32_e32 v39, 2, v38
	v_add_u32_e32 v69, 16, v68
	v_cndmask_b32_e64 v36, 0, 1.0, vcc
	v_cmp_ne_u32_e32 vcc, 0, v51
	v_add_u32_e32 v70, 2, v57
	v_lshlrev_b32_e32 v71, 4, v70
	v_cndmask_b32_e32 v114, -1.0, v36, vcc
	v_or_b32_e32 v36, v2, v56
	v_add_u32_e32 v37, 0x80, v36
	v_cmp_gt_i32_e32 vcc, v38, v36
	v_cmp_le_i32_e64 s[0:1], v38, v37
	s_and_b64 s[0:1], vcc, s[0:1]
	v_cmp_lt_i32_e32 vcc, s84, v38
	s_or_b64 s[4:5], s[22:23], vcc
	s_and_b64 s[0:1], s[0:1], s[4:5]
	v_cmp_ge_i32_e32 vcc, v38, v36
	v_cmp_lt_i32_e64 s[4:5], v38, v37
	s_and_b64 s[4:5], vcc, s[4:5]
	v_cmp_lt_i32_e32 vcc, s3, v38
	v_writelane_b32 v243, s0, 12
	s_or_b64 s[6:7], s[22:23], vcc
	v_cmp_gt_i32_e32 vcc, v39, v36
	v_writelane_b32 v243, s1, 13
	s_and_b64 s[0:1], s[4:5], s[6:7]
	v_cmp_le_i32_e64 s[6:7], v39, v37
	s_and_b64 s[6:7], vcc, s[6:7]
	v_cmp_lt_i32_e32 vcc, s84, v39
	v_writelane_b32 v243, s0, 14
	s_or_b64 s[8:9], s[22:23], vcc
	v_or_b32_e32 v38, 3, v38
	v_writelane_b32 v243, s1, 15
	s_and_b64 s[0:1], s[6:7], s[8:9]
	v_cmp_gt_i32_e32 vcc, v38, v36
	v_cmp_le_i32_e64 s[8:9], v38, v37
	s_and_b64 s[8:9], vcc, s[8:9]
	v_cmp_lt_i32_e32 vcc, s84, v38
	v_writelane_b32 v243, s0, 16
	s_or_b64 s[10:11], s[22:23], vcc
	v_or_b32_e32 v38, v69, v111
	v_writelane_b32 v243, s1, 17
	s_and_b64 s[0:1], s[8:9], s[10:11]
	v_cmp_gt_i32_e32 vcc, v38, v36
	v_cmp_le_i32_e64 s[10:11], v38, v37
	s_and_b64 s[10:11], vcc, s[10:11]
	v_cmp_lt_i32_e32 vcc, s84, v38
	v_writelane_b32 v243, s0, 18
	s_or_b64 s[12:13], s[22:23], vcc
	v_cmp_ge_i32_e32 vcc, v38, v36
	v_writelane_b32 v243, s1, 19
	s_and_b64 s[0:1], s[10:11], s[12:13]
	v_cmp_lt_i32_e64 s[12:13], v38, v37
	s_and_b64 s[12:13], vcc, s[12:13]
	v_cmp_lt_i32_e32 vcc, s3, v38
	v_writelane_b32 v243, s0, 20
	s_or_b64 s[14:15], s[22:23], vcc
	v_or_b32_e32 v39, 2, v38
	v_writelane_b32 v243, s1, 21
	s_and_b64 s[0:1], s[12:13], s[14:15]
	v_cmp_gt_i32_e32 vcc, v39, v36
	v_cmp_le_i32_e64 s[14:15], v39, v37
	s_and_b64 s[14:15], vcc, s[14:15]
	v_cmp_lt_i32_e32 vcc, s84, v39
	v_writelane_b32 v243, s0, 22
	s_or_b64 s[16:17], s[22:23], vcc
	v_or_b32_e32 v38, 3, v38
	v_writelane_b32 v243, s1, 23
	s_and_b64 s[0:1], s[14:15], s[16:17]
	v_cmp_gt_i32_e32 vcc, v38, v36
	v_cmp_le_i32_e64 s[16:17], v38, v37
	s_and_b64 s[16:17], vcc, s[16:17]
	v_cmp_lt_i32_e32 vcc, s84, v38
	v_writelane_b32 v243, s0, 24
	s_or_b64 s[18:19], s[22:23], vcc
	v_or_b32_e32 v38, v71, v111
	v_writelane_b32 v243, s1, 25
	s_and_b64 s[0:1], s[16:17], s[18:19]
	v_cmp_gt_i32_e32 vcc, v38, v36
	v_cmp_le_i32_e64 s[18:19], v38, v37
	s_and_b64 s[18:19], vcc, s[18:19]
	v_cmp_lt_i32_e32 vcc, s84, v38
	v_writelane_b32 v243, s0, 26
	s_mov_b32 s4, s20
	s_or_b64 s[20:21], s[22:23], vcc
	v_writelane_b32 v243, s1, 27
	s_and_b64 s[0:1], s[18:19], s[20:21]
	v_cmp_ge_i32_e32 vcc, v38, v36
	v_cmp_lt_i32_e64 s[20:21], v38, v37
	s_and_b64 s[20:21], vcc, s[20:21]
	v_cmp_lt_i32_e32 vcc, s3, v38
	s_mov_b64 s[6:7], s[22:23]
	s_or_b64 s[22:23], s[22:23], vcc
	v_or_b32_e32 v39, 2, v38
	s_and_b64 s[20:21], s[20:21], s[22:23]
	v_cmp_gt_i32_e32 vcc, v39, v36
	v_cmp_le_i32_e64 s[22:23], v39, v37
	s_and_b64 s[22:23], vcc, s[22:23]
	v_cmp_lt_i32_e32 vcc, s84, v39
	s_or_b64 s[24:25], s[6:7], vcc
	v_or_b32_e32 v38, 3, v38
	s_and_b64 s[22:23], s[22:23], s[24:25]
	v_cmp_gt_i32_e32 vcc, v38, v36
	v_cmp_le_i32_e64 s[24:25], v38, v37
	v_add_u32_e32 v72, 48, v68
	s_and_b64 s[24:25], vcc, s[24:25]
	v_cmp_lt_i32_e32 vcc, s84, v38
	s_or_b64 s[26:27], s[6:7], vcc
	v_or_b32_e32 v38, v72, v111
	s_and_b64 s[24:25], s[24:25], s[26:27]
	v_cmp_gt_i32_e32 vcc, v38, v36
	v_cmp_le_i32_e64 s[26:27], v38, v37
	s_and_b64 s[26:27], vcc, s[26:27]
	v_cmp_lt_i32_e32 vcc, s84, v38
	s_or_b64 s[28:29], s[6:7], vcc
	s_and_b64 s[26:27], s[26:27], s[28:29]
	v_cmp_ge_i32_e32 vcc, v38, v36
	v_cmp_lt_i32_e64 s[28:29], v38, v37
	s_and_b64 s[28:29], vcc, s[28:29]
	v_cmp_lt_i32_e32 vcc, s3, v38
	s_or_b64 s[30:31], s[6:7], vcc
	v_or_b32_e32 v39, 2, v38
	s_and_b64 s[28:29], s[28:29], s[30:31]
	v_cmp_gt_i32_e32 vcc, v39, v36
	v_cmp_le_i32_e64 s[30:31], v39, v37
	s_and_b64 s[30:31], vcc, s[30:31]
	v_cmp_lt_i32_e32 vcc, s84, v39
	s_or_b64 s[34:35], s[6:7], vcc
	v_or_b32_e32 v38, 3, v38
	v_add_u32_e32 v73, 4, v57
	s_and_b64 s[30:31], s[30:31], s[34:35]
	v_cmp_gt_i32_e32 vcc, v38, v36
	v_cmp_le_i32_e64 s[34:35], v38, v37
	v_lshlrev_b32_e32 v74, 4, v73
	s_and_b64 s[34:35], vcc, s[34:35]
	v_cmp_lt_i32_e32 vcc, s84, v38
	s_or_b64 s[36:37], s[6:7], vcc
	v_or_b32_e32 v38, v74, v111
	s_and_b64 s[34:35], s[34:35], s[36:37]
	v_cmp_gt_i32_e32 vcc, v38, v36
	v_cmp_le_i32_e64 s[36:37], v38, v37
	s_and_b64 s[36:37], vcc, s[36:37]
	v_cmp_lt_i32_e32 vcc, s84, v38
	s_or_b64 s[38:39], s[6:7], vcc
	s_and_b64 s[36:37], s[36:37], s[38:39]
	v_cmp_ge_i32_e32 vcc, v38, v36
	v_cmp_lt_i32_e64 s[38:39], v38, v37
	s_and_b64 s[38:39], vcc, s[38:39]
	v_cmp_lt_i32_e32 vcc, s3, v38
	s_or_b64 s[40:41], s[6:7], vcc
	v_or_b32_e32 v39, 2, v38
	s_and_b64 s[38:39], s[38:39], s[40:41]
	v_cmp_gt_i32_e32 vcc, v39, v36
	v_cmp_le_i32_e64 s[40:41], v39, v37
	s_and_b64 s[40:41], vcc, s[40:41]
	v_cmp_lt_i32_e32 vcc, s84, v39
	s_or_b64 s[42:43], s[6:7], vcc
	v_or_b32_e32 v38, 3, v38
	s_and_b64 s[40:41], s[40:41], s[42:43]
	v_cmp_gt_i32_e32 vcc, v38, v36
	v_cmp_le_i32_e64 s[42:43], v38, v37
	v_add_u32_e32 v75, 0x50, v68
	s_and_b64 s[42:43], vcc, s[42:43]
	v_cmp_lt_i32_e32 vcc, s84, v38
	s_or_b64 s[44:45], s[6:7], vcc
	v_or_b32_e32 v38, v75, v111
	s_and_b64 s[42:43], s[42:43], s[44:45]
	v_cmp_gt_i32_e32 vcc, v38, v36
	v_cmp_le_i32_e64 s[44:45], v38, v37
	s_and_b64 s[44:45], vcc, s[44:45]
	v_cmp_lt_i32_e32 vcc, s84, v38
	s_or_b64 s[46:47], s[6:7], vcc
	s_and_b64 s[44:45], s[44:45], s[46:47]
	v_cmp_ge_i32_e32 vcc, v38, v36
	v_cmp_lt_i32_e64 s[46:47], v38, v37
	s_and_b64 s[46:47], vcc, s[46:47]
	v_cmp_lt_i32_e32 vcc, s3, v38
	s_or_b64 s[48:49], s[6:7], vcc
	v_or_b32_e32 v39, 2, v38
	s_and_b64 s[46:47], s[46:47], s[48:49]
	v_cmp_gt_i32_e32 vcc, v39, v36
	v_cmp_le_i32_e64 s[48:49], v39, v37
	s_and_b64 s[48:49], vcc, s[48:49]
	v_cmp_lt_i32_e32 vcc, s84, v39
	s_or_b64 s[50:51], s[6:7], vcc
	v_or_b32_e32 v38, 3, v38
	v_add_u32_e32 v76, 6, v57
	s_and_b64 s[48:49], s[48:49], s[50:51]
	v_cmp_gt_i32_e32 vcc, v38, v36
	v_cmp_le_i32_e64 s[50:51], v38, v37
	v_lshlrev_b32_e32 v77, 4, v76
	s_and_b64 s[50:51], vcc, s[50:51]
	v_cmp_lt_i32_e32 vcc, s84, v38
	s_or_b64 s[52:53], s[6:7], vcc
	v_or_b32_e32 v38, v77, v111
	s_and_b64 s[50:51], s[50:51], s[52:53]
	v_cmp_gt_i32_e32 vcc, v38, v36
	v_cmp_le_i32_e64 s[52:53], v38, v37
	s_and_b64 s[52:53], vcc, s[52:53]
	v_cmp_lt_i32_e32 vcc, s84, v38
	s_or_b64 s[54:55], s[6:7], vcc
	s_and_b64 s[52:53], s[52:53], s[54:55]
	v_cmp_ge_i32_e32 vcc, v38, v36
	v_cmp_lt_i32_e64 s[54:55], v38, v37
	s_and_b64 s[54:55], vcc, s[54:55]
	v_cmp_lt_i32_e32 vcc, s3, v38
	s_or_b64 s[56:57], s[6:7], vcc
	v_or_b32_e32 v39, 2, v38
	s_and_b64 s[54:55], s[54:55], s[56:57]
	v_cmp_gt_i32_e32 vcc, v39, v36
	v_cmp_le_i32_e64 s[56:57], v39, v37
	s_and_b64 s[56:57], vcc, s[56:57]
	v_cmp_lt_i32_e32 vcc, s84, v39
	s_or_b64 s[58:59], s[6:7], vcc
	v_or_b32_e32 v38, 3, v38
	s_and_b64 s[56:57], s[56:57], s[58:59]
	v_cmp_gt_i32_e32 vcc, v38, v36
	v_cmp_le_i32_e64 s[58:59], v38, v37
	v_add_u32_e32 v78, 0x70, v68
	s_and_b64 s[58:59], vcc, s[58:59]
	v_cmp_lt_i32_e32 vcc, s84, v38
	s_or_b64 s[60:61], s[6:7], vcc
	v_or_b32_e32 v38, v78, v111
	s_and_b64 s[58:59], s[58:59], s[60:61]
	v_cmp_gt_i32_e32 vcc, v38, v36
	v_cmp_le_i32_e64 s[60:61], v38, v37
	s_and_b64 s[60:61], vcc, s[60:61]
	v_cmp_lt_i32_e32 vcc, s84, v38
	s_or_b64 s[62:63], s[6:7], vcc
	s_and_b64 s[60:61], s[60:61], s[62:63]
	v_cmp_ge_i32_e32 vcc, v38, v36
	v_cmp_lt_i32_e64 s[62:63], v38, v37
	s_and_b64 s[62:63], vcc, s[62:63]
	v_cmp_lt_i32_e32 vcc, s3, v38
	s_or_b64 s[64:65], s[6:7], vcc
	v_or_b32_e32 v39, 2, v38
	s_and_b64 s[62:63], s[62:63], s[64:65]
	v_cmp_gt_i32_e32 vcc, v39, v36
	v_cmp_le_i32_e64 s[64:65], v39, v37
	s_and_b64 s[64:65], vcc, s[64:65]
	v_cmp_lt_i32_e32 vcc, s84, v39
	s_or_b64 s[66:67], s[6:7], vcc
	v_or_b32_e32 v38, 3, v38
	s_and_b64 s[64:65], s[64:65], s[66:67]
	v_cmp_gt_i32_e32 vcc, v38, v36
	v_cmp_le_i32_e64 s[66:67], v38, v37
	v_add_u32_e32 v79, 8, v57
	s_and_b64 s[66:67], vcc, s[66:67]
	v_cmp_lt_i32_e32 vcc, s84, v38
	v_lshlrev_b32_e32 v98, 4, v79
	s_or_b64 s[68:69], s[6:7], vcc
	v_or_b32_e32 v38, v98, v111
	s_and_b64 s[66:67], s[66:67], s[68:69]
	v_cmp_gt_i32_e32 vcc, v38, v36
	v_cmp_le_i32_e64 s[68:69], v38, v37
	s_and_b64 s[68:69], vcc, s[68:69]
	v_cmp_lt_i32_e32 vcc, s84, v38
	s_or_b64 s[70:71], s[6:7], vcc
	s_and_b64 s[68:69], s[68:69], s[70:71]
	v_cmp_ge_i32_e32 vcc, v38, v36
	v_cmp_lt_i32_e64 s[70:71], v38, v37
	s_and_b64 s[70:71], vcc, s[70:71]
	v_cmp_lt_i32_e32 vcc, s3, v38
	s_or_b64 s[72:73], s[6:7], vcc
	v_or_b32_e32 v39, 2, v38
	s_and_b64 s[70:71], s[70:71], s[72:73]
	v_cmp_gt_i32_e32 vcc, v39, v36
	v_cmp_le_i32_e64 s[72:73], v39, v37
	s_and_b64 s[72:73], vcc, s[72:73]
	v_cmp_lt_i32_e32 vcc, s84, v39
	s_or_b64 s[74:75], s[6:7], vcc
	v_or_b32_e32 v38, 3, v38
	s_and_b64 s[72:73], s[72:73], s[74:75]
	v_cmp_gt_i32_e32 vcc, v38, v36
	v_cmp_le_i32_e64 s[74:75], v38, v37
	s_and_b64 s[74:75], vcc, s[74:75]
	v_cmp_lt_i32_e32 vcc, s84, v38
	v_add_u32_e32 v99, 0x90, v68
	s_or_b64 s[76:77], s[6:7], vcc
	v_or_b32_e32 v38, v99, v111
	s_and_b64 s[74:75], s[74:75], s[76:77]
	v_cmp_gt_i32_e32 vcc, v38, v36
	v_cmp_le_i32_e64 s[76:77], v38, v37
	s_and_b64 s[76:77], vcc, s[76:77]
	v_cmp_lt_i32_e32 vcc, s84, v38
	s_or_b64 s[78:79], s[6:7], vcc
	s_and_b64 s[76:77], s[76:77], s[78:79]
	v_cmp_ge_i32_e32 vcc, v38, v36
	v_cmp_lt_i32_e64 s[78:79], v38, v37
	s_and_b64 s[78:79], vcc, s[78:79]
	v_cmp_lt_i32_e32 vcc, s3, v38
	s_or_b64 s[80:81], s[6:7], vcc
	v_or_b32_e32 v39, 2, v38
	s_and_b64 s[78:79], s[78:79], s[80:81]
	v_cmp_gt_i32_e32 vcc, v39, v36
	v_cmp_le_i32_e64 s[80:81], v39, v37
	s_and_b64 s[80:81], vcc, s[80:81]
	v_cmp_lt_i32_e32 vcc, s84, v39
	s_or_b64 s[82:83], s[6:7], vcc
	v_writelane_b32 v243, s6, 28
	v_or_b32_e32 v38, 3, v38
	v_add_u32_e32 v64, s2, v50
	v_writelane_b32 v243, s7, 29
	v_add_u32_e32 v90, s2, v2
	s_mov_b32 s2, s4
	v_add_u32_e32 v2, s4, v2
	s_and_b64 s[80:81], s[80:81], s[82:83]
	v_cmp_gt_i32_e32 vcc, v38, v36
	v_cmp_le_i32_e64 s[82:83], v38, v37
	v_writelane_b32 v243, s2, 30
	v_or_b32_e32 v80, v2, v56
	v_lshlrev_b32_e32 v58, 3, v51
	v_mov_b64_e32 v[36:37], s[88:89]
	v_writelane_b32 v243, s3, 31
	v_mad_i64_i32 v[82:83], s[2:3], v80, s92, v[36:37]
	v_lshlrev_b32_e32 v2, 4, v51
	v_bitop3_b32 v60, v58, 8, v58 bitop3:0xc
	v_lshl_add_u64 v[36:37], v[82:83], 0, v[2:3]
	v_lshlrev_b32_e32 v44, 1, v60
	v_mov_b32_e32 v45, v3
	s_and_b64 s[82:83], vcc, s[82:83]
	v_cmp_lt_i32_e32 vcc, s84, v38
	global_load_dwordx4 v[40:43], v[36:37], off offset:2048
	s_nop 0
	global_load_dwordx4 v[36:39], v[36:37], off offset:2112
	v_lshl_add_u64 v[44:45], v[82:83], 0, v[44:45]
	global_load_dwordx4 v[44:47], v[44:45], off offset:2048
	v_mul_lo_u32 v59, v59, s93
	v_add_u32_e32 v59, s96, v59
	v_mul_u32_u24_e32 v100, 0x210, v56
	v_add3_u32 v109, v59, v100, v58
	v_mul_lo_u32 v59, v50, s97
	v_add_u32_e32 v62, 0, v59
	v_lshl_add_u32 v115, v55, 1, v62
	v_mad_u64_u32 v[62:63], s[2:3], v50, s98, v[62:63]
	v_lshl_add_u64 v[52:53], s[88:89], 0, v[52:53]
	s_mov_b32 s2, 0xfff70b80
	v_lshl_add_u64 v[52:53], v[48:49], 1, v[52:53]
	s_mov_b32 s3, -1
	v_lshl_add_u64 v[86:87], v[52:53], 0, s[2:3]
	s_mov_b32 s2, 0xfff70a80
	s_mov_b32 s3, -1
	v_max_i32_e32 v50, 0x80, v64
	v_lshl_add_u64 v[88:89], v[52:53], 0, s[2:3]
	v_or_b32_e32 v52, v90, v56
	v_lshl_add_u32 v64, v50, 4, v183
	v_lshlrev_b32_e32 v52, 4, v52
	s_or_b64 s[84:85], s[6:7], vcc
	v_ashrrev_i32_e32 v65, 31, v64
	v_ashrrev_i32_e32 v53, 31, v52
	s_and_b64 s[82:83], s[82:83], s[84:85]
	v_lshl_add_u64 v[84:85], v[64:65], 2, s[86:87]
	v_lshl_add_u64 v[90:91], v[52:53], 2, s[86:87]
	s_mov_b32 s2, s96
	v_readlane_b32 s84, v244, 10
	v_readlane_b32 s88, v244, 14
	v_readlane_b32 s89, v244, 15
	v_readlane_b32 s90, v244, 16
	v_readlane_b32 s91, v244, 17
	v_readlane_b32 s92, v244, 18
	v_readlane_b32 s93, v244, 19
	v_readlane_b32 s94, v244, 20
	v_readlane_b32 s95, v244, 21
	v_readlane_b32 s96, v244, 22
	v_readlane_b32 s97, v244, 23
	s_mov_b64 s[8:9], s[88:89]
	v_add_u32_e32 v52, 0, v2
	s_mov_b64 s[12:13], s[92:93]
	v_lshlrev_b32_e32 v2, 5, v51
	v_lshl_add_u64 v[94:95], s[12:13], 0, v[2:3]
	v_lshlrev_b32_e32 v2, 2, v60
	s_mov_b64 s[10:11], s[90:91]
	s_mov_b64 s[14:15], s[94:95]
	s_mov_b64 s[16:17], s[96:97]
	s_movk_i32 s97, 0x90
	v_lshl_add_u64 v[96:97], s[12:13], 0, v[2:3]
	v_or_b32_e32 v2, v68, v56
	v_lshl_add_u64 v[92:93], v[48:49], 2, s[14:15]
	v_mul_lo_u32 v48, v2, s97
	v_or_b32_e32 v2, v69, v56
	v_mul_lo_u32 v49, v2, s97
	v_or_b32_e32 v2, v71, v56
	v_mul_lo_u32 v55, v2, s97
	v_or_b32_e32 v2, v72, v56
	v_mul_lo_u32 v59, v2, s97
	v_or_b32_e32 v2, v74, v56
	v_lshlrev_b32_e32 v129, 2, v61
	v_mul_lo_u32 v61, v2, s97
	v_or_b32_e32 v2, v75, v56
	v_mul_lo_u32 v63, v2, s97
	v_or_b32_e32 v2, v77, v56
	v_mul_lo_u32 v64, v2, s97
	v_or_b32_e32 v2, v78, v56
	v_mul_lo_u32 v65, v2, s97
	v_or_b32_e32 v2, v98, v56
	v_lshlrev_b32_e32 v128, 2, v66
	v_mov_b32_e32 v53, v52
	v_mul_lo_u32 v66, v2, s97
	v_or_b32_e32 v2, v99, v56
	v_mul_u32_u24_e32 v50, 0x4200, v54
	v_lshlrev_b32_e32 v113, 2, v67
	v_readlane_b32 s85, v244, 11
	v_readlane_b32 s86, v244, 12
	v_readlane_b32 s87, v244, 13
	v_readlane_b32 s98, v244, 24
	v_mul_lo_u32 v56, v2, s97
	v_lshl_add_u32 v57, v57, 5, v53
	v_lshl_add_u32 v67, v70, 5, v53
	v_lshl_add_u32 v68, v73, 5, v53
	v_lshl_add_u32 v69, v76, 5, v53
	v_lshl_add_u32 v53, v79, 5, v53
	v_ashrrev_i32_e32 v81, 31, v80
	v_readlane_b32 s99, v244, 25
	s_movk_i32 s98, 0xff72
	s_mov_b32 s96, s2
	s_movk_i32 s93, 0x2100
	s_movk_i32 s92, 0x1200
	v_and_b32_e32 v241, 24, v62
	v_and_b32_e32 v242, 32, v62
	v_and_b32_e32 v62, 0xffffffc7, v62
	v_lshlrev_b32_e32 v241, 1, v241
	v_lshrrev_b32_e32 v242, 2, v242
	v_or3_b32 v62, v62, v241, v242
	v_add_u32_e32 v116, v62, v50
	v_lshlrev_b32_e32 v2, 1, v60
	v_lshlrev_b32_e32 v98, 1, v58
	v_add_u32_e32 v117, v52, v48
	v_add_u32_e32 v118, v52, v49
	v_add_u32_e32 v119, v52, v55
	v_add_u32_e32 v120, v52, v59
	v_add_u32_e32 v121, v52, v61
	v_add_u32_e32 v122, v52, v63
	v_add_u32_e32 v123, v52, v64
	v_add_u32_e32 v124, v52, v65
	v_add_u32_e32 v125, v52, v66
	v_add_u32_e32 v126, v52, v56
	v_add_u32_e32 v127, v57, v100
	v_add_u32_e32 v130, v67, v100
	v_add_u32_e32 v131, v68, v100
	v_add_u32_e32 v132, v69, v100
	v_add_u32_e32 v133, v53, v100
	v_cmp_eq_u32_e64 s[84:85], 0, v54
	v_cmp_gt_u32_e64 s[86:87], 2, v51
	s_mov_b64 s[2:3], -1
	s_branch .LBB0_182

.LBB0_189:
	v_readlane_b32 s4, v244, 10
	s_xor_b64 s[2:3], s[2:3], -1
	s_lshl_b64 s[94:95], s[90:91], 2
	v_readlane_b32 s16, v244, 22
	v_readlane_b32 s17, v244, 23
	s_add_u32 s94, s16, s94
	s_addc_u32 s95, s17, s95
	ds_read_b128 v[134:137], v117
	ds_read_b128 v[138:141], v117 offset:64
	global_load_dword v99, v3, s[94:95]
	ds_read_b128 v[142:145], v118
	ds_read_b128 v[146:149], v118 offset:64
	s_waitcnt lgkmcnt(3)
	v_mfma_f32_16x16x32_bf16 v[134:137], v[134:137], v[72:75], 0
	v_readlane_b32 s6, v244, 12
	v_readlane_b32 s7, v244, 13
	s_mov_b32 s4, 0xf149f2ca
	s_waitcnt lgkmcnt(1)
	v_mfma_f32_16x16x32_bf16 v[142:145], v[142:145], v[72:75], 0
	v_readlane_b32 s6, v243, 12
	v_mov_b32_e32 v100, s4
	v_readlane_b32 s7, v243, 13
	v_mfma_f32_16x16x32_bf16 v[134:137], v[138:141], v[68:71], v[134:137]
	ds_read_b128 v[138:141], v119
	v_mov_b32_e32 v178, s4
	v_mov_b32_e32 v216, s4
	s_waitcnt lgkmcnt(1)
	v_mfma_f32_16x16x32_bf16 v[142:145], v[146:149], v[68:71], v[142:145]
	ds_read_b128 v[146:149], v119 offset:64
	ds_read_b128 v[150:153], v120
	ds_read_b128 v[154:157], v120 offset:64
	ds_read_b128 v[158:161], v121
	ds_read_b128 v[162:165], v121 offset:64
	v_cndmask_b32_e64 v100, v100, v134, s[6:7]
	s_waitcnt lgkmcnt(5)
	v_mfma_f32_16x16x32_bf16 v[138:141], v[138:141], v[72:75], 0
	v_readlane_b32 s6, v243, 14
	v_readlane_b32 s7, v243, 15
	v_mov_b32_e32 v218, s4
	s_waitcnt lgkmcnt(1)
	v_mfma_f32_16x16x32_bf16 v[158:161], v[158:161], v[72:75], 0
	v_mov_b32_e32 v220, s4
	v_mov_b32_e32 v222, s4
	v_readlane_b32 s5, v244, 11
	v_mfma_f32_16x16x32_bf16 v[138:141], v[146:149], v[68:71], v[138:141]
	ds_read_b128 v[146:149], v122
	ds_read_b128 v[166:169], v122 offset:64
	ds_read_b128 v[170:173], v123
	ds_read_b128 v[174:177], v123 offset:64
	ds_read_b128 v[196:199], v124
	ds_read_b128 v[200:203], v124 offset:64
	ds_read_b128 v[204:207], v125
	ds_read_b128 v[208:211], v125 offset:64
	v_readlane_b32 s8, v244, 14
	s_waitcnt lgkmcnt(8)
	v_mfma_f32_16x16x32_bf16 v[158:161], v[162:165], v[68:71], v[158:161]
	v_cndmask_b32_e64 v163, v184, v135, s[6:7]
	v_readlane_b32 s6, v243, 16
	v_readlane_b32 s7, v243, 17
	s_waitcnt lgkmcnt(7)
	v_mfma_f32_16x16x32_bf16 v[146:149], v[146:149], v[72:75], 0
	v_mov_b32_e32 v162, s4
	v_cndmask_b32_e64 v165, v184, v136, s[6:7]
	v_readlane_b32 s6, v243, 18
	v_readlane_b32 s7, v243, 19
	s_waitcnt lgkmcnt(6)
	v_mfma_f32_16x16x32_bf16 v[146:149], v[166:169], v[68:71], v[146:149]
	v_cndmask_b32_e64 v158, v162, v158, s[36:37]
	v_cndmask_b32_e64 v166, v184, v137, s[6:7]
	v_readlane_b32 s6, v243, 20
	v_readlane_b32 s7, v243, 21
	v_mfma_f32_16x16x32_bf16 v[150:153], v[150:153], v[72:75], 0
	v_cndmask_b32_e64 v159, v184, v159, s[38:39]
	v_cndmask_b32_e64 v167, v178, v142, s[6:7]
	v_readlane_b32 s6, v243, 22
	v_readlane_b32 s7, v243, 23
	v_mfma_f32_16x16x32_bf16 v[150:153], v[154:157], v[68:71], v[150:153]
	ds_read_b128 v[154:157], v126
	ds_read_b128 v[212:215], v126 offset:64
	v_cndmask_b32_e64 v168, v184, v143, s[6:7]
	v_readlane_b32 s6, v243, 24
	v_readlane_b32 s7, v243, 25
	s_waitcnt lgkmcnt(7)
	v_mfma_f32_16x16x32_bf16 v[134:137], v[170:173], v[72:75], 0
	v_cndmask_b32_e64 v171, v216, v138, s[0:1]
	v_cndmask_b32_e64 v169, v184, v144, s[6:7]
	v_readlane_b32 s6, v243, 26
	v_readlane_b32 s7, v243, 27
	s_waitcnt lgkmcnt(6)
	v_mfma_f32_16x16x32_bf16 v[134:137], v[174:177], v[68:71], v[134:137]
	v_cndmask_b32_e64 v172, v184, v139, s[20:21]
	v_cndmask_b32_e64 v170, v184, v145, s[6:7]
	v_cndmask_b32_e64 v173, v184, v140, s[22:23]
	s_waitcnt lgkmcnt(5)
	v_mfma_f32_16x16x32_bf16 v[142:145], v[196:199], v[72:75], 0
	v_cndmask_b32_e64 v174, v184, v141, s[24:25]
	v_cndmask_b32_e64 v150, v218, v150, s[26:27]
	v_cndmask_b32_e64 v151, v184, v151, s[28:29]
	s_waitcnt lgkmcnt(4)
	v_mfma_f32_16x16x32_bf16 v[138:141], v[200:203], v[68:71], v[142:145]
	v_cndmask_b32_e64 v152, v184, v152, s[30:31]
	v_cndmask_b32_e64 v153, v184, v153, s[34:35]
	v_mov_b32_e32 v164, s4
	s_waitcnt lgkmcnt(3)
	v_mfma_f32_16x16x32_bf16 v[142:145], v[204:207], v[72:75], 0
	v_cndmask_b32_e64 v160, v184, v160, s[40:41]
	v_cndmask_b32_e64 v161, v184, v161, s[42:43]
	v_cndmask_b32_e64 v146, v164, v146, s[44:45]
	s_waitcnt lgkmcnt(1)
	v_mfma_f32_16x16x32_bf16 v[72:75], v[154:157], v[72:75], 0
	v_cndmask_b32_e64 v147, v184, v147, s[46:47]
	v_cndmask_b32_e64 v148, v184, v148, s[48:49]
	v_cndmask_b32_e64 v149, v184, v149, s[50:51]
	v_mfma_f32_16x16x32_bf16 v[142:145], v[208:211], v[68:71], v[142:145]
	v_cndmask_b32_e64 v134, v220, v134, s[52:53]
	v_cndmask_b32_e64 v135, v184, v135, s[54:55]
	v_readlane_b32 s9, v244, 15
	s_waitcnt lgkmcnt(0)
	v_mfma_f32_16x16x32_bf16 v[68:71], v[212:215], v[68:71], v[72:75]
	v_readlane_b32 s10, v244, 16
	s_nop 1
	v_cndmask_b32_e64 v154, v184, v143, s[70:71]
	v_cndmask_b32_e64 v155, v184, v144, s[72:73]
	s_waitcnt vmcnt(0)
	v_mul_f32_e32 v72, 0x3fb8aa3b, v99
	v_max3_f32 v72, v72, v100, v163
	v_max3_f32 v72, v72, v165, v166
	v_max3_f32 v72, v72, v167, v168
	v_max3_f32 v72, v72, v169, v170
	v_max3_f32 v72, v72, v171, v172
	v_max3_f32 v72, v72, v173, v174
	v_max3_f32 v72, v72, v150, v151
	v_max3_f32 v72, v72, v152, v153
	v_max3_f32 v72, v72, v158, v159
	v_max3_f32 v72, v72, v160, v161
	v_max3_f32 v72, v72, v146, v147
	v_max3_f32 v72, v72, v148, v149
	v_cndmask_b32_e64 v73, v184, v136, s[56:57]
	v_cndmask_b32_e64 v74, v184, v137, s[58:59]
	v_max3_f32 v72, v72, v134, v135
	v_cndmask_b32_e64 v75, v222, v138, s[60:61]
	v_cndmask_b32_e64 v136, v184, v139, s[62:63]
	v_max3_f32 v72, v72, v73, v74
	v_max3_f32 v72, v72, v75, v136
	v_cndmask_b32_e64 v137, v184, v140, s[64:65]
	v_cndmask_b32_e64 v138, v184, v141, s[66:67]
	v_max3_f32 v139, v72, v137, v138
	v_mov_b32_e32 v72, s4
	v_cndmask_b32_e64 v140, v72, v142, s[68:69]
	v_max3_f32 v72, v139, v140, v154
	v_cndmask_b32_e64 v162, v184, v145, s[74:75]
	v_max3_f32 v139, v72, v155, v162
	v_mov_b32_e32 v72, s4
	v_cndmask_b32_e64 v164, v72, v68, s[76:77]
	v_cndmask_b32_e64 v175, v184, v69, s[78:79]
	v_max3_f32 v68, v139, v164, v175
	v_cndmask_b32_e64 v176, v184, v70, s[80:81]
	v_cndmask_b32_e64 v177, v184, v71, s[82:83]
	v_max3_f32 v68, v68, v176, v177
	ds_bpermute_b32 v69, v128, v68
	s_mov_b32 s4, 0x3fb8aa3b
	v_readlane_b32 s11, v244, 17
	v_readlane_b32 s12, v244, 18
	v_readlane_b32 s13, v244, 19
	s_waitcnt lgkmcnt(0)
	v_max_f32_e32 v69, v69, v69
	v_max_f32_e32 v68, v68, v69
	ds_bpermute_b32 v69, v113, v68
	v_readlane_b32 s14, v244, 20
	v_readlane_b32 s15, v244, 21
	v_readlane_b32 s18, v244, 24
	v_readlane_b32 s19, v244, 25
	s_waitcnt lgkmcnt(0)
	v_max_f32_e32 v69, v69, v69
	v_max_f32_e32 v178, v68, v69
	v_sub_f32_e32 v68, v100, v178
	v_exp_f32_e32 v72, v68
	v_sub_f32_e32 v68, v163, v178
	v_exp_f32_e32 v100, v68
	v_sub_f32_e32 v69, v165, v178
	v_exp_f32_e32 v139, v69
	v_sub_f32_e32 v69, v166, v178
	v_exp_f32_e32 v141, v69
	v_sub_f32_e32 v69, v167, v178
	v_add_f32_e32 v68, 0, v72
	v_exp_f32_e32 v142, v69
	v_sub_f32_e32 v69, v168, v178
	v_add_f32_e32 v68, v100, v68
	v_exp_f32_e32 v143, v69
	v_sub_f32_e32 v69, v169, v178
	v_add_f32_e32 v68, v139, v68
	v_exp_f32_e32 v144, v69
	v_sub_f32_e32 v69, v170, v178
	v_add_f32_e32 v68, v141, v68
	v_exp_f32_e32 v145, v69
	v_sub_f32_e32 v69, v171, v178
	v_add_f32_e32 v68, v142, v68
	v_exp_f32_e32 v156, v69
	v_sub_f32_e32 v69, v172, v178
	v_add_f32_e32 v68, v143, v68
	v_exp_f32_e32 v157, v69
	v_sub_f32_e32 v69, v173, v178
	v_add_f32_e32 v68, v144, v68
	v_exp_f32_e32 v163, v69
	v_sub_f32_e32 v69, v174, v178
	v_add_f32_e32 v68, v145, v68
	v_exp_f32_e32 v165, v69
	v_sub_f32_e32 v69, v150, v178
	v_add_f32_e32 v68, v156, v68
	v_exp_f32_e32 v166, v69
	v_sub_f32_e32 v69, v151, v178
	v_add_f32_e32 v68, v157, v68
	v_exp_f32_e32 v167, v69
	v_sub_f32_e32 v69, v152, v178
	v_add_f32_e32 v68, v163, v68
	v_exp_f32_e32 v168, v69
	v_sub_f32_e32 v69, v153, v178
	v_add_f32_e32 v68, v165, v68
	v_exp_f32_e32 v169, v69
	v_sub_f32_e32 v69, v158, v178
	v_add_f32_e32 v68, v166, v68
	v_exp_f32_e32 v158, v69
	v_sub_f32_e32 v69, v159, v178
	v_add_f32_e32 v68, v167, v68
	v_exp_f32_e32 v159, v69
	v_sub_f32_e32 v69, v160, v178
	v_add_f32_e32 v68, v168, v68
	v_exp_f32_e32 v160, v69
	v_sub_f32_e32 v69, v161, v178
	v_add_f32_e32 v68, v169, v68
	v_exp_f32_e32 v161, v69
	v_sub_f32_e32 v69, v146, v178
	v_add_f32_e32 v68, v158, v68
	v_exp_f32_e32 v170, v69
	v_sub_f32_e32 v69, v147, v178
	v_add_f32_e32 v68, v159, v68
	v_exp_f32_e32 v171, v69
	v_sub_f32_e32 v69, v148, v178
	v_add_f32_e32 v68, v160, v68
	v_exp_f32_e32 v172, v69
	v_sub_f32_e32 v69, v149, v178
	v_add_f32_e32 v68, v161, v68
	v_exp_f32_e32 v173, v69
	v_sub_f32_e32 v69, v134, v178
	v_add_f32_e32 v68, v170, v68
	v_exp_f32_e32 v174, v69
	v_sub_f32_e32 v69, v135, v178
	v_add_f32_e32 v68, v171, v68
	v_exp_f32_e32 v179, v69
	v_sub_f32_e32 v69, v73, v178
	v_add_f32_e32 v68, v172, v68
	v_exp_f32_e32 v195, v69
	v_sub_f32_e32 v69, v74, v178
	v_add_f32_e32 v68, v173, v68
	v_exp_f32_e32 v196, v69
	v_sub_f32_e32 v69, v75, v178
	v_add_f32_e32 v68, v174, v68
	v_exp_f32_e32 v197, v69
	v_sub_f32_e32 v69, v136, v178
	v_add_f32_e32 v68, v179, v68
	v_exp_f32_e32 v198, v69
	v_add_f32_e32 v68, v195, v68
	v_add_f32_e32 v68, v196, v68
	v_add_f32_e32 v68, v197, v68
	v_add_f32_e32 v146, v198, v68
	v_sub_f32_e32 v68, v137, v178
	v_exp_f32_e32 v199, v68
	v_sub_f32_e32 v68, v138, v178
	v_add_u32_e32 v74, 0xb000, v127
	v_exp_f32_e32 v200, v68
	v_add_u32_e32 v68, 0x9000, v127
	v_cvt_pk_bf16_f32 v72, v72, v100
	ds_read_b128 v[134:137], v74 offset:256
	v_cvt_pk_bf16_f32 v74, v142, v143
	v_add_u32_e32 v100, 0xd000, v127
	v_add_u32_e32 v142, 0xf000, v127
	v_sub_f32_e32 v147, v140, v178
	ds_read_b128 v[68:71], v68
	v_cvt_pk_bf16_f32 v73, v139, v141
	v_cvt_pk_bf16_f32 v75, v144, v145
	ds_read_b128 v[138:141], v100 offset:512
	ds_read_b128 v[142:145], v142 offset:768
	s_waitcnt lgkmcnt(2)
	v_mfma_f32_16x16x32_bf16 v[68:71], v[68:71], v[72:75], 0
	v_exp_f32_e32 v100, v147
	v_add_f32_e32 v146, v199, v146
	v_add_f32_e32 v146, v200, v146
	v_mfma_f32_16x16x32_bf16 v[134:137], v[134:137], v[72:75], 0
	v_add_f32_e32 v201, v100, v146
	v_sub_f32_e32 v146, v154, v178
	v_add_u32_e32 v148, 0xb000, v130
	s_waitcnt lgkmcnt(1)
	v_mfma_f32_16x16x32_bf16 v[138:141], v[138:141], v[72:75], 0
	v_exp_f32_e32 v202, v146
	v_cvt_pk_bf16_f32 v146, v156, v157
	v_cvt_pk_bf16_f32 v147, v163, v165
	s_waitcnt lgkmcnt(0)
	v_mfma_f32_16x16x32_bf16 v[72:75], v[142:145], v[72:75], 0
	v_add_u32_e32 v142, 0x9000, v130
	ds_read_b128 v[142:145], v142
	ds_read_b128 v[150:153], v148 offset:256
	v_cvt_pk_bf16_f32 v148, v166, v167
	v_cvt_pk_bf16_f32 v149, v168, v169
	v_add_u32_e32 v154, 0xd000, v130
	s_waitcnt lgkmcnt(1)
	v_mfma_f32_16x16x32_bf16 v[68:71], v[142:145], v[146:149], v[68:71]
	v_add_u32_e32 v142, 0xf000, v130
	ds_read_b128 v[142:145], v142 offset:768
	v_sub_f32_e32 v203, v155, v178
	ds_read_b128 v[154:157], v154 offset:512
	s_waitcnt lgkmcnt(1)
	v_mfma_f32_16x16x32_bf16 v[72:75], v[142:145], v[146:149], v[72:75]
	v_add_u32_e32 v142, 0x9000, v131
	ds_read_b128 v[142:145], v142
	v_exp_f32_e32 v163, v203
	v_mfma_f32_16x16x32_bf16 v[134:137], v[150:153], v[146:149], v[134:137]
	v_sub_f32_e32 v150, v162, v178
	v_exp_f32_e32 v162, v150
	v_add_f32_e32 v150, v202, v201
	s_waitcnt lgkmcnt(1)
	v_mfma_f32_16x16x32_bf16 v[138:141], v[154:157], v[146:149], v[138:141]
	v_add_f32_e32 v150, v163, v150
	v_add_u32_e32 v148, 0xb000, v131
	v_add_f32_e32 v165, v162, v150
	v_cvt_pk_bf16_f32 v146, v158, v159
	v_cvt_pk_bf16_f32 v147, v160, v161
	ds_read_b128 v[150:153], v148 offset:256
	v_cvt_pk_bf16_f32 v148, v170, v171
	v_cvt_pk_bf16_f32 v149, v172, v173
	v_add_u32_e32 v154, 0xd000, v131
	s_waitcnt lgkmcnt(1)
	v_mfma_f32_16x16x32_bf16 v[68:71], v[142:145], v[146:149], v[68:71]
	v_add_u32_e32 v142, 0xf000, v131
	ds_read_b128 v[142:145], v142 offset:768
	ds_read_b128 v[154:157], v154 offset:512
	s_waitcnt lgkmcnt(1)
	v_mfma_f32_16x16x32_bf16 v[72:75], v[142:145], v[146:149], v[72:75]
	v_add_u32_e32 v142, 0x9000, v132
	ds_read_b128 v[142:145], v142
	v_sub_f32_e32 v164, v164, v178
	v_mfma_f32_16x16x32_bf16 v[134:137], v[150:153], v[146:149], v[134:137]
	v_sub_f32_e32 v150, v175, v178
	v_exp_f32_e32 v160, v150
	v_sub_f32_e32 v150, v176, v178
	s_waitcnt lgkmcnt(1)
	v_mfma_f32_16x16x32_bf16 v[138:141], v[154:157], v[146:149], v[138:141]
	v_add_u32_e32 v148, 0xb000, v132
	v_exp_f32_e32 v161, v150
	ds_read_b128 v[150:153], v148 offset:256
	v_exp_f32_e32 v158, v164
	v_sub_f32_e32 v164, v177, v178
	v_exp_f32_e32 v164, v164
	v_cvt_pk_bf16_f32 v146, v174, v179
	v_add_f32_e32 v159, v158, v165
	v_cvt_pk_bf16_f32 v147, v195, v196
	v_cvt_pk_bf16_f32 v148, v197, v198
	v_cvt_pk_bf16_f32 v149, v199, v200
	v_add_u32_e32 v154, 0xd000, v132
	s_waitcnt lgkmcnt(1)
	v_mfma_f32_16x16x32_bf16 v[68:71], v[142:145], v[146:149], v[68:71]
	v_add_f32_e32 v142, v160, v159
	v_add_f32_e32 v142, v161, v142
	ds_read_b128 v[154:157], v154 offset:512
	s_waitcnt lgkmcnt(1)
	v_mfma_f32_16x16x32_bf16 v[134:137], v[150:153], v[146:149], v[134:137]
	v_add_f32_e32 v150, v164, v142
	v_add_u32_e32 v142, 0xf000, v132
	ds_read_b128 v[142:145], v142 offset:768
	ds_bpermute_b32 v151, v128, v150
	s_waitcnt lgkmcnt(1)
	v_mfma_f32_16x16x32_bf16 v[72:75], v[142:145], v[146:149], v[72:75]
	v_add_u32_e32 v142, 0x9000, v133
	ds_read_b128 v[142:145], v142
	s_waitcnt lgkmcnt(1)
	v_add_f32_e32 v159, v150, v151
	v_mfma_f32_16x16x32_bf16 v[138:141], v[154:157], v[146:149], v[138:141]
	ds_bpermute_b32 v165, v113, v159
	v_cvt_pk_bf16_f32 v146, v100, v202
	v_add_u32_e32 v100, 0xb000, v133
	ds_read_b128 v[150:153], v100 offset:256
	v_add_u32_e32 v100, 0xd000, v133
	v_fma_f32 v99, v99, s4, -v178
	ds_read_b128 v[154:157], v100 offset:512
	v_add_u32_e32 v100, 0xf000, v133
	v_exp_f32_e32 v99, v99
	v_cvt_pk_bf16_f32 v147, v163, v162
	v_cvt_pk_bf16_f32 v148, v158, v160
	v_cvt_pk_bf16_f32 v149, v161, v164
	v_writelane_b32 v244, s90, 62
	s_waitcnt lgkmcnt(3)
	v_mfma_f32_16x16x32_bf16 v[68:71], v[142:145], v[146:149], v[68:71]
	ds_read_b128 v[142:145], v100 offset:768
	s_waitcnt lgkmcnt(3)
	v_add_f32_e32 v100, v159, v165
	v_add_f32_e32 v99, v99, v100
	v_rcp_f32_e32 v100, v99
	s_waitcnt lgkmcnt(2)
	v_mfma_f32_16x16x32_bf16 v[134:137], v[150:153], v[146:149], v[134:137]
	v_lshl_add_u32 v99, s90, 7, v109
	s_mov_b32 s16, 0xf149f2ca
	v_pk_mul_f32 v[70:71], v[70:71], v[100:101] op_sel_hi:[1,0]
	s_waitcnt lgkmcnt(1)
	v_mfma_f32_16x16x32_bf16 v[138:141], v[154:157], v[146:149], v[138:141]
	v_mul_f32_e64 v68, v68, v100
	v_mul_f32_e64 v69, v69, v100
	s_nop 0
	v_pk_mul_f32 v[134:135], v[134:135], v[100:101] op_sel_hi:[1,0]
	v_writelane_b32 v244, s91, 63
	s_waitcnt lgkmcnt(0)
	v_mfma_f32_16x16x32_bf16 v[72:75], v[142:145], v[146:149], v[72:75]
	v_mul_f32_e64 v142, v70, v70
	v_mul_f32_e64 v143, v71, v71
	v_pk_mul_f32 v[144:145], v[68:69], v[68:69]
	v_cvt_pk_bf16_f32 v68, v68, v69
	v_cvt_pk_bf16_f32 v69, v70, v71
	v_pk_mul_f32 v[70:71], v[136:137], v[100:101] op_sel_hi:[1,0]
	v_pk_mov_b32 v[146:147], v[144:145], v[142:143] op_sel:[1,0]
	v_mov_b32_e32 v145, v143
	v_pk_add_f32 v[142:143], v[146:147], v[144:145]
	v_pk_mul_f32 v[136:137], v[70:71], v[70:71]
	v_add_f32_e32 v142, v142, v143
	v_pk_mul_f32 v[144:145], v[134:135], v[134:135]
	v_cvt_pk_bf16_f32 v134, v134, v135
	v_cvt_pk_bf16_f32 v135, v70, v71
	v_pk_mul_f32 v[70:71], v[138:139], v[100:101] op_sel_hi:[1,0]
	v_add_f32_e32 v143, v110, v142
	v_pk_mov_b32 v[146:147], v[144:145], v[136:137] op_sel:[1,0]
	v_mov_b32_e32 v145, v137
	ds_write2_b64 v99, v[68:69], v[134:135] offset1:4
	v_pk_mul_f32 v[68:69], v[140:141], v[100:101] op_sel_hi:[1,0]
	v_mul_f32_e32 v110, v70, v70
	v_pk_add_f32 v[136:137], v[146:147], v[144:145]
	v_pk_fma_f32 v[134:135], v[70:71], v[70:71], v[110:111] op_sel_hi:[1,1,0]
	v_mul_f32_e32 v110, v68, v68
	v_pk_add_f32 v[136:137], v[136:137], v[136:137] op_sel_hi:[0,1]
	v_pk_fma_f32 v[138:139], v[68:69], v[68:69], v[110:111] op_sel_hi:[1,1,0]
	v_cvt_pk_bf16_f32 v70, v70, v71
	v_cvt_pk_bf16_f32 v71, v68, v69
	v_pk_mul_f32 v[68:69], v[74:75], v[100:101] op_sel_hi:[1,0]
	v_pk_mul_f32 v[72:73], v[72:73], v[100:101] op_sel_hi:[1,0]
	v_mul_f32_e32 v136, v68, v68
	v_mul_f32_e32 v134, v72, v72
	v_mul_f32_e32 v138, v73, v73
	v_mul_f32_e32 v142, v69, v69
	v_pk_add_f32 v[74:75], v[134:135], v[138:139]
	v_pk_add_f32 v[134:135], v[136:137], v[142:143]
	s_and_b64 vcc, exec, s[2:3]
	v_pk_add_f32 v[74:75], v[74:75], v[134:135]
	s_mov_b32 s90, 1
	v_add_f32_e32 v110, v74, v75
	s_mov_b64 s[2:3], 0
	v_cvt_pk_bf16_f32 v72, v72, v73
	v_cvt_pk_bf16_f32 v73, v68, v69
	ds_write2_b64 v99, v[70:71], v[72:73] offset0:8 offset1:12
	s_cbranch_vccnz .LBB0_181

.LBB0_208:
	s_waitcnt vmcnt(0)
	v_lshlrev_b32_e32 v2, 1, v111
	v_lshl_add_u64 v[14:15], v[82:83], 0, v[2:3]
	global_load_dwordx2 v[20:21], v[14:15], off offset:3072
	v_readlane_b32 s8, v244, 0
	v_lshlrev_b32_e32 v18, 2, v111
	v_readlane_b32 s12, v244, 4
	v_readlane_b32 s13, v244, 5
	ds_bpermute_b32 v16, v128, v110
	v_readlane_b32 s4, v244, 57
	v_lshlrev_b64 v[12:13], 11, v[80:81]
	v_readlane_b32 s6, v244, 59
	v_readlane_b32 s7, v244, 60
	global_load_dwordx4 v[8:11], v18, s[12:13] offset:2048
	global_load_dwordx2 v[46:47], v[14:15], off offset:3104
	global_load_dwordx2 v[52:53], v[14:15], off offset:3136
	global_load_dwordx2 v[54:55], v[14:15], off offset:3168
	global_load_dwordx4 v[56:59], v18, s[12:13] offset:2112
	global_load_dwordx4 v[60:63], v18, s[12:13] offset:2176
	global_load_dwordx4 v[64:67], v18, s[12:13] offset:2240
	global_load_dwordx2 v[68:69], v[14:15], off offset:3200
	global_load_dwordx4 v[70:73], v18, s[12:13] offset:2304
	global_load_dwordx2 v[74:75], v[14:15], off offset:3232
	global_load_dwordx2 v[76:77], v[14:15], off offset:3264
	global_load_dwordx2 v[78:79], v[14:15], off offset:3296
	global_load_dwordx4 v[84:87], v18, s[12:13] offset:2368
	global_load_dwordx4 v[88:91], v18, s[12:13] offset:2432
	global_load_dwordx4 v[92:95], v18, s[12:13] offset:2496
	global_load_dwordx2 v[96:97], v[14:15], off offset:3328
	global_load_dwordx4 v[98:101], v18, s[12:13] offset:2560
	global_load_dwordx2 v[102:103], v[14:15], off offset:3360
	global_load_dwordx2 v[104:105], v[14:15], off offset:3392
	global_load_dwordx2 v[106:107], v[14:15], off offset:3424
	global_load_dwordx4 v[116:119], v18, s[12:13] offset:2624
	global_load_dwordx4 v[120:123], v18, s[12:13] offset:2688
	global_load_dwordx4 v[124:127], v18, s[12:13] offset:2752
	global_load_dwordx2 v[132:133], v[14:15], off offset:3456
	global_load_dwordx4 v[134:137], v18, s[12:13] offset:2816
	global_load_dwordx2 v[138:139], v[14:15], off offset:3488
	global_load_dwordx2 v[140:141], v[14:15], off offset:3520
	global_load_dwordx2 v[142:143], v[14:15], off offset:3552
	global_load_dwordx4 v[144:147], v18, s[12:13] offset:2880
	global_load_dwordx4 v[148:151], v18, s[12:13] offset:2944
	global_load_dwordx4 v[152:155], v18, s[12:13] offset:3008
	s_waitcnt lgkmcnt(0)
	v_add_f32_e32 v19, v110, v16
	ds_bpermute_b32 v28, v113, v19
	s_mov_b64 s[0:1], 0xdde0400
	v_lshl_add_u64 v[12:13], s[6:7], 0, v[12:13]
	v_lshl_add_u64 v[12:13], v[12:13], 0, s[0:1]
	s_mov_b32 s0, 0x800000
	s_waitcnt lgkmcnt(0)
	v_add_f32_e32 v19, v19, v28
	v_fmamk_f32 v19, v19, 0x3b800000, v180
	v_mul_f32_e32 v28, 0x4b800000, v19
	v_cmp_gt_f32_e32 vcc, s0, v19
	ds_read2_b64 v[4:7], v109 offset1:4
	v_cndmask_b32_e32 v19, v19, v28, vcc
	v_rsq_f32_e32 v19, v19
	v_lshl_add_u64 v[26:27], v[12:13], 0, v[2:3]
	s_waitcnt lgkmcnt(0)
	v_lshlrev_b32_e32 v29, 16, v4
	v_and_b32_e32 v31, 0xffff0000, v4
	v_mul_f32_e32 v4, 0x45800000, v19
	v_lshlrev_b32_e32 v33, 16, v5
	v_and_b32_e32 v35, 0xffff0000, v5
	v_cndmask_b32_e32 v5, v19, v4, vcc
	v_mov_b32_e32 v38, v5
	v_mov_b32_e32 v40, v5
	v_mov_b32_e32 v42, v5
	v_readlane_b32 s88, v243, 5
	v_readlane_b32 s20, v243, 30
	v_readlane_b32 s89, v243, 6
	v_readlane_b32 s0, v243, 8
	v_mov_b32_e32 v45, v3
	v_mov_b32_e32 v115, v3
	v_readlane_b32 s2, v244, 62
	v_readlane_b32 s10, v244, 2
	v_readlane_b32 s11, v244, 3
	v_mov_b32_e32 v51, v3
	v_readlane_b32 s9, v244, 1
	v_readlane_b32 s3, v244, 63
	v_readlane_b32 s14, v244, 6
	v_readlane_b32 s15, v244, 7
	v_readlane_b32 s5, v244, 58
	v_readlane_b32 s86, v243, 3
	v_readlane_b32 s22, v243, 28
	v_mov_b32_e32 v130, 0
	s_mov_b64 s[4:5], 0
	v_readlane_b32 s58, v243, 2
	v_readlane_b32 s87, v243, 4
	s_movk_i32 s84, 0x7f
	v_readlane_b32 s23, v243, 29
	v_readlane_b32 s21, v243, 31
	s_waitcnt vmcnt(31)
	v_lshlrev_b32_e32 v28, 16, v20
	v_mul_f32_e32 v4, 0xbfb8aa3b, v28
	v_exp_f32_e32 v4, v4
	v_and_b32_e32 v30, 0xffff0000, v20
	v_mul_f32_e32 v19, 0xbfb8aa3b, v30
	v_exp_f32_e32 v19, v19
	v_add_f32_e32 v4, 1.0, v4
	v_rcp_f32_e32 v4, v4
	v_lshlrev_b32_e32 v32, 16, v21
	v_and_b32_e32 v34, 0xffff0000, v21
	v_mul_f32_e32 v20, 0xbfb8aa3b, v32
	v_mul_f32_e32 v21, 0xbfb8aa3b, v34
	v_exp_f32_e32 v36, v20
	v_add_f32_e32 v19, 1.0, v19
	v_exp_f32_e32 v37, v21
	v_pk_mul_f32 v[20:21], v[4:5], v[28:29]
	v_rcp_f32_e32 v4, v19
	v_add_f32_e32 v19, 1.0, v36
	s_waitcnt vmcnt(30)
	v_mul_f32_e32 v8, v8, v21
	v_add_f32_e32 v36, 1.0, v37
	v_pk_mul_f32 v[28:29], v[4:5], v[30:31]
	v_rcp_f32_e32 v4, v19
	v_mul_f32_e32 v19, v20, v8
	v_mul_f32_e32 v8, v9, v29
	v_mul_f32_e32 v20, v28, v8
	v_pk_mul_f32 v[8:9], v[4:5], v[32:33]
	v_rcp_f32_e32 v4, v36
	v_mul_f32_e32 v9, v10, v9
	v_mul_f32_e32 v10, v8, v9
	v_cvt_pk_bf16_f32 v20, v19, v20
	v_pk_mul_f32 v[8:9], v[4:5], v[34:35]
	v_lshlrev_b32_e32 v28, 16, v7
	v_mul_f32_e32 v4, v11, v9
	v_mul_f32_e32 v4, v8, v4
	v_cvt_pk_bf16_f32 v21, v10, v4
	global_store_dwordx2 v[26:27], v[20:21], off
	v_and_b32_e32 v30, 0xffff0000, v7
	s_waitcnt vmcnt(30)
	v_lshlrev_b32_e32 v27, 16, v46
	v_and_b32_e32 v7, 0xffff0000, v46
	v_lshlrev_b32_e32 v29, 16, v47
	v_and_b32_e32 v31, 0xffff0000, v47
	v_mul_f32_e32 v4, 0xbfb8aa3b, v27
	v_mul_f32_e32 v19, 0xbfb8aa3b, v7
	v_mul_f32_e32 v22, 0xbfb8aa3b, v29
	v_mul_f32_e32 v23, 0xbfb8aa3b, v31
	v_exp_f32_e32 v4, v4
	v_exp_f32_e32 v19, v19
	v_exp_f32_e32 v22, v22
	v_exp_f32_e32 v23, v23
	v_add_f32_e32 v4, 1.0, v4
	v_add_f32_e32 v19, 1.0, v19
	v_add_f32_e32 v22, 1.0, v22
	v_add_f32_e32 v23, 1.0, v23
	v_rcp_f32_e32 v33, v4
	v_rcp_f32_e32 v35, v19
	v_rcp_f32_e32 v37, v22
	v_rcp_f32_e32 v39, v23
	v_lshlrev_b32_e32 v26, 16, v6
	v_and_b32_e32 v6, 0xffff0000, v6
	v_mov_b32_e32 v32, v5
	v_mov_b32_e32 v34, v5
	v_mov_b32_e32 v36, v5
	v_pk_mul_f32 v[22:23], v[32:33], v[26:27]
	v_pk_mul_f32 v[6:7], v[34:35], v[6:7]
	v_pk_mul_f32 v[26:27], v[36:37], v[28:29]
	v_mov_b32_e32 v21, v3
	v_or_b32_e32 v20, 32, v2
	v_pk_mul_f32 v[28:29], v[38:39], v[30:31]
	v_lshl_add_u64 v[20:21], v[12:13], 0, v[20:21]
	s_waitcnt vmcnt(29)
	v_and_b32_e32 v31, 0xffff0000, v53
	s_waitcnt vmcnt(27)
	v_mul_f32_e32 v4, v56, v22
	v_mul_f32_e32 v6, v57, v6
	v_mul_f32_e32 v8, v58, v26
	v_mul_f32_e32 v9, v59, v28
	v_mul_f32_e32 v6, v6, v7
	v_mul_f32_e32 v7, v8, v27
	v_mul_f32_e32 v4, v4, v23
	v_mul_f32_e32 v8, v9, v29
	v_cvt_pk_bf16_f32 v6, v4, v6
	v_cvt_pk_bf16_f32 v7, v7, v8
	global_store_dwordx2 v[20:21], v[6:7], off
	ds_read2_b64 v[20:23], v109 offset0:8 offset1:12
	v_lshlrev_b32_e32 v27, 16, v52
	v_lshlrev_b32_e32 v29, 16, v53
	v_mul_f32_e32 v4, 0xbfb8aa3b, v27
	v_mul_f32_e32 v25, 0xbfb8aa3b, v31
	s_waitcnt lgkmcnt(0)
	v_lshlrev_b32_e32 v28, 16, v21
	v_and_b32_e32 v30, 0xffff0000, v21
	v_and_b32_e32 v21, 0xffff0000, v52
	v_mul_f32_e32 v19, 0xbfb8aa3b, v21
	v_mul_f32_e32 v24, 0xbfb8aa3b, v29
	v_exp_f32_e32 v4, v4
	v_exp_f32_e32 v19, v19
	v_exp_f32_e32 v24, v24
	v_exp_f32_e32 v25, v25
	v_add_f32_e32 v4, 1.0, v4
	v_add_f32_e32 v19, 1.0, v19
	v_add_f32_e32 v24, 1.0, v24
	v_add_f32_e32 v25, 1.0, v25
	v_rcp_f32_e32 v33, v4
	v_rcp_f32_e32 v35, v19
	v_rcp_f32_e32 v37, v24
	v_rcp_f32_e32 v39, v25
	v_lshlrev_b32_e32 v26, 16, v20
	v_and_b32_e32 v20, 0xffff0000, v20
	v_pk_mul_f32 v[24:25], v[32:33], v[26:27]
	v_pk_mul_f32 v[20:21], v[34:35], v[20:21]
	v_pk_mul_f32 v[26:27], v[36:37], v[28:29]
	v_mov_b32_e32 v11, v3
	v_or_b32_e32 v10, 64, v2
	v_pk_mul_f32 v[28:29], v[38:39], v[30:31]
	v_lshl_add_u64 v[10:11], v[12:13], 0, v[10:11]
	v_mov_b32_e32 v30, v5
	s_waitcnt vmcnt(27)
	v_mul_f32_e32 v4, v60, v24
	v_mul_f32_e32 v6, v61, v20
	v_mul_f32_e32 v7, v62, v26
	v_mul_f32_e32 v8, v63, v28
	v_mul_f32_e32 v6, v6, v21
	v_mul_f32_e32 v7, v7, v27
	v_mul_f32_e32 v4, v4, v25
	v_mul_f32_e32 v8, v8, v29
	v_cvt_pk_bf16_f32 v6, v4, v6
	v_cvt_pk_bf16_f32 v7, v7, v8
	global_store_dwordx2 v[10:11], v[6:7], off
	v_lshlrev_b32_e32 v26, 16, v23
	v_and_b32_e32 v28, 0xffff0000, v23
	v_lshlrev_b32_e32 v21, 16, v54
	v_and_b32_e32 v23, 0xffff0000, v54
	v_lshlrev_b32_e32 v27, 16, v55
	v_and_b32_e32 v29, 0xffff0000, v55
	v_mul_f32_e32 v4, 0xbfb8aa3b, v21
	v_mul_f32_e32 v16, 0xbfb8aa3b, v23
	v_mul_f32_e32 v17, 0xbfb8aa3b, v27
	v_mul_f32_e32 v19, 0xbfb8aa3b, v29
	v_exp_f32_e32 v4, v4
	v_exp_f32_e32 v16, v16
	v_exp_f32_e32 v17, v17
	v_exp_f32_e32 v19, v19
	v_add_f32_e32 v4, 1.0, v4
	v_add_f32_e32 v16, 1.0, v16
	v_add_f32_e32 v17, 1.0, v17
	v_add_f32_e32 v19, 1.0, v19
	v_rcp_f32_e32 v31, v4
	v_rcp_f32_e32 v33, v16
	v_rcp_f32_e32 v35, v17
	v_rcp_f32_e32 v37, v19
	v_lshlrev_b32_e32 v20, 16, v22
	v_and_b32_e32 v22, 0xffff0000, v22
	v_pk_mul_f32 v[16:17], v[30:31], v[20:21]
	v_pk_mul_f32 v[20:21], v[32:33], v[22:23]
	v_pk_mul_f32 v[22:23], v[34:35], v[26:27]
	v_mov_b32_e32 v11, v3
	v_or_b32_e32 v10, 0x60, v2
	v_pk_mul_f32 v[26:27], v[36:37], v[28:29]
	v_lshl_add_u64 v[10:11], v[12:13], 0, v[10:11]
	s_waitcnt vmcnt(27)
	v_mul_f32_e32 v4, v64, v16
	v_mul_f32_e32 v6, v65, v20
	v_mul_f32_e32 v7, v66, v22
	v_mul_f32_e32 v8, v67, v26
	v_mul_f32_e32 v6, v6, v21
	v_mul_f32_e32 v7, v7, v23
	v_mul_f32_e32 v4, v4, v17
	v_mul_f32_e32 v8, v8, v27
	v_cvt_pk_bf16_f32 v6, v4, v6
	v_cvt_pk_bf16_f32 v7, v7, v8
	global_store_dwordx2 v[10:11], v[6:7], off
	ds_read2_b64 v[20:23], v109 offset0:16 offset1:20
	s_waitcnt vmcnt(27)
	v_lshlrev_b32_e32 v31, 16, v68
	v_lshlrev_b32_e32 v33, 16, v69
	v_and_b32_e32 v35, 0xffff0000, v69
	s_waitcnt lgkmcnt(0)
	v_lshlrev_b32_e32 v32, 16, v21
	v_and_b32_e32 v34, 0xffff0000, v21
	v_and_b32_e32 v21, 0xffff0000, v68
	v_mul_f32_e32 v4, 0xbfb8aa3b, v31
	v_mul_f32_e32 v19, 0xbfb8aa3b, v21
	v_mul_f32_e32 v24, 0xbfb8aa3b, v33
	v_mul_f32_e32 v25, 0xbfb8aa3b, v35
	v_exp_f32_e32 v4, v4
	v_exp_f32_e32 v19, v19
	v_exp_f32_e32 v24, v24
	v_exp_f32_e32 v25, v25
	v_add_f32_e32 v4, 1.0, v4
	v_add_f32_e32 v19, 1.0, v19
	v_add_f32_e32 v24, 1.0, v24
	v_add_f32_e32 v25, 1.0, v25
	v_rcp_f32_e32 v37, v4
	v_rcp_f32_e32 v39, v19
	v_rcp_f32_e32 v41, v24
	v_rcp_f32_e32 v43, v25
	v_lshlrev_b32_e32 v30, 16, v20
	v_and_b32_e32 v20, 0xffff0000, v20
	v_pk_mul_f32 v[24:25], v[36:37], v[30:31]
	v_pk_mul_f32 v[20:21], v[38:39], v[20:21]
	v_pk_mul_f32 v[30:31], v[40:41], v[32:33]
	v_mov_b32_e32 v17, v3
	v_or_b32_e32 v16, 0x80, v2
	v_pk_mul_f32 v[32:33], v[42:43], v[34:35]
	v_lshl_add_u64 v[16:17], v[12:13], 0, v[16:17]
	v_mov_b32_e32 v34, v5
	s_waitcnt vmcnt(26)
	v_mul_f32_e32 v4, v70, v24
	v_mul_f32_e32 v8, v71, v20
	v_mul_f32_e32 v9, v72, v30
	v_mul_f32_e32 v10, v73, v32
	v_mul_f32_e32 v8, v8, v21
	v_mul_f32_e32 v9, v9, v31
	v_mul_f32_e32 v4, v4, v25
	v_mul_f32_e32 v10, v10, v33
	v_cvt_pk_bf16_f32 v8, v4, v8
	v_cvt_pk_bf16_f32 v9, v9, v10
	global_store_dwordx2 v[16:17], v[8:9], off
	v_lshlrev_b32_e32 v24, 16, v23
	v_and_b32_e32 v30, 0xffff0000, v23
	s_waitcnt vmcnt(26)
	v_lshlrev_b32_e32 v21, 16, v74
	v_and_b32_e32 v23, 0xffff0000, v74
	v_lshlrev_b32_e32 v25, 16, v75
	v_and_b32_e32 v31, 0xffff0000, v75
	v_mul_f32_e32 v4, 0xbfb8aa3b, v21
	v_mul_f32_e32 v19, 0xbfb8aa3b, v23
	v_mul_f32_e32 v26, 0xbfb8aa3b, v25
	v_mul_f32_e32 v27, 0xbfb8aa3b, v31
	v_exp_f32_e32 v4, v4
	v_exp_f32_e32 v19, v19
	v_exp_f32_e32 v26, v26
	v_exp_f32_e32 v27, v27
	v_add_f32_e32 v4, 1.0, v4
	v_add_f32_e32 v19, 1.0, v19
	v_add_f32_e32 v26, 1.0, v26
	v_add_f32_e32 v27, 1.0, v27
	v_rcp_f32_e32 v33, v4
	v_rcp_f32_e32 v35, v19
	v_rcp_f32_e32 v37, v26
	v_rcp_f32_e32 v39, v27
	v_lshlrev_b32_e32 v20, 16, v22
	v_and_b32_e32 v22, 0xffff0000, v22
	v_mov_b32_e32 v32, v5
	v_pk_mul_f32 v[20:21], v[32:33], v[20:21]
	v_pk_mul_f32 v[22:23], v[34:35], v[22:23]
	v_pk_mul_f32 v[24:25], v[36:37], v[24:25]
	v_mov_b32_e32 v17, v3
	v_or_b32_e32 v16, 0xa0, v2
	v_pk_mul_f32 v[26:27], v[38:39], v[30:31]
	v_lshl_add_u64 v[16:17], v[12:13], 0, v[16:17]
	s_waitcnt vmcnt(25)
	v_and_b32_e32 v31, 0xffff0000, v77
	s_waitcnt vmcnt(23)
	v_mul_f32_e32 v4, v84, v20
	v_mul_f32_e32 v8, v85, v22
	v_mul_f32_e32 v9, v86, v24
	v_mul_f32_e32 v10, v87, v26
	v_mul_f32_e32 v8, v8, v23
	v_mul_f32_e32 v9, v9, v25
	v_mul_f32_e32 v4, v4, v21
	v_mul_f32_e32 v10, v10, v27
	v_cvt_pk_bf16_f32 v8, v4, v8
	v_cvt_pk_bf16_f32 v9, v9, v10
	global_store_dwordx2 v[16:17], v[8:9], off
	ds_read2_b64 v[20:23], v109 offset0:24 offset1:28
	v_lshlrev_b32_e32 v25, 16, v76
	v_lshlrev_b32_e32 v27, 16, v77
	v_mul_f32_e32 v4, 0xbfb8aa3b, v25
	v_mul_f32_e32 v29, 0xbfb8aa3b, v31
	s_waitcnt lgkmcnt(0)
	v_lshlrev_b32_e32 v26, 16, v21
	v_and_b32_e32 v30, 0xffff0000, v21
	v_and_b32_e32 v21, 0xffff0000, v76
	v_mul_f32_e32 v19, 0xbfb8aa3b, v21
	v_mul_f32_e32 v28, 0xbfb8aa3b, v27
	v_exp_f32_e32 v4, v4
	v_exp_f32_e32 v19, v19
	v_exp_f32_e32 v28, v28
	v_exp_f32_e32 v29, v29
	v_add_f32_e32 v4, 1.0, v4
	v_add_f32_e32 v19, 1.0, v19
	v_add_f32_e32 v28, 1.0, v28
	v_add_f32_e32 v29, 1.0, v29
	v_rcp_f32_e32 v33, v4
	v_rcp_f32_e32 v35, v19
	v_rcp_f32_e32 v37, v28
	v_rcp_f32_e32 v39, v29
	v_lshlrev_b32_e32 v24, 16, v20
	v_and_b32_e32 v20, 0xffff0000, v20
	v_pk_mul_f32 v[24:25], v[32:33], v[24:25]
	v_pk_mul_f32 v[20:21], v[34:35], v[20:21]
	v_pk_mul_f32 v[26:27], v[36:37], v[26:27]
	v_mov_b32_e32 v17, v3
	v_or_b32_e32 v16, 0xc0, v2
	v_pk_mul_f32 v[28:29], v[38:39], v[30:31]
	v_lshl_add_u64 v[16:17], v[12:13], 0, v[16:17]
	v_mov_b32_e32 v30, v5
	s_waitcnt vmcnt(23)
	v_mul_f32_e32 v4, v88, v24
	v_mul_f32_e32 v8, v89, v20
	v_mul_f32_e32 v9, v90, v26
	v_mul_f32_e32 v10, v91, v28
	v_mul_f32_e32 v8, v8, v21
	v_mul_f32_e32 v9, v9, v27
	v_mul_f32_e32 v4, v4, v25
	v_mul_f32_e32 v10, v10, v29
	v_cvt_pk_bf16_f32 v8, v4, v8
	v_cvt_pk_bf16_f32 v9, v9, v10
	global_store_dwordx2 v[16:17], v[8:9], off
	v_lshlrev_b32_e32 v26, 16, v23
	v_and_b32_e32 v28, 0xffff0000, v23
	v_lshlrev_b32_e32 v21, 16, v78
	v_and_b32_e32 v23, 0xffff0000, v78
	v_lshlrev_b32_e32 v27, 16, v79
	v_and_b32_e32 v29, 0xffff0000, v79
	v_mul_f32_e32 v4, 0xbfb8aa3b, v21
	v_mul_f32_e32 v6, 0xbfb8aa3b, v23
	v_mul_f32_e32 v7, 0xbfb8aa3b, v27
	v_mul_f32_e32 v19, 0xbfb8aa3b, v29
	v_exp_f32_e32 v4, v4
	v_exp_f32_e32 v6, v6
	v_exp_f32_e32 v7, v7
	v_exp_f32_e32 v19, v19
	v_add_f32_e32 v4, 1.0, v4
	v_add_f32_e32 v6, 1.0, v6
	v_add_f32_e32 v7, 1.0, v7
	v_add_f32_e32 v19, 1.0, v19
	v_rcp_f32_e32 v31, v4
	v_rcp_f32_e32 v33, v6
	v_rcp_f32_e32 v35, v7
	v_rcp_f32_e32 v37, v19
	v_lshlrev_b32_e32 v20, 16, v22
	v_and_b32_e32 v22, 0xffff0000, v22
	v_pk_mul_f32 v[6:7], v[30:31], v[20:21]
	v_pk_mul_f32 v[20:21], v[32:33], v[22:23]
	v_pk_mul_f32 v[22:23], v[34:35], v[26:27]
	v_mov_b32_e32 v17, v3
	v_or_b32_e32 v16, 0xe0, v2
	v_pk_mul_f32 v[26:27], v[36:37], v[28:29]
	v_lshl_add_u64 v[16:17], v[12:13], 0, v[16:17]
	s_waitcnt vmcnt(23)
	v_mul_f32_e32 v4, v92, v6
	v_mul_f32_e32 v6, v93, v20
	v_mul_f32_e32 v8, v94, v22
	v_mul_f32_e32 v9, v95, v26
	v_mul_f32_e32 v4, v4, v7
	v_mul_f32_e32 v6, v6, v21
	v_mul_f32_e32 v7, v8, v23
	v_mul_f32_e32 v8, v9, v27
	v_cvt_pk_bf16_f32 v6, v4, v6
	v_cvt_pk_bf16_f32 v7, v7, v8
	global_store_dwordx2 v[16:17], v[6:7], off
	ds_read2_b64 v[20:23], v109 offset0:32 offset1:36
	s_waitcnt vmcnt(23)
	v_lshlrev_b32_e32 v31, 16, v96
	v_lshlrev_b32_e32 v33, 16, v97
	v_and_b32_e32 v35, 0xffff0000, v97
	s_waitcnt lgkmcnt(0)
	v_lshlrev_b32_e32 v32, 16, v21
	v_and_b32_e32 v34, 0xffff0000, v21
	v_and_b32_e32 v21, 0xffff0000, v96
	v_mul_f32_e32 v4, 0xbfb8aa3b, v31
	v_mul_f32_e32 v19, 0xbfb8aa3b, v21
	v_mul_f32_e32 v24, 0xbfb8aa3b, v33
	v_mul_f32_e32 v25, 0xbfb8aa3b, v35
	v_exp_f32_e32 v4, v4
	v_exp_f32_e32 v19, v19
	v_exp_f32_e32 v24, v24
	v_exp_f32_e32 v25, v25
	v_add_f32_e32 v4, 1.0, v4
	v_add_f32_e32 v19, 1.0, v19
	v_add_f32_e32 v24, 1.0, v24
	v_add_f32_e32 v25, 1.0, v25
	v_rcp_f32_e32 v37, v4
	v_rcp_f32_e32 v39, v19
	v_rcp_f32_e32 v41, v24
	v_rcp_f32_e32 v43, v25
	v_lshlrev_b32_e32 v30, 16, v20
	v_and_b32_e32 v20, 0xffff0000, v20
	v_pk_mul_f32 v[24:25], v[36:37], v[30:31]
	v_pk_mul_f32 v[20:21], v[38:39], v[20:21]
	v_pk_mul_f32 v[30:31], v[40:41], v[32:33]
	v_mov_b32_e32 v17, v3
	v_or_b32_e32 v16, 0x100, v2
	v_pk_mul_f32 v[32:33], v[42:43], v[34:35]
	v_lshl_add_u64 v[16:17], v[12:13], 0, v[16:17]
	v_mov_b32_e32 v34, v5
	s_waitcnt vmcnt(22)
	v_mul_f32_e32 v4, v98, v24
	v_mul_f32_e32 v8, v99, v20
	v_mul_f32_e32 v9, v100, v30
	v_mul_f32_e32 v10, v101, v32
	v_mul_f32_e32 v8, v8, v21
	v_mul_f32_e32 v9, v9, v31
	v_mul_f32_e32 v4, v4, v25
	v_mul_f32_e32 v10, v10, v33
	v_cvt_pk_bf16_f32 v8, v4, v8
	v_cvt_pk_bf16_f32 v9, v9, v10
	global_store_dwordx2 v[16:17], v[8:9], off
	v_lshlrev_b32_e32 v24, 16, v23
	v_and_b32_e32 v30, 0xffff0000, v23
	s_waitcnt vmcnt(22)
	v_lshlrev_b32_e32 v21, 16, v102
	v_and_b32_e32 v23, 0xffff0000, v102
	v_lshlrev_b32_e32 v25, 16, v103
	v_and_b32_e32 v31, 0xffff0000, v103
	v_mul_f32_e32 v4, 0xbfb8aa3b, v21
	v_mul_f32_e32 v19, 0xbfb8aa3b, v23
	v_mul_f32_e32 v26, 0xbfb8aa3b, v25
	v_mul_f32_e32 v27, 0xbfb8aa3b, v31
	v_exp_f32_e32 v4, v4
	v_exp_f32_e32 v19, v19
	v_exp_f32_e32 v26, v26
	v_exp_f32_e32 v27, v27
	v_add_f32_e32 v4, 1.0, v4
	v_add_f32_e32 v19, 1.0, v19
	v_add_f32_e32 v26, 1.0, v26
	v_add_f32_e32 v27, 1.0, v27
	v_rcp_f32_e32 v33, v4
	v_rcp_f32_e32 v35, v19
	v_rcp_f32_e32 v37, v26
	v_rcp_f32_e32 v39, v27
	v_lshlrev_b32_e32 v20, 16, v22
	v_and_b32_e32 v22, 0xffff0000, v22
	v_mov_b32_e32 v32, v5
	v_pk_mul_f32 v[20:21], v[32:33], v[20:21]
	v_pk_mul_f32 v[22:23], v[34:35], v[22:23]
	v_pk_mul_f32 v[24:25], v[36:37], v[24:25]
	v_mov_b32_e32 v17, v3
	v_or_b32_e32 v16, 0x120, v2
	v_pk_mul_f32 v[26:27], v[38:39], v[30:31]
	v_lshl_add_u64 v[16:17], v[12:13], 0, v[16:17]
	s_waitcnt vmcnt(21)
	v_and_b32_e32 v31, 0xffff0000, v105
	s_waitcnt vmcnt(19)
	v_mul_f32_e32 v4, v116, v20
	v_mul_f32_e32 v8, v117, v22
	v_mul_f32_e32 v9, v118, v24
	v_mul_f32_e32 v10, v119, v26
	v_mul_f32_e32 v8, v8, v23
	v_mul_f32_e32 v9, v9, v25
	v_mul_f32_e32 v4, v4, v21
	v_mul_f32_e32 v10, v10, v27
	v_cvt_pk_bf16_f32 v8, v4, v8
	v_cvt_pk_bf16_f32 v9, v9, v10
	global_store_dwordx2 v[16:17], v[8:9], off
	ds_read2_b64 v[20:23], v109 offset0:40 offset1:44
	v_lshlrev_b32_e32 v25, 16, v104
	v_lshlrev_b32_e32 v27, 16, v105
	v_mul_f32_e32 v4, 0xbfb8aa3b, v25
	v_mul_f32_e32 v29, 0xbfb8aa3b, v31
	s_waitcnt lgkmcnt(0)
	v_lshlrev_b32_e32 v26, 16, v21
	v_and_b32_e32 v30, 0xffff0000, v21
	v_and_b32_e32 v21, 0xffff0000, v104
	v_mul_f32_e32 v19, 0xbfb8aa3b, v21
	v_mul_f32_e32 v28, 0xbfb8aa3b, v27
	v_exp_f32_e32 v4, v4
	v_exp_f32_e32 v19, v19
	v_exp_f32_e32 v28, v28
	v_exp_f32_e32 v29, v29
	v_add_f32_e32 v4, 1.0, v4
	v_add_f32_e32 v19, 1.0, v19
	v_add_f32_e32 v28, 1.0, v28
	v_add_f32_e32 v29, 1.0, v29
	v_rcp_f32_e32 v33, v4
	v_rcp_f32_e32 v35, v19
	v_rcp_f32_e32 v37, v28
	v_rcp_f32_e32 v39, v29
	v_lshlrev_b32_e32 v24, 16, v20
	v_and_b32_e32 v20, 0xffff0000, v20
	v_pk_mul_f32 v[24:25], v[32:33], v[24:25]
	v_pk_mul_f32 v[20:21], v[34:35], v[20:21]
	v_pk_mul_f32 v[26:27], v[36:37], v[26:27]
	v_mov_b32_e32 v17, v3
	v_or_b32_e32 v16, 0x140, v2
	v_pk_mul_f32 v[28:29], v[38:39], v[30:31]
	v_lshl_add_u64 v[16:17], v[12:13], 0, v[16:17]
	v_mov_b32_e32 v30, v5
	s_waitcnt vmcnt(19)
	v_mul_f32_e32 v4, v120, v24
	v_mul_f32_e32 v8, v121, v20
	v_mul_f32_e32 v9, v122, v26
	v_mul_f32_e32 v10, v123, v28
	v_mul_f32_e32 v8, v8, v21
	v_mul_f32_e32 v9, v9, v27
	v_mul_f32_e32 v4, v4, v25
	v_mul_f32_e32 v10, v10, v29
	v_cvt_pk_bf16_f32 v8, v4, v8
	v_cvt_pk_bf16_f32 v9, v9, v10
	global_store_dwordx2 v[16:17], v[8:9], off
	v_lshlrev_b32_e32 v26, 16, v23
	v_and_b32_e32 v28, 0xffff0000, v23
	v_lshlrev_b32_e32 v21, 16, v106
	v_and_b32_e32 v23, 0xffff0000, v106
	v_lshlrev_b32_e32 v27, 16, v107
	v_and_b32_e32 v29, 0xffff0000, v107
	v_mul_f32_e32 v4, 0xbfb8aa3b, v21
	v_mul_f32_e32 v6, 0xbfb8aa3b, v23
	v_mul_f32_e32 v7, 0xbfb8aa3b, v27
	v_mul_f32_e32 v19, 0xbfb8aa3b, v29
	v_exp_f32_e32 v4, v4
	v_exp_f32_e32 v6, v6
	v_exp_f32_e32 v7, v7
	v_exp_f32_e32 v19, v19
	v_add_f32_e32 v4, 1.0, v4
	v_add_f32_e32 v6, 1.0, v6
	v_add_f32_e32 v7, 1.0, v7
	v_add_f32_e32 v19, 1.0, v19
	v_rcp_f32_e32 v31, v4
	v_rcp_f32_e32 v33, v6
	v_rcp_f32_e32 v35, v7
	v_rcp_f32_e32 v37, v19
	v_lshlrev_b32_e32 v20, 16, v22
	v_and_b32_e32 v22, 0xffff0000, v22
	v_pk_mul_f32 v[6:7], v[30:31], v[20:21]
	v_pk_mul_f32 v[20:21], v[32:33], v[22:23]
	v_pk_mul_f32 v[22:23], v[34:35], v[26:27]
	v_mov_b32_e32 v17, v3
	v_or_b32_e32 v16, 0x160, v2
	v_pk_mul_f32 v[26:27], v[36:37], v[28:29]
	v_lshl_add_u64 v[16:17], v[12:13], 0, v[16:17]
	s_waitcnt vmcnt(19)
	v_mul_f32_e32 v4, v124, v6
	v_mul_f32_e32 v6, v125, v20
	v_mul_f32_e32 v8, v126, v22
	v_mul_f32_e32 v9, v127, v26
	v_mul_f32_e32 v4, v4, v7
	v_mul_f32_e32 v6, v6, v21
	v_mul_f32_e32 v7, v8, v23
	v_mul_f32_e32 v8, v9, v27
	v_cvt_pk_bf16_f32 v6, v4, v6
	v_cvt_pk_bf16_f32 v7, v7, v8
	global_store_dwordx2 v[16:17], v[6:7], off
	ds_read2_b64 v[20:23], v109 offset0:48 offset1:52
	v_mov_b32_e32 v17, v3
	v_or_b32_e32 v16, 0x180, v2
	v_lshl_add_u64 v[14:15], v[12:13], 0, v[16:17]
	s_waitcnt lgkmcnt(0)
	v_lshlrev_b32_e32 v30, 16, v21
	v_and_b32_e32 v32, 0xffff0000, v21
	s_waitcnt vmcnt(19)
	v_lshlrev_b32_e32 v17, 16, v132
	v_and_b32_e32 v21, 0xffff0000, v132
	v_lshlrev_b32_e32 v31, 16, v133
	v_and_b32_e32 v33, 0xffff0000, v133
	v_mul_f32_e32 v4, 0xbfb8aa3b, v17
	v_mul_f32_e32 v19, 0xbfb8aa3b, v21
	v_mul_f32_e32 v24, 0xbfb8aa3b, v31
	v_mul_f32_e32 v25, 0xbfb8aa3b, v33
	v_exp_f32_e32 v4, v4
	v_exp_f32_e32 v19, v19
	v_exp_f32_e32 v24, v24
	v_exp_f32_e32 v25, v25
	v_add_f32_e32 v4, 1.0, v4
	v_add_f32_e32 v19, 1.0, v19
	v_add_f32_e32 v24, 1.0, v24
	v_add_f32_e32 v25, 1.0, v25
	v_rcp_f32_e32 v35, v4
	v_rcp_f32_e32 v37, v19
	v_rcp_f32_e32 v39, v24
	v_rcp_f32_e32 v41, v25
	v_lshlrev_b32_e32 v16, 16, v20
	v_and_b32_e32 v20, 0xffff0000, v20
	v_pk_mul_f32 v[16:17], v[34:35], v[16:17]
	v_pk_mul_f32 v[20:21], v[36:37], v[20:21]
	v_pk_mul_f32 v[24:25], v[38:39], v[30:31]
	v_pk_mul_f32 v[30:31], v[40:41], v[32:33]
	v_mov_b32_e32 v32, v5
	s_waitcnt vmcnt(18)
	v_mul_f32_e32 v4, v134, v16
	v_mul_f32_e32 v8, v135, v20
	v_mul_f32_e32 v9, v136, v24
	v_mul_f32_e32 v10, v137, v30
	v_mul_f32_e32 v8, v8, v21
	v_mul_f32_e32 v9, v9, v25
	v_mul_f32_e32 v4, v4, v17
	v_mul_f32_e32 v10, v10, v31
	v_cvt_pk_bf16_f32 v8, v4, v8
	v_cvt_pk_bf16_f32 v9, v9, v10
	global_store_dwordx2 v[14:15], v[8:9], off
	v_lshlrev_b32_e32 v16, 16, v22
	v_and_b32_e32 v20, 0xffff0000, v22
	v_lshlrev_b32_e32 v22, 16, v23
	v_and_b32_e32 v24, 0xffff0000, v23
	s_waitcnt vmcnt(18)
	v_lshlrev_b32_e32 v17, 16, v138
	v_and_b32_e32 v21, 0xffff0000, v138
	v_lshlrev_b32_e32 v23, 16, v139
	v_and_b32_e32 v25, 0xffff0000, v139
	v_mul_f32_e32 v4, 0xbfb8aa3b, v17
	v_mul_f32_e32 v19, 0xbfb8aa3b, v21
	v_mul_f32_e32 v26, 0xbfb8aa3b, v23
	v_mul_f32_e32 v27, 0xbfb8aa3b, v25
	v_exp_f32_e32 v4, v4
	v_exp_f32_e32 v19, v19
	v_exp_f32_e32 v26, v26
	v_exp_f32_e32 v27, v27
	v_add_f32_e32 v4, 1.0, v4
	v_add_f32_e32 v19, 1.0, v19
	v_add_f32_e32 v26, 1.0, v26
	v_add_f32_e32 v27, 1.0, v27
	v_rcp_f32_e32 v31, v4
	v_rcp_f32_e32 v33, v19
	v_rcp_f32_e32 v35, v26
	v_rcp_f32_e32 v37, v27
	v_mov_b32_e32 v30, v5
	v_pk_mul_f32 v[16:17], v[30:31], v[16:17]
	v_pk_mul_f32 v[20:21], v[32:33], v[20:21]
	v_pk_mul_f32 v[22:23], v[34:35], v[22:23]
	v_mov_b32_e32 v15, v3
	v_or_b32_e32 v14, 0x1a0, v2
	v_pk_mul_f32 v[24:25], v[36:37], v[24:25]
	v_lshl_add_u64 v[14:15], v[12:13], 0, v[14:15]
	s_waitcnt vmcnt(17)
	v_and_b32_e32 v27, 0xffff0000, v141
	s_waitcnt vmcnt(15)
	v_mul_f32_e32 v4, v144, v16
	v_mul_f32_e32 v8, v145, v20
	v_mul_f32_e32 v9, v146, v22
	v_mul_f32_e32 v10, v147, v24
	v_mul_f32_e32 v8, v8, v21
	v_mul_f32_e32 v9, v9, v23
	v_mul_f32_e32 v4, v4, v17
	v_mul_f32_e32 v10, v10, v25
	v_cvt_pk_bf16_f32 v8, v4, v8
	v_cvt_pk_bf16_f32 v9, v9, v10
	global_store_dwordx2 v[14:15], v[8:9], off
	ds_read2_b64 v[14:17], v109 offset0:56 offset1:60
	v_lshlrev_b32_e32 v23, 16, v140
	v_lshlrev_b32_e32 v25, 16, v141
	v_mul_f32_e32 v4, 0xbfb8aa3b, v23
	v_mul_f32_e32 v29, 0xbfb8aa3b, v27
	s_waitcnt lgkmcnt(0)
	v_lshlrev_b32_e32 v24, 16, v15
	v_and_b32_e32 v26, 0xffff0000, v15
	v_and_b32_e32 v15, 0xffff0000, v140
	v_mul_f32_e32 v19, 0xbfb8aa3b, v15
	v_mul_f32_e32 v28, 0xbfb8aa3b, v25
	v_exp_f32_e32 v4, v4
	v_exp_f32_e32 v19, v19
	v_exp_f32_e32 v28, v28
	v_exp_f32_e32 v29, v29
	v_add_f32_e32 v4, 1.0, v4
	v_add_f32_e32 v19, 1.0, v19
	v_add_f32_e32 v28, 1.0, v28
	v_add_f32_e32 v29, 1.0, v29
	v_rcp_f32_e32 v31, v4
	v_rcp_f32_e32 v33, v19
	v_rcp_f32_e32 v35, v28
	v_rcp_f32_e32 v37, v29
	v_lshlrev_b32_e32 v22, 16, v14
	v_and_b32_e32 v14, 0xffff0000, v14
	v_pk_mul_f32 v[22:23], v[30:31], v[22:23]
	v_pk_mul_f32 v[14:15], v[32:33], v[14:15]
	v_pk_mul_f32 v[24:25], v[34:35], v[24:25]
	v_mov_b32_e32 v21, v3
	v_or_b32_e32 v20, 0x1c0, v2
	v_pk_mul_f32 v[26:27], v[36:37], v[26:27]
	v_lshl_add_u64 v[20:21], v[12:13], 0, v[20:21]
	v_or_b32_e32 v2, 0x1e0, v2
	v_mov_b32_e32 v28, v5
	v_lshlrev_b32_e32 v19, 16, v143
	v_lshl_add_u64 v[12:13], v[12:13], 0, v[2:3]
	v_mov_b32_e32 v30, v0
	s_waitcnt vmcnt(15)
	v_mul_f32_e32 v4, v148, v22
	v_mul_f32_e32 v8, v149, v14
	v_mul_f32_e32 v9, v150, v24
	v_mul_f32_e32 v10, v151, v26
	v_mul_f32_e32 v8, v8, v15
	v_mul_f32_e32 v9, v9, v25
	v_mul_f32_e32 v4, v4, v23
	v_mul_f32_e32 v10, v10, v27
	v_cvt_pk_bf16_f32 v8, v4, v8
	v_cvt_pk_bf16_f32 v9, v9, v10
	global_store_dwordx2 v[20:21], v[8:9], off
	v_lshlrev_b32_e32 v18, 16, v17
	v_and_b32_e32 v20, 0xffff0000, v17
	v_mov_b32_e32 v22, v5
	v_mov_b32_e32 v24, v5
	v_mov_b32_e32 v26, v5
	v_lshlrev_b32_e32 v5, 16, v142
	v_and_b32_e32 v17, 0xffff0000, v142
	v_and_b32_e32 v21, 0xffff0000, v143
	v_mul_f32_e32 v2, 0xbfb8aa3b, v5
	v_mul_f32_e32 v6, 0xbfb8aa3b, v17
	v_mul_f32_e32 v7, 0xbfb8aa3b, v19
	v_mul_f32_e32 v23, 0xbfb8aa3b, v21
	v_exp_f32_e32 v2, v2
	v_exp_f32_e32 v6, v6
	v_exp_f32_e32 v7, v7
	v_exp_f32_e32 v23, v23
	v_add_f32_e32 v2, 1.0, v2
	v_add_f32_e32 v6, 1.0, v6
	v_add_f32_e32 v7, 1.0, v7
	v_add_f32_e32 v29, 1.0, v23
	v_rcp_f32_e32 v23, v2
	v_rcp_f32_e32 v25, v6
	v_rcp_f32_e32 v27, v7
	v_rcp_f32_e32 v29, v29
	v_lshlrev_b32_e32 v4, 16, v16
	v_and_b32_e32 v16, 0xffff0000, v16
	v_pk_mul_f32 v[4:5], v[22:23], v[4:5]
	v_pk_mul_f32 v[6:7], v[24:25], v[16:17]
	v_pk_mul_f32 v[16:17], v[26:27], v[18:19]
	v_pk_mul_f32 v[18:19], v[28:29], v[20:21]
	v_mov_b64_e32 v[14:15], s[88:89]
	s_waitcnt vmcnt(15)
	v_mul_f32_e32 v2, v152, v4
	v_mul_f32_e32 v4, v153, v6
	v_mul_f32_e32 v6, v154, v16
	v_mul_f32_e32 v8, v155, v18
	v_mul_f32_e32 v2, v2, v5
	v_mul_f32_e32 v4, v4, v7
	v_mul_f32_e32 v5, v6, v17
	v_mul_f32_e32 v6, v8, v19
	v_cvt_pk_bf16_f32 v4, v2, v4
	v_cvt_pk_bf16_f32 v5, v5, v6
	global_store_dwordx2 v[12:13], v[4:5], off
	s_nop 0
	v_and_b32_e32 v52, 15, v30
	v_ashrrev_i32_e32 v2, 6, v30
	v_or_b32_e32 v5, s20, v52
	v_ashrrev_i32_e32 v46, 1, v30
	v_lshl_add_u32 v116, v2, 4, v5
	v_lshl_add_u32 v4, s0, 8, v46
	v_mad_i64_i32 v[118:119], s[0:1], v116, s92, v[14:15]
	v_ashrrev_i32_e32 v5, 31, v4
	v_readlane_b32 s0, v244, 50
	v_and_b32_e32 v50, 1, v30
	v_lshlrev_b64 v[4:5], 10, v[4:5]
	v_readlane_b32 s1, v244, 51
	v_bfe_u32 v47, v30, 4, 2
	v_lshlrev_b32_e32 v44, 6, v50
	v_lshl_add_u64 v[4:5], s[0:1], 0, v[4:5]
	v_lshlrev_b32_e32 v114, 4, v47
	v_lshl_add_u64 v[20:21], v[4:5], 0, v[44:45]
	v_lshl_add_u64 v[120:121], v[118:119], 0, v[114:115]
	global_load_dwordx4 v[4:7], v[20:21], off offset:48
	global_load_dwordx4 v[12:15], v[20:21], off offset:32
	global_load_dwordx4 v[16:19], v[20:21], off offset:16
	global_load_dwordx4 v[8:11], v[20:21], off
	global_load_dwordx4 v[28:31], v[20:21], off offset:512
	global_load_dwordx4 v[32:35], v[20:21], off offset:528
	global_load_dwordx4 v[36:39], v[20:21], off offset:544
	global_load_dwordx4 v[40:43], v[20:21], off offset:560
	s_nop 0
	global_load_dwordx4 v[20:23], v[120:121], off offset:3584
	global_load_dwordx4 v[24:27], v[120:121], off offset:3648
	v_readlane_b32 s0, v243, 0
	v_mul_lo_u32 v45, v46, s97
	s_and_b32 s0, s0, 7
	v_add_u32_e32 v48, 0, v45
	s_lshl_b32 s2, s0, 18
	v_add_u32_e32 v132, v48, v44
	v_mad_u64_u32 v[48:49], s[0:1], v46, s98, v[48:49]
	v_mul_u32_u24_e32 v45, 0x4200, v50
	v_lshlrev_b32_e32 v50, 7, v50
	v_mul_lo_u32 v131, v2, s93
	v_lshlrev_b32_e32 v2, 3, v47
	v_lshl_add_u64 v[122:123], s[10:11], 0, v[50:51]
	v_lshlrev_b32_e32 v50, 5, v47
	v_or_b32_e32 v47, 16, v52
	s_movk_i32 s0, 0x210
	v_lshl_add_u64 v[124:125], s[8:9], 0, v[50:51]
	global_load_dwordx4 v[224:227], v[124:125], off
	global_load_dwordx4 v[228:231], v[124:125], off offset:128
	global_load_dwordx4 v[232:235], v[124:125], off offset:16
	global_load_dwordx4 v[236:239], v[124:125], off offset:144
	v_mul_u32_u24_e32 v51, 0x210, v47
	v_mad_u32_u24 v47, v52, s0, v131
	v_add3_u32 v134, v47, v2, s96
	v_ashrrev_i32_e32 v47, 31, v46
	v_lshlrev_b64 v[46:47], 10, v[46:47]
	v_add_u32_e32 v49, 0, v114
	s_mov_b32 s1, s3
	v_lshl_add_u64 v[46:47], s[2:3], 0, v[46:47]
	v_mov_b32_e32 v133, v49
	v_mul_u32_u24_e32 v50, 0x90, v52
	v_writelane_b32 v244, s0, 62
	v_or_b32_e32 v46, v46, v44
	v_mul_u32_u24_e32 v115, 0x210, v52
	v_ashrrev_i32_e32 v117, 31, v116
	v_writelane_b32 v244, s1, 63
	v_lshl_add_u64 v[126:127], s[6:7], 0, v[46:47]
	s_mov_b64 s[0:1], 64
	v_and_b32_e32 v241, 24, v48
	v_and_b32_e32 v242, 32, v48
	v_and_b32_e32 v48, 0xffffffc7, v48
	v_lshlrev_b32_e32 v241, 1, v241
	v_lshrrev_b32_e32 v242, 2, v242
	v_or3_b32 v48, v48, v241, v242
	v_add_u32_e32 v135, v48, v45
	v_add_u32_e32 v136, v49, v50
	v_add_u32_e32 v137, v133, v51
	s_branch .LBB0_210
.LBB0_209:
	ds_read_b128 v[48:51], v136
	ds_read_b128 v[52:55], v136 offset:64
	ds_read_b128 v[56:59], v136 offset:2304
	ds_read_b128 v[60:63], v136 offset:2368
	s_add_u32 s0, s0, 64
	s_addc_u32 s1, s1, 0
	s_waitcnt lgkmcnt(3)
	v_mfma_f32_16x16x32_bf16 v[48:51], v[48:51], v[104:107], 0
	s_add_u32 s4, s4, 0x80
	s_addc_u32 s5, s5, 0
	s_cmpk_lg_i32 s4, 0x200
	s_waitcnt lgkmcnt(1)
	v_mfma_f32_16x16x32_bf16 v[56:59], v[56:59], v[104:107], 0
	v_mfma_f32_16x16x32_bf16 v[108:111], v[52:55], v[44:47], v[48:51]
	ds_read_b128 v[52:55], v136 offset:4672
	s_nop 1
	ds_read_b128 v[48:51], v136 offset:4608
	s_waitcnt lgkmcnt(2)
	v_mfma_f32_16x16x32_bf16 v[100:103], v[60:63], v[44:47], v[56:59]
	s_nop 2
	ds_read_b128 v[56:59], v136 offset:6912
	s_waitcnt lgkmcnt(1)
	v_mfma_f32_16x16x32_bf16 v[48:51], v[48:51], v[104:107], 0
	v_mfma_f32_16x16x32_bf16 v[96:99], v[52:55], v[44:47], v[48:51]
	s_nop 6
	ds_read_b128 v[48:51], v136 offset:6976
	s_waitcnt lgkmcnt(1)
	v_mfma_f32_16x16x32_bf16 v[52:55], v[56:59], v[104:107], 0
	ds_read_b128 v[56:59], v136 offset:9216
	s_waitcnt lgkmcnt(1)
	v_mfma_f32_16x16x32_bf16 v[92:95], v[48:51], v[44:47], v[52:55]
	ds_read_b128 v[48:51], v136 offset:9280
	s_waitcnt lgkmcnt(1)
	v_mfma_f32_16x16x32_bf16 v[52:55], v[56:59], v[104:107], 0
	ds_read_b128 v[56:59], v136 offset:11520
	s_waitcnt lgkmcnt(1)
	v_mfma_f32_16x16x32_bf16 v[88:91], v[48:51], v[44:47], v[52:55]
	ds_read_b128 v[48:51], v136 offset:11584
	s_waitcnt lgkmcnt(1)
	v_mfma_f32_16x16x32_bf16 v[52:55], v[56:59], v[104:107], 0
	ds_read_b128 v[56:59], v136 offset:13824
	s_waitcnt lgkmcnt(1)
	v_mfma_f32_16x16x32_bf16 v[84:87], v[48:51], v[44:47], v[52:55]
	ds_read_b128 v[48:51], v136 offset:13888
	s_waitcnt lgkmcnt(1)
	v_mfma_f32_16x16x32_bf16 v[52:55], v[56:59], v[104:107], 0
	ds_read_b128 v[56:59], v136 offset:16128
	s_waitcnt lgkmcnt(1)
	v_mfma_f32_16x16x32_bf16 v[80:83], v[48:51], v[44:47], v[52:55]
	ds_read_b128 v[48:51], v136 offset:16192
	s_waitcnt lgkmcnt(1)
	v_mfma_f32_16x16x32_bf16 v[52:55], v[56:59], v[104:107], 0
	ds_read_b128 v[56:59], v136 offset:18432
	s_waitcnt lgkmcnt(1)
	v_mfma_f32_16x16x32_bf16 v[76:79], v[48:51], v[44:47], v[52:55]
	ds_read_b128 v[48:51], v136 offset:18496
	s_waitcnt lgkmcnt(1)
	v_mfma_f32_16x16x32_bf16 v[52:55], v[56:59], v[104:107], 0
	ds_read_b128 v[56:59], v136 offset:20736
	s_waitcnt lgkmcnt(1)
	v_mfma_f32_16x16x32_bf16 v[68:71], v[48:51], v[44:47], v[52:55]
	ds_read_b128 v[48:51], v136 offset:20800
	s_waitcnt lgkmcnt(1)
	v_mfma_f32_16x16x32_bf16 v[52:55], v[56:59], v[104:107], 0
	ds_read_b128 v[56:59], v136 offset:23040
	ds_read_b128 v[60:63], v136 offset:23104
	ds_read_b128 v[138:141], v136 offset:25344
	ds_read_b128 v[142:145], v136 offset:25408
	s_waitcnt lgkmcnt(3)
	v_mfma_f32_16x16x32_bf16 v[56:59], v[56:59], v[104:107], 0
	s_waitcnt lgkmcnt(2)
	v_mfma_f32_16x16x32_bf16 v[72:75], v[60:63], v[44:47], v[56:59]
	v_mfma_f32_16x16x32_bf16 v[64:67], v[48:51], v[44:47], v[52:55]
	s_nop 4
	v_max3_f32 v56, v108, s16, v109
	v_max3_f32 v56, v56, v110, v111
	v_max3_f32 v60, v56, v100, v101
	s_waitcnt lgkmcnt(1)
	v_mfma_f32_16x16x32_bf16 v[56:59], v[138:141], v[104:107], 0
	v_max3_f32 v60, v60, v102, v103
	v_max3_f32 v60, v60, v96, v97
	v_max3_f32 v138, v60, v98, v99
	ds_read_b128 v[48:51], v136 offset:27648
	ds_read_b128 v[52:55], v136 offset:27712
	ds_read_b128 v[146:149], v136 offset:29952
	ds_read_b128 v[150:153], v136 offset:30016
	s_waitcnt lgkmcnt(4)
	v_mfma_f32_16x16x32_bf16 v[60:63], v[142:145], v[44:47], v[56:59]
	ds_read_b128 v[154:157], v136 offset:32256
	ds_read_b128 v[158:161], v136 offset:32320
	ds_read_b128 v[162:165], v136 offset:34560
	ds_read_b128 v[166:169], v136 offset:34624
	v_max3_f32 v56, v138, v92, v93
	v_max3_f32 v56, v56, v94, v95
	v_max3_f32 v56, v56, v88, v89
	s_waitcnt lgkmcnt(7)
	v_mfma_f32_16x16x32_bf16 v[48:51], v[48:51], v[104:107], 0
	v_max3_f32 v56, v56, v90, v91
	v_max3_f32 v56, v56, v84, v85
	v_max3_f32 v138, v56, v86, v87
	s_waitcnt lgkmcnt(6)
	v_mfma_f32_16x16x32_bf16 v[56:59], v[52:55], v[44:47], v[48:51]
	s_nop 2
	v_max3_f32 v48, v138, v80, v81
	v_max3_f32 v48, v48, v82, v83
	v_max3_f32 v52, v48, v76, v77
	s_waitcnt lgkmcnt(5)
	v_mfma_f32_16x16x32_bf16 v[48:51], v[146:149], v[104:107], 0
	v_max3_f32 v52, v52, v78, v79
	v_max3_f32 v52, v52, v68, v69
	v_max3_f32 v138, v52, v70, v71
	s_waitcnt lgkmcnt(4)
	v_mfma_f32_16x16x32_bf16 v[52:55], v[150:153], v[44:47], v[48:51]
	s_nop 2
	v_max3_f32 v48, v138, v64, v65
	v_max3_f32 v48, v48, v66, v67
	v_max3_f32 v138, v48, v72, v73
	s_waitcnt lgkmcnt(3)
	v_mfma_f32_16x16x32_bf16 v[48:51], v[154:157], v[104:107], 0
	v_max3_f32 v138, v138, v74, v75
	v_max3_f32 v138, v138, v60, v61
	v_max3_f32 v138, v138, v62, v63
	s_waitcnt lgkmcnt(1)
	v_mfma_f32_16x16x32_bf16 v[104:107], v[162:165], v[104:107], 0
	v_max3_f32 v138, v138, v56, v57
	v_max3_f32 v138, v138, v58, v59
	v_max3_f32 v138, v138, v52, v53
	v_mfma_f32_16x16x32_bf16 v[48:51], v[158:161], v[44:47], v[48:51]
	v_max3_f32 v138, v138, v54, v55
	s_waitcnt lgkmcnt(0)
	v_mfma_f32_16x16x32_bf16 v[44:47], v[166:169], v[44:47], v[104:107]
	s_nop 4
	v_max3_f32 v138, v138, v48, v49
	v_max3_f32 v138, v138, v50, v51
	s_nop 0
	v_max3_f32 v104, v138, v44, v45
	v_max3_f32 v104, v104, v46, v47
	ds_bpermute_b32 v105, v128, v104
	s_waitcnt lgkmcnt(0)
	v_max_f32_e32 v105, v105, v105
	v_max_f32_e32 v104, v104, v105
	ds_bpermute_b32 v105, v113, v104
	s_waitcnt lgkmcnt(0)
	v_max_f32_e32 v105, v105, v105
	v_max_f32_e32 v104, v104, v105
	v_sub_f32_e32 v105, v108, v104
	v_exp_f32_e32 v106, v105
	v_sub_f32_e32 v105, v109, v104
	v_exp_f32_e32 v107, v105
	v_sub_f32_e32 v105, v110, v104
	v_exp_f32_e32 v108, v105
	v_sub_f32_e32 v105, v111, v104
	v_exp_f32_e32 v110, v105
	v_sub_f32_e32 v100, v100, v104
	v_add_f32_e32 v105, 0, v106
	v_exp_f32_e32 v109, v100
	v_sub_f32_e32 v100, v101, v104
	v_add_f32_e32 v105, v107, v105
	v_exp_f32_e32 v111, v100
	v_sub_f32_e32 v100, v102, v104
	v_add_f32_e32 v105, v108, v105
	v_exp_f32_e32 v138, v100
	v_sub_f32_e32 v100, v103, v104
	v_add_f32_e32 v105, v110, v105
	v_exp_f32_e32 v139, v100
	v_add_f32_e32 v100, v109, v105
	v_add_f32_e32 v100, v111, v100
	v_add_f32_e32 v100, v138, v100
	v_sub_f32_e32 v96, v96, v104
	v_add_f32_e32 v102, v139, v100
	v_exp_f32_e32 v100, v96
	v_sub_f32_e32 v96, v97, v104
	v_exp_f32_e32 v101, v96
	v_sub_f32_e32 v96, v98, v104
	v_exp_f32_e32 v97, v96
	v_sub_f32_e32 v96, v99, v104
	v_exp_f32_e32 v98, v96
	v_sub_f32_e32 v92, v92, v104
	v_add_f32_e32 v96, v100, v102
	v_exp_f32_e32 v99, v92
	v_sub_f32_e32 v92, v93, v104
	v_add_f32_e32 v96, v101, v96
	v_exp_f32_e32 v102, v92
	v_sub_f32_e32 v92, v94, v104
	v_add_f32_e32 v96, v97, v96
	v_exp_f32_e32 v103, v92
	v_sub_f32_e32 v92, v95, v104
	v_add_f32_e32 v96, v98, v96
	v_exp_f32_e32 v105, v92
	v_add_f32_e32 v92, v99, v96
	v_add_f32_e32 v92, v102, v92
	v_add_f32_e32 v92, v103, v92
	v_sub_f32_e32 v88, v88, v104
	v_add_f32_e32 v94, v105, v92
	v_exp_f32_e32 v92, v88
	v_sub_f32_e32 v88, v89, v104
	v_exp_f32_e32 v93, v88
	v_sub_f32_e32 v88, v90, v104
	v_exp_f32_e32 v89, v88
	v_sub_f32_e32 v88, v91, v104
	v_exp_f32_e32 v90, v88
	v_sub_f32_e32 v84, v84, v104
	v_add_f32_e32 v88, v92, v94
	v_exp_f32_e32 v91, v84
	v_sub_f32_e32 v84, v85, v104
	v_add_f32_e32 v88, v93, v88
	v_exp_f32_e32 v94, v84
	v_sub_f32_e32 v84, v86, v104
	v_add_f32_e32 v88, v89, v88
	v_exp_f32_e32 v95, v84
	v_sub_f32_e32 v84, v87, v104
	v_add_f32_e32 v88, v90, v88
	v_exp_f32_e32 v96, v84
	v_add_f32_e32 v84, v91, v88
	v_add_f32_e32 v84, v94, v84
	v_add_f32_e32 v84, v95, v84
	v_sub_f32_e32 v80, v80, v104
	v_add_f32_e32 v86, v96, v84
	v_exp_f32_e32 v84, v80
	v_sub_f32_e32 v80, v81, v104
	v_exp_f32_e32 v85, v80
	v_sub_f32_e32 v80, v82, v104
	v_exp_f32_e32 v81, v80
	v_sub_f32_e32 v80, v83, v104
	v_exp_f32_e32 v82, v80
	v_sub_f32_e32 v76, v76, v104
	v_add_f32_e32 v80, v84, v86
	v_exp_f32_e32 v83, v76
	v_sub_f32_e32 v76, v77, v104
	v_add_f32_e32 v80, v85, v80
	v_exp_f32_e32 v86, v76
	v_sub_f32_e32 v76, v78, v104
	v_add_f32_e32 v80, v81, v80
	v_exp_f32_e32 v87, v76
	v_sub_f32_e32 v76, v79, v104
	v_add_f32_e32 v80, v82, v80
	v_exp_f32_e32 v88, v76
	v_add_f32_e32 v76, v83, v80
	v_add_f32_e32 v76, v86, v76
	v_add_f32_e32 v76, v87, v76
	v_sub_f32_e32 v68, v68, v104
	v_add_f32_e32 v78, v88, v76
	v_exp_f32_e32 v76, v68
	v_sub_f32_e32 v68, v69, v104
	v_exp_f32_e32 v77, v68
	v_sub_f32_e32 v68, v70, v104
	v_exp_f32_e32 v68, v68
	v_sub_f32_e32 v69, v71, v104
	v_exp_f32_e32 v69, v69
	v_sub_f32_e32 v64, v64, v104
	v_add_f32_e32 v70, v76, v78
	v_exp_f32_e32 v71, v64
	v_sub_f32_e32 v64, v65, v104
	v_add_f32_e32 v70, v77, v70
	v_exp_f32_e32 v78, v64
	v_sub_f32_e32 v64, v66, v104
	v_add_f32_e32 v70, v68, v70
	v_exp_f32_e32 v79, v64
	v_sub_f32_e32 v64, v67, v104
	v_add_f32_e32 v70, v69, v70
	v_exp_f32_e32 v80, v64
	v_add_f32_e32 v64, v71, v70
	v_add_f32_e32 v64, v78, v64
	v_add_f32_e32 v64, v79, v64
	v_add_f32_e32 v70, v80, v64
	v_sub_f32_e32 v64, v72, v104
	v_exp_f32_e32 v65, v64
	v_sub_f32_e32 v64, v73, v104
	v_exp_f32_e32 v67, v64
	v_sub_f32_e32 v64, v74, v104
	v_exp_f32_e32 v64, v64
	v_sub_f32_e32 v66, v75, v104
	v_exp_f32_e32 v66, v66
	v_sub_f32_e32 v60, v60, v104
	v_add_f32_e32 v70, v65, v70
	v_exp_f32_e32 v60, v60
	v_sub_f32_e32 v61, v61, v104
	v_add_f32_e32 v70, v67, v70
	v_exp_f32_e32 v61, v61
	v_sub_f32_e32 v62, v62, v104
	v_add_f32_e32 v70, v64, v70
	v_exp_f32_e32 v62, v62
	v_sub_f32_e32 v63, v63, v104
	v_add_f32_e32 v70, v66, v70
	v_exp_f32_e32 v63, v63
	v_add_f32_e32 v70, v60, v70
	v_add_f32_e32 v70, v61, v70
	v_add_f32_e32 v70, v62, v70
	v_add_f32_e32 v75, v63, v70
	v_sub_f32_e32 v56, v56, v104
	v_add_u32_e32 v70, v133, v115
	v_add_u32_e32 v73, 0x9000, v70
	v_add_u32_e32 v72, 0x9000, v137
	v_add_u32_e32 v70, 0xb000, v137
	v_exp_f32_e32 v74, v56
	v_add_u32_e32 v56, 0xd000, v137
	ds_read_b128 v[140:143], v73
	ds_read_b128 v[144:147], v72
	ds_read_b128 v[148:151], v70 offset:256
	ds_read_b128 v[152:155], v56 offset:512
	v_cvt_pk_bf16_f32 v106, v106, v107
	v_cvt_pk_bf16_f32 v107, v108, v110
	v_cvt_pk_bf16_f32 v108, v109, v111
	v_cvt_pk_bf16_f32 v109, v138, v139
	ds_read_b128 v[156:159], v73 offset:64
	s_waitcnt lgkmcnt(4)
	v_mfma_f32_16x16x32_bf16 v[138:141], v[140:143], v[106:109], 0
	v_cvt_pk_bf16_f32 v100, v100, v101
	v_cvt_pk_bf16_f32 v101, v97, v98
	v_cvt_pk_bf16_f32 v102, v99, v102
	s_waitcnt lgkmcnt(3)
	v_mfma_f32_16x16x32_bf16 v[142:145], v[144:147], v[106:109], 0
	v_cvt_pk_bf16_f32 v103, v103, v105
	ds_read_b128 v[160:163], v70 offset:320
	v_cvt_pk_bf16_f32 v92, v92, v93
	s_waitcnt lgkmcnt(3)
	v_mfma_f32_16x16x32_bf16 v[146:149], v[148:151], v[106:109], 0
	v_cvt_pk_bf16_f32 v93, v89, v90
	v_cvt_pk_bf16_f32 v94, v91, v94
	v_cvt_pk_bf16_f32 v95, v95, v96
	s_waitcnt lgkmcnt(2)
	v_mfma_f32_16x16x32_bf16 v[106:109], v[152:155], v[106:109], 0
	ds_read_b128 v[150:153], v72 offset:64
	v_cvt_pk_bf16_f32 v84, v84, v85
	v_cvt_pk_bf16_f32 v85, v81, v82
	s_waitcnt lgkmcnt(2)
	v_mfma_f32_16x16x32_bf16 v[138:141], v[156:159], v[100:103], v[138:141]
	ds_read_b128 v[154:157], v56 offset:576
	v_cvt_pk_bf16_f32 v86, v83, v86
	v_cvt_pk_bf16_f32 v87, v87, v88
	s_waitcnt lgkmcnt(1)
	v_mfma_f32_16x16x32_bf16 v[142:145], v[150:153], v[100:103], v[142:145]
	ds_read_b128 v[150:153], v73 offset:128
	v_sub_f32_e32 v57, v57, v104
	v_cvt_pk_bf16_f32 v76, v76, v77
	v_mfma_f32_16x16x32_bf16 v[146:149], v[160:163], v[100:103], v[146:149]
	v_cvt_pk_bf16_f32 v77, v68, v69
	v_cvt_pk_bf16_f32 v78, v71, v78
	v_cvt_pk_bf16_f32 v79, v79, v80
	s_waitcnt lgkmcnt(1)
	v_mfma_f32_16x16x32_bf16 v[98:101], v[154:157], v[100:103], v[106:109]
	ds_read_b128 v[154:157], v70 offset:384
	v_exp_f32_e32 v57, v57
	v_sub_f32_e32 v58, v58, v104
	ds_read_b128 v[106:109], v72 offset:128
	s_waitcnt lgkmcnt(2)
	v_mfma_f32_16x16x32_bf16 v[138:141], v[150:153], v[92:95], v[138:141]
	ds_read_b128 v[150:153], v56 offset:640
	v_exp_f32_e32 v58, v58
	v_sub_f32_e32 v59, v59, v104
	s_waitcnt lgkmcnt(1)
	v_mfma_f32_16x16x32_bf16 v[106:109], v[106:109], v[92:95], v[142:145]
	v_exp_f32_e32 v59, v59
	v_sub_f32_e32 v52, v52, v104
	v_add_f32_e32 v75, v74, v75
	v_mfma_f32_16x16x32_bf16 v[142:145], v[154:157], v[92:95], v[146:149]
	v_exp_f32_e32 v52, v52
	v_sub_f32_e32 v53, v53, v104
	v_add_f32_e32 v75, v57, v75
	ds_read_b128 v[146:149], v73 offset:192
	s_waitcnt lgkmcnt(1)
	v_mfma_f32_16x16x32_bf16 v[90:93], v[150:153], v[92:95], v[98:101]
	ds_read_b128 v[94:97], v72 offset:192
	v_exp_f32_e32 v53, v53
	v_sub_f32_e32 v54, v54, v104
	ds_read_b128 v[98:101], v70 offset:448
	s_waitcnt lgkmcnt(2)
	v_mfma_f32_16x16x32_bf16 v[138:141], v[146:149], v[84:87], v[138:141]
	ds_read_b128 v[146:149], v56 offset:704
	v_add_f32_e32 v75, v58, v75
	v_exp_f32_e32 v54, v54
	s_waitcnt lgkmcnt(2)
	v_mfma_f32_16x16x32_bf16 v[94:97], v[94:97], v[84:87], v[106:109]
	v_sub_f32_e32 v55, v55, v104
	v_add_f32_e32 v75, v59, v75
	v_exp_f32_e32 v55, v55
	ds_read_b128 v[106:109], v73 offset:256
	s_waitcnt lgkmcnt(2)
	v_mfma_f32_16x16x32_bf16 v[98:101], v[98:101], v[84:87], v[142:145]
	v_sub_f32_e32 v48, v48, v104
	v_add_f32_e32 v75, v52, v75
	v_exp_f32_e32 v102, v48
	s_waitcnt lgkmcnt(1)
	v_mfma_f32_16x16x32_bf16 v[82:85], v[146:149], v[84:87], v[90:93]
	ds_read_b128 v[86:89], v72 offset:256
	v_sub_f32_e32 v48, v49, v104
	v_add_f32_e32 v75, v53, v75
	ds_read_b128 v[90:93], v70 offset:512
	s_waitcnt lgkmcnt(2)
	v_mfma_f32_16x16x32_bf16 v[106:109], v[106:109], v[76:79], v[138:141]
	v_exp_f32_e32 v103, v48
	v_sub_f32_e32 v48, v50, v104
	v_add_f32_e32 v75, v54, v75
	ds_read_b128 v[138:141], v56 offset:768
	s_waitcnt lgkmcnt(2)
	v_mfma_f32_16x16x32_bf16 v[86:89], v[86:89], v[76:79], v[94:97]
	v_exp_f32_e32 v68, v48
	v_add_f32_e32 v75, v55, v75
	v_cvt_pk_bf16_f32 v80, v65, v67
	s_waitcnt lgkmcnt(1)
	v_mfma_f32_16x16x32_bf16 v[90:93], v[90:93], v[76:79], v[98:101]
	ds_read_b128 v[94:97], v72 offset:320
	v_cvt_pk_bf16_f32 v81, v64, v66
	ds_read_b128 v[64:67], v56 offset:832
	s_waitcnt lgkmcnt(2)
	v_mfma_f32_16x16x32_bf16 v[76:79], v[138:141], v[76:79], v[82:85]
	v_cvt_pk_bf16_f32 v82, v60, v61
	v_cvt_pk_bf16_f32 v83, v62, v63
	ds_read_b128 v[60:63], v70 offset:576
	v_add_f32_e32 v48, v102, v75
	v_add_f32_e32 v48, v103, v48
	v_add_f32_e32 v69, v68, v48
	v_sub_f32_e32 v71, v51, v104
	ds_read_b128 v[48:51], v73 offset:320
	s_waitcnt lgkmcnt(3)
	v_mfma_f32_16x16x32_bf16 v[84:87], v[94:97], v[80:83], v[86:89]
	v_exp_f32_e32 v71, v71
	v_sub_f32_e32 v44, v44, v104
	v_exp_f32_e32 v94, v44
	s_waitcnt lgkmcnt(1)
	v_mfma_f32_16x16x32_bf16 v[60:63], v[60:63], v[80:83], v[90:93]
	v_sub_f32_e32 v44, v45, v104
	v_exp_f32_e32 v95, v44
	v_sub_f32_e32 v45, v46, v104
	ds_read_b128 v[88:91], v73 offset:384
	v_mfma_f32_16x16x32_bf16 v[64:67], v[64:67], v[80:83], v[76:79]
	v_cvt_pk_bf16_f32 v76, v52, v53
	v_cvt_pk_bf16_f32 v77, v54, v55
	ds_read_b128 v[52:55], v70 offset:640
	s_waitcnt lgkmcnt(2)
	v_mfma_f32_16x16x32_bf16 v[48:51], v[48:51], v[80:83], v[106:109]
	v_add_f32_e32 v69, v71, v69
	v_cvt_pk_bf16_f32 v74, v74, v57
	v_exp_f32_e32 v57, v45
	v_sub_f32_e32 v45, v47, v104
	v_add_f32_e32 v44, v94, v69
	v_exp_f32_e32 v69, v45
	v_add_f32_e32 v44, v95, v44
	ds_read_b128 v[78:81], v72 offset:384
	v_cvt_pk_bf16_f32 v75, v58, v59
	v_add_f32_e32 v58, v57, v44
	s_waitcnt lgkmcnt(2)
	v_mfma_f32_16x16x32_bf16 v[48:51], v[88:91], v[74:77], v[48:51]
	ds_read_b128 v[88:91], v56 offset:896
	s_waitcnt lgkmcnt(2)
	v_mfma_f32_16x16x32_bf16 v[44:47], v[52:55], v[74:77], v[60:63]
	ds_read_b128 v[52:55], v73 offset:448
	v_add_f32_e32 v73, v69, v58
	ds_bpermute_b32 v82, v128, v73
	v_cvt_pk_bf16_f32 v69, v57, v69
	s_waitcnt lgkmcnt(3)
	v_mfma_f32_16x16x32_bf16 v[78:81], v[78:81], v[74:77], v[84:87]
	s_waitcnt lgkmcnt(0)
	v_add_f32_e32 v57, v73, v82
	v_mfma_f32_16x16x32_bf16 v[58:61], v[88:91], v[74:77], v[64:67]
	ds_bpermute_b32 v74, v113, v57
	v_cvt_pk_bf16_f32 v66, v102, v103
	v_cvt_pk_bf16_f32 v67, v68, v71
	v_cvt_pk_bf16_f32 v68, v94, v95
	s_nop 0
	v_mfma_f32_16x16x32_bf16 v[48:51], v[52:55], v[66:69], v[48:51]
	ds_read_b128 v[62:65], v72 offset:448
	ds_read_b128 v[52:55], v70 offset:704
	ds_read_b128 v[70:73], v56 offset:960
	s_waitcnt lgkmcnt(3)
	v_add_f32_e32 v56, v57, v74
	v_rcp_f32_e32 v56, v56
	s_waitcnt lgkmcnt(2)
	v_mfma_f32_16x16x32_bf16 v[62:65], v[62:65], v[66:69], v[78:81]
	v_mul_f32_e64 v50, v56, v50
	v_mul_f32_e64 v51, v56, v51
	v_pk_mul_f32 v[48:49], v[56:57], v[48:49] op_sel_hi:[0,1]
	s_waitcnt lgkmcnt(1)
	v_mfma_f32_16x16x32_bf16 v[44:47], v[52:55], v[66:69], v[44:47]
	s_waitcnt lgkmcnt(0)
	v_mfma_f32_16x16x32_bf16 v[52:55], v[70:73], v[66:69], v[58:61]
	s_nop 2
	v_mul_f32_e64 v58, v50, v50
	v_mul_f32_e64 v59, v51, v51
	v_pk_mul_f32 v[60:61], v[48:49], v[48:49]
	v_cvt_pk_bf16_f32 v48, v48, v49
	v_cvt_pk_bf16_f32 v49, v50, v51
	s_nop 0
	v_pk_mov_b32 v[66:67], v[60:61], v[58:59] op_sel:[1,0]
	v_mov_b32_e32 v61, v59
	v_pk_add_f32 v[58:59], v[66:67], v[60:61]
	s_nop 0
	v_add_f32_e32 v57, v58, v59
	v_pk_mul_f32 v[50:51], v[56:57], v[64:65] op_sel_hi:[0,1]
	v_pk_mul_f32 v[60:61], v[56:57], v[62:63] op_sel_hi:[0,1]
	v_pk_mul_f32 v[62:63], v[50:51], v[50:51]
	v_pk_mul_f32 v[64:65], v[60:61], v[60:61]
	v_pk_mul_f32 v[52:53], v[56:57], v[52:53] op_sel_hi:[0,1]
	v_pk_mov_b32 v[66:67], v[64:65], v[62:63] op_sel:[1,0]
	v_mov_b32_e32 v65, v63
	v_pk_add_f32 v[62:63], v[66:67], v[64:65]
	v_cvt_pk_bf16_f32 v60, v60, v61
	v_cvt_pk_bf16_f32 v61, v50, v51
	v_pk_mul_f32 v[46:47], v[56:57], v[46:47] op_sel_hi:[0,1]
	v_pk_mul_f32 v[44:45], v[56:57], v[44:45] op_sel_hi:[0,1]
	v_pk_mul_f32 v[50:51], v[56:57], v[54:55] op_sel_hi:[0,1]
	v_mul_f32_e32 v56, v53, v53
	v_pk_add_f32 v[54:55], v[62:63], v[62:63] op_sel:[0,1] op_sel_hi:[1,0]
	v_add_f32_e32 v58, v130, v57
	v_mul_f32_e32 v57, v50, v50
	v_mov_b32_e32 v55, v56
	v_mul_f32_e32 v56, v45, v45
	ds_write2_b64 v134, v[48:49], v[60:61] offset1:4
	v_cvt_pk_bf16_f32 v48, v44, v45
	v_pk_fma_f32 v[44:45], v[44:45], v[44:45], v[56:57] op_sel_hi:[1,1,0]
	v_mul_f32_e32 v56, v47, v47
	v_cvt_pk_bf16_f32 v49, v46, v47
	v_mul_f32_e32 v60, v51, v51
	v_pk_fma_f32 v[46:47], v[46:47], v[46:47], v[56:57] op_sel_hi:[1,1,0]
	v_mul_f32_e32 v59, v52, v52
	v_mov_b32_e32 v45, v57
	v_mov_b32_e32 v47, v60
	v_pk_add_f32 v[54:55], v[58:59], v[54:55]
	v_pk_add_f32 v[44:45], v[44:45], v[46:47]
	s_nop 0
	v_pk_add_f32 v[44:45], v[54:55], v[44:45]
	s_nop 0
	v_add_f32_e32 v130, v44, v45
	v_cvt_pk_bf16_f32 v44, v52, v53
	v_cvt_pk_bf16_f32 v45, v50, v51
	ds_write2_b64 v134, v[48:49], v[44:45] offset0:8 offset1:12
	v_add_u32_e32 v134, 0x80, v134
	s_cbranch_scc0 .LBB0_215
.LBB0_210:
	s_barrier
	global_load_dwordx4 v[44:47], v[122:123], off offset:16
	global_load_dwordx4 v[60:63], v[122:123], off
	global_load_dwordx4 v[52:55], v[122:123], off offset:48
	global_load_dwordx4 v[56:59], v[122:123], off offset:32
	global_load_dwordx4 v[48:51], v[122:123], off offset:80
	global_load_dwordx4 v[72:75], v[122:123], off offset:64
	global_load_dwordx4 v[64:67], v[122:123], off offset:112
	global_load_dwordx4 v[68:71], v[122:123], off offset:96
	s_waitcnt vmcnt(10)
	v_and_b32_e32 v83, 0xffff0000, v8
	v_lshlrev_b32_e32 v84, 16, v8
	v_mul_f32_e32 v96, v83, v83
	v_lshlrev_b32_e32 v82, 16, v9
	v_fmac_f32_e32 v96, v84, v84
	v_and_b32_e32 v81, 0xffff0000, v9
	v_fmac_f32_e32 v96, v82, v82
	v_lshlrev_b32_e32 v80, 16, v10
	v_fmac_f32_e32 v96, v81, v81
	v_and_b32_e32 v98, 0xffff0000, v10
	v_fmac_f32_e32 v96, v80, v80
	v_lshlrev_b32_e32 v99, 16, v11
	v_fmac_f32_e32 v96, v98, v98
	v_and_b32_e32 v100, 0xffff0000, v11
	v_fmac_f32_e32 v96, v99, v99
	v_lshlrev_b32_e32 v101, 16, v16
	v_fmac_f32_e32 v96, v100, v100
	v_and_b32_e32 v102, 0xffff0000, v16
	v_fmac_f32_e32 v96, v101, v101
	v_lshlrev_b32_e32 v103, 16, v17
	v_fmac_f32_e32 v96, v102, v102
	v_and_b32_e32 v104, 0xffff0000, v17
	v_fmac_f32_e32 v96, v103, v103
	v_lshlrev_b32_e32 v105, 16, v18
	v_fmac_f32_e32 v96, v104, v104
	v_and_b32_e32 v106, 0xffff0000, v18
	v_fmac_f32_e32 v96, v105, v105
	v_lshlrev_b32_e32 v107, 16, v19
	v_fmac_f32_e32 v96, v106, v106
	v_and_b32_e32 v108, 0xffff0000, v19
	v_fmac_f32_e32 v96, v107, v107
	v_lshlrev_b32_e32 v109, 16, v12
	v_fmac_f32_e32 v96, v108, v108
	v_and_b32_e32 v94, 0xffff0000, v12
	v_fmac_f32_e32 v96, v109, v109
	v_lshlrev_b32_e32 v92, 16, v13
	v_fmac_f32_e32 v96, v94, v94
	v_and_b32_e32 v95, 0xffff0000, v13
	v_fmac_f32_e32 v96, v92, v92
	v_lshlrev_b32_e32 v93, 16, v14
	v_fmac_f32_e32 v96, v95, v95
	v_and_b32_e32 v91, 0xffff0000, v14
	v_fmac_f32_e32 v96, v93, v93
	v_lshlrev_b32_e32 v90, 16, v15
	v_fmac_f32_e32 v96, v91, v91
	v_and_b32_e32 v89, 0xffff0000, v15
	v_fmac_f32_e32 v96, v90, v90
	v_lshlrev_b32_e32 v88, 16, v4
	v_fmac_f32_e32 v96, v89, v89
	v_and_b32_e32 v87, 0xffff0000, v4
	v_fmac_f32_e32 v96, v88, v88
	v_lshlrev_b32_e32 v86, 16, v5
	v_fmac_f32_e32 v96, v87, v87
	v_and_b32_e32 v85, 0xffff0000, v5
	v_fmac_f32_e32 v96, v86, v86
	v_and_b32_e32 v76, 0xffff0000, v6
	v_lshlrev_b32_e32 v77, 16, v6
	v_fmac_f32_e32 v96, v85, v85
	v_pk_mul_f32 v[78:79], v[76:77], v[76:77]
	s_cmpk_lg_i32 s4, 0x180
	v_add_f32_e32 v79, v79, v96
	v_add_f32_e32 v110, v78, v79
	v_and_b32_e32 v78, 0xffff0000, v7
	v_lshlrev_b32_e32 v79, 16, v7
	v_pk_mul_f32 v[96:97], v[78:79], v[78:79]
	s_cselect_b64 s[2:3], -1, 0
	v_add_f32_e32 v97, v97, v110
	v_add_f32_e32 v96, v96, v97
	ds_bpermute_b32 v97, v129, v96
	s_cmpk_eq_i32 s4, 0x180
	s_waitcnt lgkmcnt(0)
	v_add_f32_e32 v96, v96, v97
	v_fmamk_f32 v96, v96, 0x3c800000, v180
	v_rsq_f32_e32 v96, v96
	s_nop 0
	v_mul_f32_e32 v80, v96, v80
	v_mul_f32_e32 v81, v96, v81
	s_waitcnt vmcnt(7)
	v_mul_f32_e32 v80, v44, v80
	v_mul_f32_e32 v44, v96, v98
	v_mul_f32_e32 v82, v96, v82
	s_waitcnt vmcnt(6)
	v_mul_f32_e32 v63, v63, v81
	v_mul_f32_e32 v81, v45, v44
	v_mul_f32_e32 v44, v96, v99
	v_mul_f32_e32 v62, v62, v82
	v_mul_f32_e32 v82, v46, v44
	v_mul_f32_e32 v44, v96, v100
	v_mul_f32_e32 v47, v47, v44
	v_mul_f32_e32 v44, v96, v101
	s_waitcnt vmcnt(4)
	v_mul_f32_e32 v56, v56, v44
	v_mul_f32_e32 v44, v96, v102
	v_mul_f32_e32 v57, v57, v44
	v_mul_f32_e32 v44, v96, v103
	v_mul_f32_e32 v58, v58, v44
	v_mul_f32_e32 v44, v96, v104
	v_mul_f32_e32 v59, v59, v44
	v_mul_f32_e32 v44, v96, v105
	v_mul_f32_e32 v52, v52, v44
	v_mul_f32_e32 v44, v96, v106
	v_mul_f32_e32 v53, v53, v44
	v_mul_f32_e32 v44, v96, v107
	v_mul_f32_e32 v54, v54, v44
	v_mul_f32_e32 v44, v96, v108
	v_mul_f32_e32 v55, v55, v44
	v_mul_f32_e32 v44, v96, v109
	s_waitcnt vmcnt(2)
	v_mul_f32_e32 v72, v72, v44
	v_mul_f32_e32 v44, v96, v94
	v_mul_f32_e32 v73, v73, v44
	v_mul_f32_e32 v44, v96, v92
	v_mul_f32_e32 v74, v74, v44
	v_mul_f32_e32 v44, v96, v95
	v_mul_f32_e32 v75, v75, v44
	v_mul_f32_e32 v44, v96, v93
	v_mul_f32_e32 v48, v48, v44
	v_mul_f32_e32 v44, v96, v91
	v_mul_f32_e32 v49, v49, v44
	v_mul_f32_e32 v44, v96, v90
	v_mul_f32_e32 v50, v50, v44
	v_mul_f32_e32 v44, v96, v89
	v_mul_f32_e32 v51, v51, v44
	v_mul_f32_e32 v44, v96, v88
	s_waitcnt vmcnt(0)
	v_mul_f32_e32 v68, v68, v44
	v_mul_f32_e32 v44, v96, v87
	v_mul_f32_e32 v69, v69, v44
	v_mul_f32_e32 v44, v96, v86
	v_mul_f32_e32 v70, v44, v70
	v_mul_f32_e32 v44, v96, v85
	v_mul_f32_e32 v71, v44, v71
	v_mul_f32_e32 v44, v96, v77
	v_mul_f32_e32 v64, v44, v64
	v_mul_f32_e32 v44, v96, v76
	v_mul_f32_e32 v65, v44, v65
	v_mul_f32_e32 v44, v96, v79
	v_mul_f32_e32 v84, v96, v84
	v_mul_f32_e32 v83, v96, v83
	v_mul_f32_e32 v66, v44, v66
	v_mul_f32_e32 v44, v96, v78
	v_mul_f32_e32 v60, v60, v84
	v_mul_f32_e32 v61, v61, v83
	v_mul_f32_e32 v67, v44, v67
	v_cvt_pk_bf16_f32 v44, v60, v61
	v_cvt_pk_bf16_f32 v45, v62, v63
	v_cvt_pk_bf16_f32 v46, v80, v81
	v_cvt_pk_bf16_f32 v47, v82, v47
	ds_write_b128 v132, v[44:47]
	v_cvt_pk_bf16_f32 v44, v56, v57
	v_cvt_pk_bf16_f32 v45, v58, v59
	v_cvt_pk_bf16_f32 v46, v52, v53
	v_cvt_pk_bf16_f32 v47, v54, v55
	ds_write_b128 v132, v[44:47] offset:16
	v_cvt_pk_bf16_f32 v44, v72, v73
	v_cvt_pk_bf16_f32 v45, v74, v75
	v_cvt_pk_bf16_f32 v46, v48, v49
	v_cvt_pk_bf16_f32 v47, v50, v51
	ds_write_b128 v132, v[44:47] offset:32
	v_cvt_pk_bf16_f32 v44, v68, v69
	v_cvt_pk_bf16_f32 v45, v70, v71
	v_cvt_pk_bf16_f32 v46, v64, v65
	v_cvt_pk_bf16_f32 v47, v66, v67
	ds_write_b128 v132, v[44:47] offset:48
	ds_write_b16 v135, v28 offset:36864
	ds_write_b16_d16_hi v135, v28 offset:37392
	ds_write_b16 v135, v29 offset:37920
	ds_write_b16_d16_hi v135, v29 offset:38448
	ds_write_b16 v135, v30 offset:38976
	ds_write_b16_d16_hi v135, v30 offset:39504
	ds_write_b16 v135, v31 offset:40032
	ds_write_b16_d16_hi v135, v31 offset:40560
	ds_write_b16 v135, v32 offset:41088
	ds_write_b16_d16_hi v135, v32 offset:41616
	ds_write_b16 v135, v33 offset:42144
	ds_write_b16_d16_hi v135, v33 offset:42672
	ds_write_b16 v135, v34 offset:43200
	ds_write_b16_d16_hi v135, v34 offset:43728
	ds_write_b16 v135, v35 offset:44256
	ds_write_b16_d16_hi v135, v35 offset:44784
	ds_write_b16 v135, v36 offset:45312
	ds_write_b16_d16_hi v135, v36 offset:45840
	ds_write_b16 v135, v37 offset:46368
	ds_write_b16_d16_hi v135, v37 offset:46896
	ds_write_b16 v135, v38 offset:47424
	ds_write_b16_d16_hi v135, v38 offset:47952
	ds_write_b16 v135, v39 offset:48480
	ds_write_b16_d16_hi v135, v39 offset:49008
	ds_write_b16 v135, v40 offset:49536
	ds_write_b16_d16_hi v135, v40 offset:50064
	ds_write_b16 v135, v41 offset:50592
	ds_write_b16_d16_hi v135, v41 offset:51120
	ds_write_b16 v135, v42 offset:51648
	ds_write_b16_d16_hi v135, v42 offset:52176
	ds_write_b16 v135, v43 offset:52704
	ds_write_b16_d16_hi v135, v43 offset:53232
	s_waitcnt lgkmcnt(0)
	s_barrier
	s_cbranch_scc1 .LBB0_212
	v_lshl_add_u64 v[4:5], v[126:127], 0, s[4:5]
	s_mov_b64 s[6:7], 0xdbe0080
	v_add_co_u32_e32 v40, vcc, 0xdbe0000, v4
	v_lshl_add_u64 v[16:17], v[4:5], 0, s[6:7]
	s_nop 0
	v_addc_co_u32_e32 v41, vcc, 0, v5, vcc
	global_load_dwordx4 v[8:11], v[40:41], off offset:128
	global_load_dwordx4 v[4:7], v[16:17], off offset:48
	global_load_dwordx4 v[12:15], v[16:17], off offset:32
	s_nop 0
	global_load_dwordx4 v[16:19], v[16:17], off offset:16
	s_nop 0
	global_load_dwordx4 v[28:31], v[40:41], off offset:640
	global_load_dwordx4 v[32:35], v[40:41], off offset:656
	global_load_dwordx4 v[36:39], v[40:41], off offset:672
	s_nop 0
	global_load_dwordx4 v[40:43], v[40:41], off offset:688
	s_mov_b64 s[6:7], s[0:1]
	s_branch .LBB0_213

.LBB0_213:
	v_lshlrev_b32_e32 v72, 16, v24
	v_and_b32_e32 v73, 0xffff0000, v24
	v_lshlrev_b32_e32 v66, 16, v20
	v_and_b32_e32 v67, 0xffff0000, v20
	v_lshlrev_b32_e32 v74, 16, v25
	v_mul_f32_e32 v78, v72, v72
	v_mul_f32_e32 v79, v73, v73
	v_lshlrev_b32_e32 v68, 16, v21
	v_and_b32_e32 v75, 0xffff0000, v25
	v_mul_f32_e32 v80, v74, v74
	v_fmac_f32_e32 v78, v66, v66
	v_fmac_f32_e32 v79, v67, v67
	v_and_b32_e32 v69, 0xffff0000, v21
	v_lshlrev_b32_e32 v76, 16, v26
	v_mul_f32_e32 v81, v75, v75
	v_fmac_f32_e32 v80, v68, v68
	v_add_f32_e32 v78, v78, v79
	v_lshlrev_b32_e32 v70, 16, v22
	v_and_b32_e32 v77, 0xffff0000, v26
	v_mul_f32_e32 v82, v76, v76
	v_fmac_f32_e32 v81, v69, v69
	v_add_f32_e32 v78, v80, v78
	v_and_b32_e32 v71, 0xffff0000, v22
	v_and_b32_e32 v62, 0xffff0000, v27
	v_lshlrev_b32_e32 v63, 16, v27
	v_mul_f32_e32 v83, v77, v77
	v_fmac_f32_e32 v82, v70, v70
	v_add_f32_e32 v78, v81, v78
	v_and_b32_e32 v60, 0xffff0000, v23
	v_lshlrev_b32_e32 v61, 16, v23
	v_pk_mul_f32 v[64:65], v[62:63], v[62:63]
	v_fmac_f32_e32 v83, v71, v71
	v_add_f32_e32 v78, v82, v78
	v_pk_fma_f32 v[64:65], v[60:61], v[60:61], v[64:65]
	v_add_f32_e32 v78, v83, v78
	v_add_f32_e32 v65, v65, v78
	v_add_f32_e32 v64, v64, v65
	ds_bpermute_b32 v65, v128, v64
	s_andn2_b64 vcc, exec, s[2:3]
	s_waitcnt lgkmcnt(0)
	v_add_f32_e32 v64, v64, v65
	ds_bpermute_b32 v65, v113, v64
	s_waitcnt lgkmcnt(0)
	v_add_f32_e32 v64, v64, v65
	v_fmamk_f32 v64, v64, 0x3c800000, v180
	v_rsq_f32_e32 v64, v64
	s_nop 0
	v_mul_f32_e32 v64, 0x3e38aa3b, v64
	v_mul_f32_e32 v65, v64, v66
	v_mul_f32_e32 v66, v64, v72
	v_mul_f32_e32 v72, v64, v73
	v_mul_f32_e32 v73, v64, v74
	v_mul_f32_e32 v74, v64, v75
	v_mul_f32_e32 v75, v64, v76
	v_mul_f32_e32 v71, v64, v71
	v_mul_f32_e32 v76, v64, v77
	v_mul_f32_e32 v61, v64, v61
	v_mul_f32_e32 v63, v64, v63
	v_mul_f32_e32 v60, v64, v60
	v_mul_f32_e32 v62, v64, v62
	v_mul_f32_e32 v67, v64, v67
	v_mul_f32_e32 v68, v64, v68
	v_mul_f32_e32 v69, v64, v69
	v_mul_f32_e32 v70, v64, v70
	v_mul_f32_e32 v48, v224, v65
	v_mul_f32_e32 v56, v228, v66
	v_mul_f32_e32 v49, v225, v67
	v_mul_f32_e32 v64, v75, v236
	v_mul_f32_e32 v44, v71, v233
	v_mul_f32_e32 v53, v76, v237
	v_mul_f32_e32 v45, v61, v234
	v_mul_f32_e32 v54, v63, v238
	v_mul_f32_e32 v46, v60, v235
	v_mul_f32_e32 v47, v62, v239
	v_mul_f32_e32 v57, v229, v72
	v_mul_f32_e32 v50, v226, v68
	v_mul_f32_e32 v58, v230, v73
	v_mul_f32_e32 v51, v69, v227
	v_mul_f32_e32 v59, v74, v231
	v_mul_f32_e32 v52, v70, v232
	v_cvt_pk_bf16_f32 v104, v48, v49
	v_cvt_pk_bf16_f32 v105, v50, v51
	v_cvt_pk_bf16_f32 v106, v52, v44
	v_cvt_pk_bf16_f32 v107, v45, v46
	v_cvt_pk_bf16_f32 v44, v56, v57
	v_cvt_pk_bf16_f32 v45, v58, v59
	v_cvt_pk_bf16_f32 v46, v64, v53
	v_cvt_pk_bf16_f32 v47, v54, v47
	s_cbranch_vccnz .LBB0_209
	v_lshl_add_u64 v[24:25], s[6:7], 1, v[120:121]
	global_load_dwordx4 v[20:23], v[24:25], off offset:3584
	s_nop 0
	global_load_dwordx4 v[24:27], v[24:25], off offset:3648
	s_branch .LBB0_209
.LBB0_215:
	s_waitcnt vmcnt(0)
	s_mov_b64 s[0:1], 0x1000
	v_lshl_add_u64 v[16:17], v[118:119], 0, s[0:1]
	v_lshl_add_u64 v[4:5], v[16:17], 0, v[2:3]
	v_mov_b64_e32 v[50:51], v[4:5]
	global_load_dwordx2 v[8:9], v[4:5], off
	v_readlane_b32 s4, v244, 0
	v_readlane_b32 s8, v244, 4
	v_readlane_b32 s9, v244, 5
	ds_bpermute_b32 v14, v128, v130
	v_readlane_b32 s5, v244, 1
	v_readlane_b32 s6, v244, 2
	v_readlane_b32 s7, v244, 3
	v_readlane_b32 s4, v244, 57
	global_load_dwordx4 v[4:7], v114, s[8:9] offset:3072
	global_load_dwordx2 v[52:53], v[50:51], off offset:32
	global_load_dwordx2 v[54:55], v[50:51], off offset:64
	global_load_dwordx2 v[56:57], v[50:51], off offset:96
	global_load_dwordx4 v[58:61], v114, s[8:9] offset:3136
	global_load_dwordx4 v[62:65], v114, s[8:9] offset:3200
	global_load_dwordx4 v[66:69], v114, s[8:9] offset:3264
	global_load_dwordx2 v[70:71], v[50:51], off offset:128
	global_load_dwordx4 v[72:75], v114, s[8:9] offset:3328
	global_load_dwordx2 v[76:77], v[50:51], off offset:160
	global_load_dwordx2 v[78:79], v[50:51], off offset:192
	global_load_dwordx2 v[80:81], v[50:51], off offset:224
	global_load_dwordx4 v[82:85], v114, s[8:9] offset:3392
	global_load_dwordx4 v[86:89], v114, s[8:9] offset:3456
	global_load_dwordx4 v[90:93], v114, s[8:9] offset:3520
	global_load_dwordx2 v[94:95], v[50:51], off offset:256
	global_load_dwordx4 v[96:99], v114, s[8:9] offset:3584
	global_load_dwordx2 v[100:101], v[50:51], off offset:288
	global_load_dwordx2 v[102:103], v[50:51], off offset:320
	global_load_dwordx2 v[104:105], v[50:51], off offset:352
	global_load_dwordx4 v[106:109], v114, s[8:9] offset:3648
	global_load_dwordx4 v[120:123], v114, s[8:9] offset:3712
	global_load_dwordx4 v[124:127], v114, s[8:9] offset:3776
	global_load_dwordx2 v[110:111], v[50:51], off offset:384
	global_load_dwordx4 v[132:135], v114, s[8:9] offset:3840
	global_load_dwordx2 v[136:137], v[50:51], off offset:416
	global_load_dwordx2 v[138:139], v[50:51], off offset:448
	global_load_dwordx2 v[140:141], v[50:51], off offset:480
	global_load_dwordx4 v[142:145], v114, s[8:9] offset:3904
	global_load_dwordx4 v[146:149], v114, s[8:9] offset:3968
	global_load_dwordx4 v[150:153], v114, s[8:9] offset:4032
	s_waitcnt lgkmcnt(0)
	v_add_f32_e32 v14, v130, v14
	ds_bpermute_b32 v15, v113, v14
	v_lshlrev_b64 v[10:11], 11, v[116:117]
	v_readlane_b32 s6, v244, 59
	v_readlane_b32 s7, v244, 60
	v_add_u32_e32 v12, s96, v131
	s_mov_b64 s[0:1], 0xdde0600
	v_or_b32_e32 v22, 32, v2
	v_mov_b32_e32 v23, v3
	v_or_b32_e32 v24, 64, v2
	v_mov_b32_e32 v25, v3
	v_or_b32_e32 v18, 0x60, v2
	v_mov_b32_e32 v19, v3
	v_lshl_add_u64 v[10:11], s[6:7], 0, v[10:11]
	s_waitcnt lgkmcnt(0)
	v_add_f32_e32 v14, v14, v15
	v_add3_u32 v26, v12, v115, v2
	v_lshl_add_u64 v[12:13], v[10:11], 0, s[0:1]
	v_lshl_add_u64 v[10:11], v[16:17], 0, v[22:23]
	v_lshl_add_u64 v[20:21], v[16:17], 0, v[24:25]
	v_lshl_add_u64 v[32:33], v[16:17], 0, v[18:19]
	v_fmamk_f32 v14, v14, 0x3b800000, v180
	s_mov_b32 s0, 0x800000
	ds_read2_b64 v[28:31], v26 offset1:4
	s_nop 0
	s_nop 0
	v_mul_f32_e32 v15, 0x4b800000, v14
	v_cmp_gt_f32_e32 vcc, s0, v14
	v_lshl_add_u64 v[34:35], v[12:13], 0, v[2:3]
	s_waitcnt lgkmcnt(0)
	v_lshlrev_b32_e32 v33, 16, v28
	v_cndmask_b32_e32 v14, v14, v15, vcc
	v_rsq_f32_e32 v14, v14
	v_and_b32_e32 v39, 0xffff0000, v28
	v_lshlrev_b32_e32 v41, 16, v29
	v_and_b32_e32 v29, 0xffff0000, v29
	v_mul_f32_e32 v15, 0x45800000, v14
	v_cndmask_b32_e32 v15, v14, v15, vcc
	v_lshl_add_u64 v[18:19], v[12:13], 0, v[18:19]
	v_mov_b32_e32 v44, v15
	v_mov_b32_e32 v46, v15
	v_mov_b32_e32 v48, v15
	v_readlane_b32 s36, v244, 10
	v_readlane_b32 s42, v244, 16
	v_readlane_b32 s43, v244, 17
	v_readlane_b32 s10, v244, 6
	v_readlane_b32 s11, v244, 7
	v_readlane_b32 s5, v244, 58
	s_movk_i32 s0, 0x1000
	v_readlane_b32 s37, v244, 11
	v_readlane_b32 s40, v244, 14
	v_readlane_b32 s41, v244, 15
	s_mov_b32 s3, 0x7f800000
	s_mov_b32 s2, 0x33800000
	v_readlane_b32 s38, v244, 12
	v_readlane_b32 s39, v244, 13
	v_readlane_b32 s44, v244, 18
	v_readlane_b32 s45, v244, 19
	v_readlane_b32 s46, v244, 20
	v_readlane_b32 s47, v244, 21
	v_readlane_b32 s48, v244, 22
	v_readlane_b32 s49, v244, 23
	v_readlane_b32 s50, v244, 24
	v_readlane_b32 s51, v244, 25
	s_waitcnt vmcnt(31)
	v_lshlrev_b32_e32 v32, 16, v8
	v_and_b32_e32 v38, 0xffff0000, v8
	v_mul_f32_e32 v8, 0xbfb8aa3b, v32
	v_exp_f32_e32 v8, v8
	v_lshlrev_b32_e32 v40, 16, v9
	v_and_b32_e32 v28, 0xffff0000, v9
	v_mul_f32_e32 v9, 0xbfb8aa3b, v38
	v_exp_f32_e32 v9, v9
	v_add_f32_e32 v8, 1.0, v8
	v_rcp_f32_e32 v14, v8
	v_mul_f32_e32 v27, 0xbfb8aa3b, v40
	v_exp_f32_e32 v27, v27
	v_add_f32_e32 v43, 1.0, v9
	v_pk_mul_f32 v[8:9], v[14:15], v[32:33]
	v_rcp_f32_e32 v14, v43
	v_mul_f32_e32 v42, 0xbfb8aa3b, v28
	v_exp_f32_e32 v42, v42
	v_add_f32_e32 v27, 1.0, v27
	v_pk_mul_f32 v[32:33], v[14:15], v[38:39]
	v_rcp_f32_e32 v14, v27
	s_waitcnt vmcnt(30)
	v_mul_f32_e32 v4, v4, v9
	v_add_f32_e32 v42, 1.0, v42
	v_mul_f32_e32 v8, v8, v4
	v_mul_f32_e32 v4, v5, v33
	v_mul_f32_e32 v9, v32, v4
	v_pk_mul_f32 v[4:5], v[14:15], v[40:41]
	v_rcp_f32_e32 v14, v42
	v_mul_f32_e32 v5, v6, v5
	v_mul_f32_e32 v6, v4, v5
	v_cvt_pk_bf16_f32 v8, v8, v9
	v_pk_mul_f32 v[4:5], v[14:15], v[28:29]
	s_waitcnt vmcnt(29)
	v_and_b32_e32 v29, 0xffff0000, v52
	v_mul_f32_e32 v5, v7, v5
	v_mul_f32_e32 v4, v4, v5
	v_cvt_pk_bf16_f32 v9, v6, v4
	global_store_dwordx2 v[34:35], v[8:9], off
	v_lshl_add_u64 v[8:9], v[12:13], 0, v[22:23]
	v_lshlrev_b32_e32 v23, 16, v52
	v_lshlrev_b32_e32 v22, 16, v30
	v_and_b32_e32 v28, 0xffff0000, v30
	v_lshlrev_b32_e32 v30, 16, v31
	v_and_b32_e32 v32, 0xffff0000, v31
	v_lshlrev_b32_e32 v31, 16, v53
	v_and_b32_e32 v33, 0xffff0000, v53
	v_mul_f32_e32 v10, 0xbfb8aa3b, v23
	v_mul_f32_e32 v11, 0xbfb8aa3b, v29
	v_mul_f32_e32 v14, 0xbfb8aa3b, v31
	v_mul_f32_e32 v27, 0xbfb8aa3b, v33
	v_exp_f32_e32 v10, v10
	v_exp_f32_e32 v11, v11
	v_exp_f32_e32 v14, v14
	v_exp_f32_e32 v27, v27
	v_add_f32_e32 v10, 1.0, v10
	v_add_f32_e32 v11, 1.0, v11
	v_add_f32_e32 v14, 1.0, v14
	v_add_f32_e32 v27, 1.0, v27
	v_rcp_f32_e32 v35, v10
	v_rcp_f32_e32 v39, v11
	v_rcp_f32_e32 v41, v14
	v_rcp_f32_e32 v43, v27
	v_mov_b32_e32 v34, v15
	v_mov_b32_e32 v38, v15
	v_mov_b32_e32 v40, v15
	v_mov_b32_e32 v42, v15
	v_pk_mul_f32 v[10:11], v[34:35], v[22:23]
	v_pk_mul_f32 v[22:23], v[38:39], v[28:29]
	v_pk_mul_f32 v[28:29], v[40:41], v[30:31]
	v_pk_mul_f32 v[30:31], v[42:43], v[32:33]
	v_mov_b32_e32 v32, v15
	s_waitcnt vmcnt(27)
	v_mul_f32_e32 v4, v58, v10
	v_mul_f32_e32 v5, v59, v22
	v_mul_f32_e32 v6, v60, v28
	v_mul_f32_e32 v7, v61, v30
	v_mul_f32_e32 v4, v4, v11
	v_mul_f32_e32 v5, v5, v23
	v_mul_f32_e32 v6, v6, v29
	v_mul_f32_e32 v7, v7, v31
	v_cvt_pk_bf16_f32 v4, v4, v5
	v_cvt_pk_bf16_f32 v5, v6, v7
	global_store_dwordx2 v[8:9], v[4:5], off
	ds_read2_b64 v[4:7], v26 offset0:8 offset1:12
	v_lshlrev_b32_e32 v29, 16, v55
	v_lshl_add_u64 v[22:23], v[12:13], 0, v[24:25]
	v_lshlrev_b32_e32 v25, 16, v54
	v_and_b32_e32 v31, 0xffff0000, v55
	s_waitcnt lgkmcnt(0)
	v_lshlrev_b32_e32 v28, 16, v5
	v_and_b32_e32 v30, 0xffff0000, v5
	v_and_b32_e32 v5, 0xffff0000, v54
	v_mul_f32_e32 v27, 0xbfb8aa3b, v5
	v_mul_f32_e32 v33, 0xbfb8aa3b, v29
	v_mul_f32_e32 v14, 0xbfb8aa3b, v25
	v_mul_f32_e32 v35, 0xbfb8aa3b, v31
	v_exp_f32_e32 v27, v27
	v_exp_f32_e32 v33, v33
	v_exp_f32_e32 v14, v14
	v_exp_f32_e32 v35, v35
	v_add_f32_e32 v27, 1.0, v27
	v_add_f32_e32 v36, 1.0, v33
	v_add_f32_e32 v14, 1.0, v14
	v_add_f32_e32 v37, 1.0, v35
	v_rcp_f32_e32 v35, v27
	v_rcp_f32_e32 v39, v36
	v_rcp_f32_e32 v33, v14
	v_rcp_f32_e32 v41, v37
	v_lshlrev_b32_e32 v24, 16, v4
	v_and_b32_e32 v4, 0xffff0000, v4
	v_pk_mul_f32 v[4:5], v[34:35], v[4:5]
	v_pk_mul_f32 v[28:29], v[38:39], v[28:29]
	v_pk_mul_f32 v[24:25], v[32:33], v[24:25]
	v_pk_mul_f32 v[30:31], v[40:41], v[30:31]
	v_mov_b32_e32 v36, v15
	s_waitcnt vmcnt(27)
	v_mul_f32_e32 v4, v63, v4
	v_mul_f32_e32 v9, v64, v28
	v_mul_f32_e32 v8, v62, v24
	v_mul_f32_e32 v10, v65, v30
	v_mul_f32_e32 v4, v4, v5
	v_mul_f32_e32 v5, v9, v29
	v_mul_f32_e32 v8, v8, v25
	v_mul_f32_e32 v9, v10, v31
	v_cvt_pk_bf16_f32 v4, v8, v4
	v_cvt_pk_bf16_f32 v5, v5, v9
	global_store_dwordx2 v[22:23], v[4:5], off
	v_or_b32_e32 v10, 0x80, v2
	v_mov_b32_e32 v11, v3
	v_lshl_add_u64 v[4:5], v[16:17], 0, v[10:11]
	v_lshlrev_b32_e32 v28, 16, v7
	v_and_b32_e32 v30, 0xffff0000, v7
	v_lshlrev_b32_e32 v5, 16, v56
	v_and_b32_e32 v7, 0xffff0000, v56
	v_lshlrev_b32_e32 v29, 16, v57
	v_and_b32_e32 v31, 0xffff0000, v57
	v_mul_f32_e32 v14, 0xbfb8aa3b, v5
	v_mul_f32_e32 v20, 0xbfb8aa3b, v7
	v_mul_f32_e32 v21, 0xbfb8aa3b, v29
	v_mul_f32_e32 v27, 0xbfb8aa3b, v31
	v_exp_f32_e32 v14, v14
	v_exp_f32_e32 v20, v20
	v_exp_f32_e32 v21, v21
	v_exp_f32_e32 v27, v27
	v_add_f32_e32 v14, 1.0, v14
	v_add_f32_e32 v20, 1.0, v20
	v_add_f32_e32 v21, 1.0, v21
	v_add_f32_e32 v27, 1.0, v27
	v_rcp_f32_e32 v33, v14
	v_rcp_f32_e32 v35, v20
	v_rcp_f32_e32 v37, v21
	v_rcp_f32_e32 v39, v27
	v_lshlrev_b32_e32 v4, 16, v6
	v_and_b32_e32 v6, 0xffff0000, v6
	v_pk_mul_f32 v[4:5], v[32:33], v[4:5]
	v_pk_mul_f32 v[6:7], v[34:35], v[6:7]
	v_pk_mul_f32 v[20:21], v[36:37], v[28:29]
	v_pk_mul_f32 v[28:29], v[38:39], v[30:31]
	v_lshl_add_u64 v[10:11], v[12:13], 0, v[10:11]
	s_waitcnt vmcnt(27)
	v_mul_f32_e32 v4, v66, v4
	v_mul_f32_e32 v6, v67, v6
	v_mul_f32_e32 v14, v68, v20
	v_mul_f32_e32 v20, v69, v28
	v_mul_f32_e32 v4, v4, v5
	v_mul_f32_e32 v5, v6, v7
	v_mul_f32_e32 v6, v14, v21
	v_mul_f32_e32 v7, v20, v29
	v_cvt_pk_bf16_f32 v4, v4, v5
	v_cvt_pk_bf16_f32 v5, v6, v7
	global_store_dwordx2 v[18:19], v[4:5], off
	ds_read2_b64 v[28:31], v26 offset0:16 offset1:20
	v_or_b32_e32 v22, 0xa0, v2
	v_mov_b32_e32 v23, v3
	v_or_b32_e32 v24, 0xc0, v2
	v_mov_b32_e32 v25, v3
	v_or_b32_e32 v18, 0xe0, v2
	v_mov_b32_e32 v19, v3
	v_lshl_add_u64 v[20:21], v[16:17], 0, v[22:23]
	v_lshl_add_u64 v[32:33], v[16:17], 0, v[24:25]
	v_lshl_add_u64 v[34:35], v[16:17], 0, v[18:19]
	s_nop 0
	s_nop 0
	s_waitcnt lgkmcnt(0)
	v_lshlrev_b32_e32 v38, 16, v29
	v_and_b32_e32 v40, 0xffff0000, v29
	s_waitcnt vmcnt(27)
	v_lshlrev_b32_e32 v35, 16, v70
	v_and_b32_e32 v29, 0xffff0000, v70
	v_lshlrev_b32_e32 v39, 16, v71
	v_and_b32_e32 v41, 0xffff0000, v71
	v_mul_f32_e32 v8, 0xbfb8aa3b, v35
	v_mul_f32_e32 v9, 0xbfb8aa3b, v29
	v_mul_f32_e32 v14, 0xbfb8aa3b, v39
	v_mul_f32_e32 v27, 0xbfb8aa3b, v41
	v_exp_f32_e32 v8, v8
	v_exp_f32_e32 v9, v9
	v_exp_f32_e32 v14, v14
	v_exp_f32_e32 v27, v27
	v_add_f32_e32 v8, 1.0, v8
	v_add_f32_e32 v9, 1.0, v9
	v_add_f32_e32 v14, 1.0, v14
	v_add_f32_e32 v27, 1.0, v27
	v_rcp_f32_e32 v43, v8
	v_rcp_f32_e32 v45, v9
	v_rcp_f32_e32 v47, v14
	v_rcp_f32_e32 v49, v27
	v_lshlrev_b32_e32 v34, 16, v28
	v_and_b32_e32 v28, 0xffff0000, v28
	v_pk_mul_f32 v[8:9], v[42:43], v[34:35]
	v_pk_mul_f32 v[28:29], v[44:45], v[28:29]
	v_pk_mul_f32 v[34:35], v[46:47], v[38:39]
	v_pk_mul_f32 v[38:39], v[48:49], v[40:41]
	v_mov_b32_e32 v40, v15
	v_lshl_add_u64 v[18:19], v[12:13], 0, v[18:19]
	s_waitcnt vmcnt(26)
	v_mul_f32_e32 v4, v72, v8
	v_mul_f32_e32 v5, v73, v28
	v_mul_f32_e32 v6, v74, v34
	v_mul_f32_e32 v7, v75, v38
	v_mul_f32_e32 v4, v4, v9
	v_mul_f32_e32 v5, v5, v29
	v_mul_f32_e32 v6, v6, v35
	v_mul_f32_e32 v7, v7, v39
	v_cvt_pk_bf16_f32 v4, v4, v5
	v_cvt_pk_bf16_f32 v5, v6, v7
	global_store_dwordx2 v[10:11], v[4:5], off
	v_lshl_add_u64 v[8:9], v[12:13], 0, v[22:23]
	s_waitcnt vmcnt(26)
	v_lshlrev_b32_e32 v11, 16, v76
	v_and_b32_e32 v23, 0xffff0000, v76
	v_lshlrev_b32_e32 v10, 16, v30
	v_and_b32_e32 v22, 0xffff0000, v30
	v_lshlrev_b32_e32 v28, 16, v31
	v_and_b32_e32 v30, 0xffff0000, v31
	v_lshlrev_b32_e32 v29, 16, v77
	v_and_b32_e32 v31, 0xffff0000, v77
	v_mul_f32_e32 v14, 0xbfb8aa3b, v11
	v_mul_f32_e32 v27, 0xbfb8aa3b, v23
	v_mul_f32_e32 v35, 0xbfb8aa3b, v29
	v_mul_f32_e32 v36, 0xbfb8aa3b, v31
	v_exp_f32_e32 v14, v14
	v_exp_f32_e32 v27, v27
	v_exp_f32_e32 v35, v35
	v_exp_f32_e32 v36, v36
	v_add_f32_e32 v14, 1.0, v14
	v_add_f32_e32 v27, 1.0, v27
	v_add_f32_e32 v37, 1.0, v35
	v_add_f32_e32 v36, 1.0, v36
	v_rcp_f32_e32 v35, v14
	v_rcp_f32_e32 v39, v27
	v_rcp_f32_e32 v41, v37
	v_rcp_f32_e32 v43, v36
	v_mov_b32_e32 v34, v15
	v_mov_b32_e32 v38, v15
	v_pk_mul_f32 v[10:11], v[34:35], v[10:11]
	v_pk_mul_f32 v[22:23], v[38:39], v[22:23]
	v_pk_mul_f32 v[28:29], v[40:41], v[28:29]
	v_pk_mul_f32 v[30:31], v[42:43], v[30:31]
	v_mov_b32_e32 v36, v15
	s_waitcnt vmcnt(23)
	v_mul_f32_e32 v4, v82, v10
	v_mul_f32_e32 v5, v83, v22
	v_mul_f32_e32 v6, v84, v28
	v_mul_f32_e32 v7, v85, v30
	v_mul_f32_e32 v4, v4, v11
	v_mul_f32_e32 v5, v5, v23
	v_mul_f32_e32 v6, v6, v29
	v_mul_f32_e32 v7, v7, v31
	v_cvt_pk_bf16_f32 v4, v4, v5
	v_cvt_pk_bf16_f32 v5, v6, v7
	global_store_dwordx2 v[8:9], v[4:5], off
	ds_read2_b64 v[4:7], v26 offset0:24 offset1:28
	v_lshlrev_b32_e32 v29, 16, v79
	v_lshl_add_u64 v[22:23], v[12:13], 0, v[24:25]
	v_lshlrev_b32_e32 v25, 16, v78
	v_and_b32_e32 v31, 0xffff0000, v79
	s_waitcnt lgkmcnt(0)
	v_lshlrev_b32_e32 v28, 16, v5
	v_and_b32_e32 v30, 0xffff0000, v5
	v_and_b32_e32 v5, 0xffff0000, v78
	v_mul_f32_e32 v27, 0xbfb8aa3b, v5
	v_mul_f32_e32 v32, 0xbfb8aa3b, v29
	v_mul_f32_e32 v14, 0xbfb8aa3b, v25
	v_mul_f32_e32 v33, 0xbfb8aa3b, v31
	v_exp_f32_e32 v27, v27
	v_exp_f32_e32 v32, v32
	v_exp_f32_e32 v14, v14
	v_exp_f32_e32 v33, v33
	v_add_f32_e32 v27, 1.0, v27
	v_add_f32_e32 v32, 1.0, v32
	v_add_f32_e32 v14, 1.0, v14
	v_add_f32_e32 v33, 1.0, v33
	v_rcp_f32_e32 v37, v27
	v_rcp_f32_e32 v39, v32
	v_rcp_f32_e32 v35, v14
	v_rcp_f32_e32 v41, v33
	v_lshlrev_b32_e32 v24, 16, v4
	v_and_b32_e32 v4, 0xffff0000, v4
	v_pk_mul_f32 v[4:5], v[36:37], v[4:5]
	v_pk_mul_f32 v[28:29], v[38:39], v[28:29]
	v_pk_mul_f32 v[24:25], v[34:35], v[24:25]
	v_pk_mul_f32 v[30:31], v[40:41], v[30:31]
	v_mov_b32_e32 v32, v15
	s_waitcnt vmcnt(23)
	v_mul_f32_e32 v4, v87, v4
	v_mul_f32_e32 v9, v88, v28
	v_mul_f32_e32 v8, v86, v24
	v_mul_f32_e32 v10, v89, v30
	v_mul_f32_e32 v4, v4, v5
	v_mul_f32_e32 v5, v9, v29
	v_mul_f32_e32 v8, v8, v25
	v_mul_f32_e32 v9, v10, v31
	v_cvt_pk_bf16_f32 v4, v8, v4
	v_cvt_pk_bf16_f32 v5, v5, v9
	global_store_dwordx2 v[22:23], v[4:5], off
	v_or_b32_e32 v10, 0x100, v2
	v_mov_b32_e32 v11, v3
	v_lshl_add_u64 v[4:5], v[16:17], 0, v[10:11]
	v_lshlrev_b32_e32 v28, 16, v7
	v_and_b32_e32 v30, 0xffff0000, v7
	v_lshlrev_b32_e32 v5, 16, v80
	v_and_b32_e32 v7, 0xffff0000, v80
	v_lshlrev_b32_e32 v29, 16, v81
	v_and_b32_e32 v31, 0xffff0000, v81
	v_mul_f32_e32 v14, 0xbfb8aa3b, v5
	v_mul_f32_e32 v20, 0xbfb8aa3b, v7
	v_mul_f32_e32 v21, 0xbfb8aa3b, v29
	v_mul_f32_e32 v27, 0xbfb8aa3b, v31
	v_exp_f32_e32 v14, v14
	v_exp_f32_e32 v20, v20
	v_exp_f32_e32 v21, v21
	v_exp_f32_e32 v27, v27
	v_add_f32_e32 v14, 1.0, v14
	v_add_f32_e32 v20, 1.0, v20
	v_add_f32_e32 v21, 1.0, v21
	v_add_f32_e32 v27, 1.0, v27
	v_rcp_f32_e32 v33, v14
	v_rcp_f32_e32 v35, v20
	v_rcp_f32_e32 v37, v21
	v_rcp_f32_e32 v39, v27
	v_lshlrev_b32_e32 v4, 16, v6
	v_and_b32_e32 v6, 0xffff0000, v6
	v_pk_mul_f32 v[4:5], v[32:33], v[4:5]
	v_pk_mul_f32 v[6:7], v[34:35], v[6:7]
	v_pk_mul_f32 v[20:21], v[36:37], v[28:29]
	v_pk_mul_f32 v[28:29], v[38:39], v[30:31]
	v_lshl_add_u64 v[36:37], v[12:13], 0, v[10:11]
	s_waitcnt vmcnt(23)
	v_mul_f32_e32 v4, v90, v4
	v_mul_f32_e32 v6, v91, v6
	v_mul_f32_e32 v14, v92, v20
	v_mul_f32_e32 v20, v93, v28
	v_mul_f32_e32 v4, v4, v5
	v_mul_f32_e32 v5, v6, v7
	v_mul_f32_e32 v6, v14, v21
	v_mul_f32_e32 v7, v20, v29
	v_cvt_pk_bf16_f32 v4, v4, v5
	v_cvt_pk_bf16_f32 v5, v6, v7
	global_store_dwordx2 v[18:19], v[4:5], off
	ds_read2_b64 v[28:31], v26 offset0:32 offset1:36
	v_or_b32_e32 v20, 0x120, v2
	v_mov_b32_e32 v21, v3
	v_or_b32_e32 v22, 0x140, v2
	v_mov_b32_e32 v23, v3
	v_or_b32_e32 v18, 0x160, v2
	v_mov_b32_e32 v19, v3
	v_lshl_add_u64 v[24:25], v[16:17], 0, v[20:21]
	v_lshl_add_u64 v[32:33], v[16:17], 0, v[22:23]
	v_lshl_add_u64 v[34:35], v[16:17], 0, v[18:19]
	s_nop 0
	s_nop 0
	s_waitcnt lgkmcnt(0)
	v_lshlrev_b32_e32 v38, 16, v29
	v_and_b32_e32 v40, 0xffff0000, v29
	s_waitcnt vmcnt(23)
	v_lshlrev_b32_e32 v35, 16, v94
	v_and_b32_e32 v29, 0xffff0000, v94
	v_lshlrev_b32_e32 v39, 16, v95
	v_and_b32_e32 v41, 0xffff0000, v95
	v_mul_f32_e32 v8, 0xbfb8aa3b, v35
	v_mul_f32_e32 v9, 0xbfb8aa3b, v29
	v_mul_f32_e32 v14, 0xbfb8aa3b, v39
	v_mul_f32_e32 v27, 0xbfb8aa3b, v41
	v_exp_f32_e32 v8, v8
	v_exp_f32_e32 v9, v9
	v_exp_f32_e32 v14, v14
	v_exp_f32_e32 v27, v27
	v_add_f32_e32 v8, 1.0, v8
	v_add_f32_e32 v9, 1.0, v9
	v_add_f32_e32 v14, 1.0, v14
	v_add_f32_e32 v27, 1.0, v27
	v_rcp_f32_e32 v43, v8
	v_rcp_f32_e32 v45, v9
	v_rcp_f32_e32 v47, v14
	v_rcp_f32_e32 v49, v27
	v_lshlrev_b32_e32 v34, 16, v28
	v_and_b32_e32 v28, 0xffff0000, v28
	v_pk_mul_f32 v[8:9], v[42:43], v[34:35]
	v_pk_mul_f32 v[28:29], v[44:45], v[28:29]
	v_pk_mul_f32 v[34:35], v[46:47], v[38:39]
	v_pk_mul_f32 v[38:39], v[48:49], v[40:41]
	v_mov_b32_e32 v40, v15
	s_waitcnt vmcnt(22)
	v_mul_f32_e32 v4, v96, v8
	v_mul_f32_e32 v5, v97, v28
	v_mul_f32_e32 v6, v98, v34
	v_mul_f32_e32 v7, v99, v38
	v_mul_f32_e32 v4, v4, v9
	v_mul_f32_e32 v5, v5, v29
	v_mul_f32_e32 v6, v6, v35
	v_mul_f32_e32 v7, v7, v39
	v_cvt_pk_bf16_f32 v4, v4, v5
	v_cvt_pk_bf16_f32 v5, v6, v7
	global_store_dwordx2 v[36:37], v[4:5], off
	v_lshl_add_u64 v[8:9], v[12:13], 0, v[20:21]
	s_waitcnt vmcnt(22)
	v_lshlrev_b32_e32 v21, 16, v100
	v_and_b32_e32 v29, 0xffff0000, v100
	v_lshlrev_b32_e32 v20, 16, v30
	v_and_b32_e32 v28, 0xffff0000, v30
	v_lshlrev_b32_e32 v30, 16, v31
	v_and_b32_e32 v34, 0xffff0000, v31
	v_lshlrev_b32_e32 v31, 16, v101
	v_and_b32_e32 v35, 0xffff0000, v101
	v_mul_f32_e32 v14, 0xbfb8aa3b, v21
	v_mul_f32_e32 v24, 0xbfb8aa3b, v29
	v_mul_f32_e32 v25, 0xbfb8aa3b, v31
	v_mul_f32_e32 v27, 0xbfb8aa3b, v35
	v_exp_f32_e32 v14, v14
	v_exp_f32_e32 v24, v24
	v_exp_f32_e32 v25, v25
	v_exp_f32_e32 v27, v27
	v_add_f32_e32 v14, 1.0, v14
	v_add_f32_e32 v24, 1.0, v24
	v_add_f32_e32 v25, 1.0, v25
	v_add_f32_e32 v27, 1.0, v27
	v_rcp_f32_e32 v37, v14
	v_rcp_f32_e32 v39, v24
	v_rcp_f32_e32 v41, v25
	v_rcp_f32_e32 v43, v27
	v_mov_b32_e32 v36, v15
	v_mov_b32_e32 v38, v15
	v_pk_mul_f32 v[20:21], v[36:37], v[20:21]
	v_pk_mul_f32 v[24:25], v[38:39], v[28:29]
	v_pk_mul_f32 v[28:29], v[40:41], v[30:31]
	v_pk_mul_f32 v[30:31], v[42:43], v[34:35]
	v_mov_b32_e32 v34, v15
	s_waitcnt vmcnt(19)
	v_mul_f32_e32 v4, v106, v20
	v_mul_f32_e32 v5, v107, v24
	v_mul_f32_e32 v6, v108, v28
	v_mul_f32_e32 v7, v109, v30
	v_mul_f32_e32 v4, v4, v21
	v_mul_f32_e32 v5, v5, v25
	v_mul_f32_e32 v6, v6, v29
	v_mul_f32_e32 v7, v7, v31
	v_cvt_pk_bf16_f32 v4, v4, v5
	v_cvt_pk_bf16_f32 v5, v6, v7
	global_store_dwordx2 v[8:9], v[4:5], off
	ds_read2_b64 v[4:7], v26 offset0:40 offset1:44
	v_lshl_add_u64 v[8:9], v[12:13], 0, v[22:23]
	v_lshlrev_b32_e32 v21, 16, v102
	v_lshlrev_b32_e32 v23, 16, v103
	v_and_b32_e32 v25, 0xffff0000, v103
	s_waitcnt lgkmcnt(0)
	v_lshlrev_b32_e32 v22, 16, v5
	v_and_b32_e32 v24, 0xffff0000, v5
	v_and_b32_e32 v5, 0xffff0000, v102
	v_mul_f32_e32 v14, 0xbfb8aa3b, v21
	v_mul_f32_e32 v27, 0xbfb8aa3b, v5
	v_mul_f32_e32 v32, 0xbfb8aa3b, v23
	v_mul_f32_e32 v33, 0xbfb8aa3b, v25
	v_exp_f32_e32 v14, v14
	v_exp_f32_e32 v27, v27
	v_exp_f32_e32 v32, v32
	v_exp_f32_e32 v33, v33
	v_add_f32_e32 v14, 1.0, v14
	v_add_f32_e32 v27, 1.0, v27
	v_add_f32_e32 v32, 1.0, v32
	v_add_f32_e32 v33, 1.0, v33
	v_rcp_f32_e32 v35, v14
	v_rcp_f32_e32 v37, v27
	v_rcp_f32_e32 v39, v32
	v_rcp_f32_e32 v41, v33
	v_lshlrev_b32_e32 v20, 16, v4
	v_and_b32_e32 v4, 0xffff0000, v4
	v_pk_mul_f32 v[20:21], v[34:35], v[20:21]
	v_pk_mul_f32 v[4:5], v[36:37], v[4:5]
	v_pk_mul_f32 v[22:23], v[38:39], v[22:23]
	v_pk_mul_f32 v[24:25], v[40:41], v[24:25]
	v_mov_b32_e32 v32, v15
	s_waitcnt vmcnt(19)
	v_mul_f32_e32 v14, v120, v20
	v_mul_f32_e32 v4, v121, v4
	v_mul_f32_e32 v20, v122, v22
	v_mul_f32_e32 v22, v123, v24
	v_mul_f32_e32 v4, v4, v5
	v_mul_f32_e32 v5, v20, v23
	v_mul_f32_e32 v14, v14, v21
	v_mul_f32_e32 v20, v22, v25
	v_cvt_pk_bf16_f32 v4, v14, v4
	v_cvt_pk_bf16_f32 v5, v5, v20
	global_store_dwordx2 v[8:9], v[4:5], off
	v_or_b32_e32 v20, 0x180, v2
	v_mov_b32_e32 v21, v3
	v_lshl_add_u64 v[4:5], v[16:17], 0, v[20:21]
	v_lshl_add_u64 v[8:9], v[12:13], 0, v[18:19]
	v_lshlrev_b32_e32 v28, 16, v7
	v_and_b32_e32 v30, 0xffff0000, v7
	v_lshlrev_b32_e32 v5, 16, v104
	v_and_b32_e32 v7, 0xffff0000, v104
	v_lshlrev_b32_e32 v29, 16, v105
	v_and_b32_e32 v31, 0xffff0000, v105
	v_mul_f32_e32 v10, 0xbfb8aa3b, v5
	v_mul_f32_e32 v11, 0xbfb8aa3b, v7
	v_mul_f32_e32 v14, 0xbfb8aa3b, v29
	v_mul_f32_e32 v27, 0xbfb8aa3b, v31
	v_exp_f32_e32 v10, v10
	v_exp_f32_e32 v11, v11
	v_exp_f32_e32 v14, v14
	v_exp_f32_e32 v27, v27
	v_add_f32_e32 v10, 1.0, v10
	v_add_f32_e32 v11, 1.0, v11
	v_add_f32_e32 v14, 1.0, v14
	v_add_f32_e32 v27, 1.0, v27
	v_rcp_f32_e32 v33, v10
	v_rcp_f32_e32 v35, v11
	v_rcp_f32_e32 v37, v14
	v_rcp_f32_e32 v39, v27
	v_lshlrev_b32_e32 v4, 16, v6
	v_and_b32_e32 v6, 0xffff0000, v6
	v_pk_mul_f32 v[4:5], v[32:33], v[4:5]
	v_pk_mul_f32 v[6:7], v[34:35], v[6:7]
	v_pk_mul_f32 v[10:11], v[36:37], v[28:29]
	v_pk_mul_f32 v[28:29], v[38:39], v[30:31]
	v_lshl_add_u64 v[20:21], v[12:13], 0, v[20:21]
	s_waitcnt vmcnt(19)
	v_mul_f32_e32 v4, v124, v4
	v_mul_f32_e32 v6, v125, v6
	v_mul_f32_e32 v10, v126, v10
	v_mul_f32_e32 v14, v127, v28
	v_mul_f32_e32 v4, v4, v5
	v_mul_f32_e32 v5, v6, v7
	v_mul_f32_e32 v6, v10, v11
	v_mul_f32_e32 v7, v14, v29
	v_cvt_pk_bf16_f32 v4, v4, v5
	v_cvt_pk_bf16_f32 v5, v6, v7
	global_store_dwordx2 v[8:9], v[4:5], off
	ds_read2_b64 v[8:11], v26 offset0:48 offset1:52
	s_waitcnt vmcnt(19)
	v_lshlrev_b32_e32 v33, 16, v110
	v_lshlrev_b32_e32 v35, 16, v111
	v_and_b32_e32 v37, 0xffff0000, v111
	v_mul_f32_e32 v14, 0xbfb8aa3b, v33
	s_waitcnt lgkmcnt(0)
	v_lshlrev_b32_e32 v34, 16, v9
	v_and_b32_e32 v36, 0xffff0000, v9
	v_and_b32_e32 v9, 0xffff0000, v110
	v_mul_f32_e32 v18, 0xbfb8aa3b, v9
	v_mul_f32_e32 v19, 0xbfb8aa3b, v35
	v_mul_f32_e32 v27, 0xbfb8aa3b, v37
	v_exp_f32_e32 v14, v14
	v_exp_f32_e32 v18, v18
	v_or_b32_e32 v22, 0x1a0, v2
	v_mov_b32_e32 v23, v3
	v_or_b32_e32 v24, 0x1c0, v2
	v_mov_b32_e32 v25, v3
	v_or_b32_e32 v2, 0x1e0, v2
	v_exp_f32_e32 v19, v19
	v_exp_f32_e32 v27, v27
	v_lshl_add_u64 v[28:29], v[16:17], 0, v[22:23]
	v_lshl_add_u64 v[30:31], v[16:17], 0, v[24:25]
	v_lshl_add_u64 v[16:17], v[16:17], 0, v[2:3]
	s_nop 0
	s_nop 0
	v_add_f32_e32 v14, 1.0, v14
	v_add_f32_e32 v18, 1.0, v18
	v_add_f32_e32 v19, 1.0, v19
	v_add_f32_e32 v27, 1.0, v27
	v_rcp_f32_e32 v39, v14
	v_rcp_f32_e32 v41, v18
	v_rcp_f32_e32 v43, v19
	v_rcp_f32_e32 v45, v27
	v_lshlrev_b32_e32 v32, 16, v8
	v_and_b32_e32 v8, 0xffff0000, v8
	v_pk_mul_f32 v[18:19], v[38:39], v[32:33]
	v_pk_mul_f32 v[8:9], v[40:41], v[8:9]
	v_pk_mul_f32 v[32:33], v[42:43], v[34:35]
	v_pk_mul_f32 v[34:35], v[44:45], v[36:37]
	v_mov_b32_e32 v36, v15
	v_mov_b32_e32 v42, v0
	s_waitcnt vmcnt(18)
	v_mul_f32_e32 v4, v132, v18
	v_mul_f32_e32 v5, v133, v8
	v_mul_f32_e32 v6, v134, v32
	v_mul_f32_e32 v7, v135, v34
	v_mul_f32_e32 v4, v4, v19
	v_mul_f32_e32 v5, v5, v9
	v_mul_f32_e32 v6, v6, v33
	v_mul_f32_e32 v7, v7, v35
	v_cvt_pk_bf16_f32 v4, v4, v5
	v_cvt_pk_bf16_f32 v5, v6, v7
	global_store_dwordx2 v[20:21], v[4:5], off
	v_lshl_add_u64 v[8:9], v[12:13], 0, v[22:23]
	v_lshlrev_b32_e32 v20, 16, v11
	v_and_b32_e32 v22, 0xffff0000, v11
	v_lshlrev_b32_e32 v18, 16, v10
	v_and_b32_e32 v10, 0xffff0000, v10
	v_mov_b32_e32 v32, v15
	v_mov_b32_e32 v34, v15
	s_waitcnt vmcnt(18)
	v_lshlrev_b32_e32 v19, 16, v136
	v_and_b32_e32 v11, 0xffff0000, v136
	v_lshlrev_b32_e32 v21, 16, v137
	v_and_b32_e32 v23, 0xffff0000, v137
	v_mul_f32_e32 v14, 0xbfb8aa3b, v19
	v_mul_f32_e32 v27, 0xbfb8aa3b, v11
	v_mul_f32_e32 v28, 0xbfb8aa3b, v21
	v_mul_f32_e32 v29, 0xbfb8aa3b, v23
	v_exp_f32_e32 v14, v14
	v_exp_f32_e32 v27, v27
	v_exp_f32_e32 v28, v28
	v_exp_f32_e32 v29, v29
	v_add_f32_e32 v14, 1.0, v14
	v_add_f32_e32 v27, 1.0, v27
	v_add_f32_e32 v28, 1.0, v28
	v_add_f32_e32 v29, 1.0, v29
	v_rcp_f32_e32 v33, v14
	v_rcp_f32_e32 v35, v27
	v_rcp_f32_e32 v37, v28
	v_rcp_f32_e32 v39, v29
	v_pk_mul_f32 v[18:19], v[32:33], v[18:19]
	v_pk_mul_f32 v[10:11], v[34:35], v[10:11]
	v_pk_mul_f32 v[20:21], v[36:37], v[20:21]
	v_pk_mul_f32 v[22:23], v[38:39], v[22:23]
	v_mov_b32_e32 v28, v15
	s_waitcnt vmcnt(15)
	v_mul_f32_e32 v4, v142, v18
	v_mul_f32_e32 v5, v143, v10
	v_mul_f32_e32 v6, v144, v20
	v_mul_f32_e32 v7, v145, v22
	v_mul_f32_e32 v4, v4, v19
	v_mul_f32_e32 v5, v5, v11
	v_mul_f32_e32 v6, v6, v21
	v_mul_f32_e32 v7, v7, v23
	v_cvt_pk_bf16_f32 v4, v4, v5
	v_cvt_pk_bf16_f32 v5, v6, v7
	global_store_dwordx2 v[8:9], v[4:5], off
	ds_read2_b64 v[4:7], v26 offset0:56 offset1:60
	v_lshl_add_u64 v[18:19], v[12:13], 0, v[24:25]
	v_lshlrev_b32_e32 v23, 16, v139
	v_lshlrev_b32_e32 v21, 16, v138
	v_and_b32_e32 v25, 0xffff0000, v139
	s_waitcnt lgkmcnt(0)
	v_lshlrev_b32_e32 v22, 16, v5
	v_and_b32_e32 v24, 0xffff0000, v5
	v_and_b32_e32 v5, 0xffff0000, v138
	v_mul_f32_e32 v27, 0xbfb8aa3b, v5
	v_mul_f32_e32 v29, 0xbfb8aa3b, v23
	v_mul_f32_e32 v14, 0xbfb8aa3b, v21
	v_mul_f32_e32 v30, 0xbfb8aa3b, v25
	v_exp_f32_e32 v27, v27
	v_exp_f32_e32 v29, v29
	v_exp_f32_e32 v14, v14
	v_exp_f32_e32 v30, v30
	v_add_f32_e32 v31, 1.0, v27
	v_add_f32_e32 v33, 1.0, v29
	v_add_f32_e32 v14, 1.0, v14
	v_add_f32_e32 v30, 1.0, v30
	v_rcp_f32_e32 v29, v31
	v_rcp_f32_e32 v33, v33
	v_rcp_f32_e32 v27, v14
	v_rcp_f32_e32 v35, v30
	v_lshlrev_b32_e32 v20, 16, v4
	v_and_b32_e32 v4, 0xffff0000, v4
	v_mov_b32_e32 v26, v15
	v_pk_mul_f32 v[4:5], v[28:29], v[4:5]
	v_pk_mul_f32 v[22:23], v[32:33], v[22:23]
	v_pk_mul_f32 v[20:21], v[26:27], v[20:21]
	v_pk_mul_f32 v[24:25], v[34:35], v[24:25]
	v_lshlrev_b32_e32 v14, 16, v7
	s_waitcnt vmcnt(15)
	v_mul_f32_e32 v4, v147, v4
	v_mul_f32_e32 v9, v148, v22
	v_mul_f32_e32 v8, v146, v20
	v_mul_f32_e32 v10, v149, v24
	v_mul_f32_e32 v4, v4, v5
	v_mul_f32_e32 v5, v9, v23
	v_mul_f32_e32 v8, v8, v21
	v_mul_f32_e32 v9, v10, v25
	v_cvt_pk_bf16_f32 v4, v8, v4
	v_cvt_pk_bf16_f32 v5, v5, v9
	global_store_dwordx2 v[18:19], v[4:5], off
	v_lshl_add_u64 v[4:5], v[12:13], 0, v[2:3]
	v_and_b32_e32 v18, 0xffff0000, v7
	v_mov_b32_e32 v20, v15
	v_mov_b32_e32 v22, v15
	v_mov_b32_e32 v24, v15
	v_lshlrev_b32_e32 v13, 16, v140
	v_and_b32_e32 v7, 0xffff0000, v140
	v_lshlrev_b32_e32 v15, 16, v141
	v_and_b32_e32 v19, 0xffff0000, v141
	v_mul_f32_e32 v2, 0xbfb8aa3b, v13
	v_mul_f32_e32 v16, 0xbfb8aa3b, v7
	v_mul_f32_e32 v17, 0xbfb8aa3b, v15
	v_mul_f32_e32 v21, 0xbfb8aa3b, v19
	v_exp_f32_e32 v2, v2
	v_exp_f32_e32 v16, v16
	v_exp_f32_e32 v17, v17
	v_exp_f32_e32 v21, v21
	v_add_f32_e32 v2, 1.0, v2
	v_add_f32_e32 v16, 1.0, v16
	v_add_f32_e32 v17, 1.0, v17
	v_add_f32_e32 v27, 1.0, v21
	v_rcp_f32_e32 v21, v2
	v_rcp_f32_e32 v23, v16
	v_rcp_f32_e32 v25, v17
	v_rcp_f32_e32 v27, v27
	v_lshlrev_b32_e32 v12, 16, v6
	v_and_b32_e32 v6, 0xffff0000, v6
	v_pk_mul_f32 v[12:13], v[20:21], v[12:13]
	v_pk_mul_f32 v[6:7], v[22:23], v[6:7]
	v_pk_mul_f32 v[14:15], v[24:25], v[14:15]
	v_pk_mul_f32 v[16:17], v[26:27], v[18:19]
	v_readlane_b32 s4, v244, 32
	v_readlane_b32 s14, v244, 42
	v_readlane_b32 s15, v244, 43
	v_readlane_b32 s16, v244, 44
	v_readlane_b32 s17, v244, 45
	v_readlane_b32 s6, v244, 34
	s_mov_b32 s6, 0xbfb8aa3b
	s_mov_b32 s4, 0x3f2aaaab
	v_readlane_b32 s5, v244, 33
	s_mov_b32 s5, 0x3f317218
	v_readlane_b32 s7, v244, 35
	v_readlane_b32 s8, v244, 36
	v_readlane_b32 s9, v244, 37
	v_readlane_b32 s10, v244, 38
	v_readlane_b32 s11, v244, 39
	v_readlane_b32 s12, v244, 40
	v_readlane_b32 s13, v244, 41
	v_readlane_b32 s18, v244, 46
	v_readlane_b32 s19, v244, 47
	s_waitcnt vmcnt(15)
	v_mul_f32_e32 v2, v150, v12
	v_mul_f32_e32 v6, v151, v6
	v_mul_f32_e32 v8, v152, v14
	v_mul_f32_e32 v9, v153, v16
	v_mul_f32_e32 v6, v6, v7
	v_mul_f32_e32 v7, v8, v15
	v_mul_f32_e32 v2, v2, v13
	v_mul_f32_e32 v8, v9, v17
	v_cvt_pk_bf16_f32 v6, v2, v6
	v_cvt_pk_bf16_f32 v7, v7, v8
	global_store_dwordx2 v[4:5], v[6:7], off
	s_barrier
	s_nop 0
	v_ashrrev_i32_e32 v43, 31, v42
	v_lshlrev_b64 v[4:5], 2, v[42:43]
	v_lshl_add_u64 v[6:7], s[42:43], 0, v[4:5]
	global_load_dword v2, v[6:7], off
	v_lshl_add_u64 v[8:9], s[14:15], 0, v[4:5]
	v_add_co_u32_e32 v6, vcc, s0, v8
	v_bfe_u32 v43, v42, 4, 2
	s_nop 0
	v_addc_co_u32_e32 v7, vcc, 0, v9, vcc
	global_load_dword v14, v[8:9], off
	global_load_dword v15, v[8:9], off offset:2048
	global_load_dword v16, v[6:7], off
	global_load_dword v17, v[6:7], off offset:2048
	v_and_b32_e32 v18, 0xffffffc0, v42
	v_lshl_or_b32 v104, v43, 3, v18
	v_lshl_add_u64 v[18:19], s[16:17], 0, v[4:5]
	v_lshl_add_u64 v[20:21], s[36:37], 0, v[4:5]
	v_lshl_add_u64 v[4:5], s[40:41], 0, v[4:5]
	global_load_dword v18, v[18:19], off
	s_nop 0
	global_load_dword v19, v[20:21], off
	s_nop 0
	global_load_dword v20, v[4:5], off
	v_lshl_add_u32 v30, v42, 5, 0
	v_and_b32_e32 v195, 15, v42
	v_cmp_lt_u32_e32 vcc, 2, v195
	s_or_b64 s[0:1], s[22:23], vcc
	v_mov_b32_e32 v8, v3
	v_mov_b32_e32 v9, v3
	v_mov_b32_e32 v6, v3
	v_mov_b32_e32 v7, v3
	v_mov_b64_e32 v[12:13], v[8:9]
	v_mov_b64_e32 v[10:11], v[6:7]
	v_ashrrev_i32_e32 v105, 31, v104
	s_waitcnt vmcnt(7)
	v_mul_f32_e64 v4, |v2|, s6
	v_exp_f32_e32 v21, v4
	v_max_f32_e64 v2, -v2, -v2
	v_max_f32_e32 v2, 0, v2
	s_waitcnt vmcnt(3)
	ds_write_b128 v30, v[14:17]
	v_add_f32_e32 v14, 1.0, v21
	v_add_f32_e32 v15, -1.0, v14
	v_frexp_mant_f32_e32 v16, v14
	v_cvt_f64_f32_e32 v[4:5], v14
	v_sub_f32_e32 v17, v15, v14
	v_frexp_exp_i32_f64_e32 v4, v[4:5]
	v_cmp_gt_f32_e32 vcc, s4, v16
	v_sub_f32_e32 v15, v21, v15
	v_add_f32_e32 v5, 1.0, v17
	v_subbrev_co_u32_e32 v4, vcc, 0, v4, vcc
	v_add_f32_e32 v5, v15, v5
	v_sub_u32_e32 v15, 0, v4
	v_ldexp_f32 v14, v14, v15
	v_add_f32_e32 v16, -1.0, v14
	v_add_f32_e32 v17, 1.0, v14
	v_ldexp_f32 v5, v5, v15
	v_add_f32_e32 v15, 1.0, v16
	v_add_f32_e32 v22, -1.0, v17
	v_sub_f32_e32 v15, v14, v15
	v_sub_f32_e32 v14, v14, v22
	v_add_f32_e32 v22, v5, v15
	v_add_f32_e32 v5, v5, v14
	v_add_f32_e32 v24, v17, v5
	v_rcp_f32_e32 v25, v24
	v_add_f32_e32 v15, v16, v22
	v_sub_f32_e32 v16, v15, v16
	v_sub_f32_e32 v14, v24, v17
	v_mul_f32_e32 v27, v15, v25
	v_sub_f32_e32 v26, v22, v16
	v_mul_f32_e32 v16, v24, v27
	v_sub_f32_e32 v5, v5, v14
	v_fma_f32 v22, v27, v24, -v16
	v_fmac_f32_e32 v22, v27, v5
	v_add_f32_e32 v14, v16, v22
	v_sub_f32_e32 v17, v15, v14
	v_mov_b32_e32 v23, v14
	v_pk_add_f32 v[14:15], v[14:15], v[16:17] neg_lo:[0,1] neg_hi:[0,1]
	v_cvt_f32_i32_e32 v4, v4
	v_pk_add_f32 v[14:15], v[14:15], v[22:23] neg_lo:[0,1] neg_hi:[0,1]
	v_cmp_neq_f32_e32 vcc, s3, v21
	v_add_f32_e32 v15, v26, v15
	v_add_f32_e32 v14, v14, v15
	v_add_f32_e32 v15, v17, v14
	v_mul_f32_e32 v23, v25, v15
	v_mul_f32_e32 v16, v24, v23
	v_sub_f32_e32 v17, v17, v15
	v_add_f32_e32 v28, v27, v23
	v_fma_f32 v22, v23, v24, -v16
	v_add_f32_e32 v26, v14, v17
	v_sub_f32_e32 v14, v28, v27
	v_fmac_f32_e32 v22, v23, v5
	v_sub_f32_e32 v5, v23, v14
	v_add_f32_e32 v14, v16, v22
	v_sub_f32_e32 v17, v15, v14
	v_mov_b32_e32 v23, v14
	v_pk_add_f32 v[14:15], v[14:15], v[16:17] neg_lo:[0,1] neg_hi:[0,1]
	s_nop 0
	v_pk_add_f32 v[14:15], v[14:15], v[22:23] neg_lo:[0,1] neg_hi:[0,1]
	s_nop 0
	v_add_f32_e32 v15, v26, v15
	v_add_f32_e32 v14, v14, v15
	v_add_f32_e32 v14, v17, v14
	v_mul_f32_e32 v14, v25, v14
	v_add_f32_e32 v5, v5, v14
	v_add_f32_e32 v14, v28, v5
	v_mul_f32_e32 v16, v14, v14
	v_sub_f32_e32 v17, v14, v28
	v_fmamk_f32 v22, v16, 0x3e9b6dac, v181
	v_sub_f32_e32 v17, v5, v17
	v_mul_f32_e32 v5, v14, v16
	v_fmaak_f32 v113, v16, v22, 0x3f2aaada
	v_ldexp_f32 v23, v17, 1
	v_pk_mul_f32 v[16:17], v[4:5], v[112:113]
	v_ldexp_f32 v15, v14, 1
	v_fma_f32 v14, v4, s5, -v16
	v_fmac_f32_e32 v14, 0xb102e308, v4
	v_pk_add_f32 v[4:5], v[16:17], v[14:15]
	v_mov_b32_e32 v22, v16
	v_sub_f32_e32 v26, v5, v15
	v_pk_add_f32 v[24:25], v[4:5], v[16:17] neg_lo:[0,1] neg_hi:[0,1]
	v_sub_f32_e32 v16, v17, v26
	v_add_f32_e32 v23, v23, v16
	v_pk_add_f32 v[16:17], v[4:5], v[22:23]
	v_mov_b32_e32 v15, v4
	v_mov_b32_e32 v25, v17
	v_pk_add_f32 v[28:29], v[14:15], v[24:25] neg_lo:[0,1] neg_hi:[0,1]
	v_pk_add_f32 v[14:15], v[14:15], v[24:25]
	v_mov_b32_e32 v27, v4
	v_pk_add_f32 v[24:25], v[14:15], v[4:5] op_sel:[1,0] op_sel_hi:[0,1] neg_lo:[0,1] neg_hi:[0,1]
	v_mov_b32_e32 v26, v23
	v_mov_b32_e32 v22, v17
	v_mov_b32_e32 v23, v15
	v_pk_mov_b32 v[4:5], v[4:5], v[24:25] op_sel:[1,0]
	v_pk_add_f32 v[16:17], v[16:17], v[24:25] op_sel_hi:[1,0] neg_lo:[0,1] neg_hi:[0,1]
	v_pk_add_f32 v[4:5], v[22:23], v[4:5] neg_lo:[0,1] neg_hi:[0,1]
	v_mov_b32_e32 v16, v28
	v_pk_add_f32 v[4:5], v[26:27], v[4:5] neg_lo:[0,1] neg_hi:[0,1]
	v_mov_b32_e32 v29, v15
	v_pk_add_f32 v[16:17], v[16:17], v[4:5]
	s_nop 0
	v_pk_add_f32 v[22:23], v[16:17], v[16:17] op_sel:[0,1] op_sel_hi:[1,0]
	s_nop 0
	v_pk_add_f32 v[14:15], v[14:15], v[22:23] op_sel:[1,0] op_sel_hi:[0,1]
	v_mov_b32_e32 v17, v14
	v_mov_b32_e32 v5, v22
	v_pk_add_f32 v[22:23], v[16:17], v[28:29] neg_lo:[0,1] neg_hi:[0,1]
	s_nop 0
	v_sub_f32_e32 v15, v16, v22
	v_pk_add_f32 v[4:5], v[4:5], v[22:23] neg_lo:[0,1] neg_hi:[0,1]
	v_sub_f32_e32 v15, v28, v15
	v_add_f32_e32 v4, v4, v15
	v_add_f32_e32 v4, v4, v5
	v_add_f32_e32 v4, v14, v4
	v_cndmask_b32_e32 v4, v185, v4, vcc
	v_cmp_ngt_f32_e32 vcc, -1.0, v21
	v_mov_b64_e32 v[16:17], v[8:9]
	v_mov_b64_e32 v[14:15], v[6:7]
	v_cndmask_b32_e32 v4, v186, v4, vcc
	v_cmp_neq_f32_e32 vcc, -1.0, v21
	s_nop 1
	v_cndmask_b32_e32 v4, v187, v4, vcc
	v_cmp_lt_f32_e64 vcc, |v21|, s2
	s_nop 1
	v_cndmask_b32_e32 v4, v4, v21, vcc
	v_add_f32_e32 v2, v2, v4
	v_mul_f32_e32 v21, 0xc1000000, v2
	s_waitcnt vmcnt(0)
	ds_write_b128 v30, v[18:21] offset:16
	s_and_saveexec_b64 s[2:3], s[0:1]
	s_cbranch_execz .LBB0_217
	v_add3_u32 v2, s20, -3, v195
	v_mov_b64_e32 v[4:5], s[88:89]
	v_mad_i64_i32 v[4:5], s[0:1], v2, s92, v[4:5]
	v_lshl_add_u64 v[4:5], v[104:105], 1, v[4:5]
	global_load_dwordx4 v[14:17], v[4:5], off
	global_load_dwordx4 v[10:13], v[4:5], off offset:64

.LBB0_284:
	s_ashr_i32 s4, s23, 3
	s_cmp_lt_i32 s4, 1
	v_mov_b32_e32 v2, 0
	s_cbranch_scc1 .LBB0_292
	s_and_b32 s0, s22, 7
	s_lshl_b32 s2, s0, 17
	v_lshl_add_u64 v[10:11], v[24:25], 0, s[2:3]
	global_load_dword v185, v[10:11], off offset:-2048
	global_load_dword v186, v[10:11], off
	v_lshl_add_u64 v[10:11], v[10:11], 0, s[10:11]
	s_cmp_gt_u32 s4, 1
	s_cbranch_scc0 .Lp3_fold_wait
	global_load_dword v187, v[10:11], off offset:-2048
	global_load_dword v188, v[10:11], off
	v_lshl_add_u64 v[10:11], v[10:11], 0, s[10:11]
	s_cmp_gt_u32 s4, 2
	s_cbranch_scc0 .Lp3_fold_wait
	global_load_dword v189, v[10:11], off offset:-2048
	global_load_dword v190, v[10:11], off
	v_lshl_add_u64 v[10:11], v[10:11], 0, s[10:11]
	s_cmp_gt_u32 s4, 3
	s_cbranch_scc0 .Lp3_fold_wait
	global_load_dword v191, v[10:11], off offset:-2048
	global_load_dword v192, v[10:11], off
	v_lshl_add_u64 v[10:11], v[10:11], 0, s[10:11]
	s_cmp_gt_u32 s4, 4
	s_cbranch_scc0 .Lp3_fold_wait
	global_load_dword v193, v[10:11], off offset:-2048
	global_load_dword v194, v[10:11], off
	v_lshl_add_u64 v[10:11], v[10:11], 0, s[10:11]
	s_cmp_gt_u32 s4, 5
	s_cbranch_scc0 .Lp3_fold_wait
	global_load_dword v195, v[10:11], off offset:-2048
	global_load_dword v196, v[10:11], off
	v_lshl_add_u64 v[10:11], v[10:11], 0, s[10:11]
	s_cmp_gt_u32 s4, 6
	s_cbranch_scc0 .Lp3_fold_wait
	global_load_dword v197, v[10:11], off offset:-2048
	global_load_dword v198, v[10:11], off
	v_lshl_add_u64 v[10:11], v[10:11], 0, s[10:11]
	s_cmp_gt_u32 s4, 7
	s_cbranch_scc0 .Lp3_fold_wait
	global_load_dword v199, v[10:11], off offset:-2048
	global_load_dword v200, v[10:11], off
	v_lshl_add_u64 v[10:11], v[10:11], 0, s[10:11]
	s_cmp_gt_u32 s4, 8
	s_cbranch_scc0 .Lp3_fold_wait
	global_load_dword v201, v[10:11], off offset:-2048
	global_load_dword v202, v[10:11], off
	v_lshl_add_u64 v[10:11], v[10:11], 0, s[10:11]
	s_cmp_gt_u32 s4, 9
	s_cbranch_scc0 .Lp3_fold_wait
	global_load_dword v203, v[10:11], off offset:-2048
	global_load_dword v204, v[10:11], off
	v_lshl_add_u64 v[10:11], v[10:11], 0, s[10:11]
	s_cmp_gt_u32 s4, 10
	s_cbranch_scc0 .Lp3_fold_wait
	global_load_dword v205, v[10:11], off offset:-2048
	global_load_dword v206, v[10:11], off
	v_lshl_add_u64 v[10:11], v[10:11], 0, s[10:11]
	s_cmp_gt_u32 s4, 11
	s_cbranch_scc0 .Lp3_fold_wait
	global_load_dword v207, v[10:11], off offset:-2048
	global_load_dword v208, v[10:11], off
	v_lshl_add_u64 v[10:11], v[10:11], 0, s[10:11]
	s_cmp_gt_u32 s4, 12
	s_cbranch_scc0 .Lp3_fold_wait
	global_load_dword v209, v[10:11], off offset:-2048
	global_load_dword v210, v[10:11], off
	v_lshl_add_u64 v[10:11], v[10:11], 0, s[10:11]
	s_cmp_gt_u32 s4, 13
	s_cbranch_scc0 .Lp3_fold_wait
	global_load_dword v211, v[10:11], off offset:-2048
	global_load_dword v212, v[10:11], off
	v_lshl_add_u64 v[10:11], v[10:11], 0, s[10:11]
	s_cmp_gt_u32 s4, 14
	s_cbranch_scc0 .Lp3_fold_wait
	global_load_dword v213, v[10:11], off offset:-2048
	global_load_dword v214, v[10:11], off
	v_lshl_add_u64 v[10:11], v[10:11], 0, s[10:11]
	s_cmp_gt_u32 s4, 15
	s_cbranch_scc0 .Lp3_fold_wait
	global_load_dword v215, v[10:11], off offset:-2048
	global_load_dword v216, v[10:11], off
	v_lshl_add_u64 v[10:11], v[10:11], 0, s[10:11]
	s_cmp_gt_u32 s4, 16
	s_cbranch_scc0 .Lp3_fold_wait
	global_load_dword v217, v[10:11], off offset:-2048
	global_load_dword v218, v[10:11], off
	v_lshl_add_u64 v[10:11], v[10:11], 0, s[10:11]
	s_cmp_gt_u32 s4, 17
	s_cbranch_scc0 .Lp3_fold_wait
	global_load_dword v219, v[10:11], off offset:-2048
	global_load_dword v220, v[10:11], off
	v_lshl_add_u64 v[10:11], v[10:11], 0, s[10:11]
	s_cmp_gt_u32 s4, 18
	s_cbranch_scc0 .Lp3_fold_wait
	global_load_dword v221, v[10:11], off offset:-2048
	global_load_dword v222, v[10:11], off
	v_lshl_add_u64 v[10:11], v[10:11], 0, s[10:11]
	s_cmp_gt_u32 s4, 19
	s_cbranch_scc0 .Lp3_fold_wait
	global_load_dword v223, v[10:11], off offset:-2048
	global_load_dword v224, v[10:11], off
	v_lshl_add_u64 v[10:11], v[10:11], 0, s[10:11]
	s_cmp_gt_u32 s4, 20
	s_cbranch_scc0 .Lp3_fold_wait
	global_load_dword v225, v[10:11], off offset:-2048
	global_load_dword v226, v[10:11], off
	v_lshl_add_u64 v[10:11], v[10:11], 0, s[10:11]
	s_cmp_gt_u32 s4, 21
	s_cbranch_scc0 .Lp3_fold_wait
	global_load_dword v227, v[10:11], off offset:-2048
	global_load_dword v228, v[10:11], off
	v_lshl_add_u64 v[10:11], v[10:11], 0, s[10:11]
	s_cmp_gt_u32 s4, 22
	s_cbranch_scc0 .Lp3_fold_wait
	global_load_dword v229, v[10:11], off offset:-2048
	global_load_dword v230, v[10:11], off
	v_lshl_add_u64 v[10:11], v[10:11], 0, s[10:11]
	s_cmp_gt_u32 s4, 23
	s_cbranch_scc0 .Lp3_fold_wait
	global_load_dword v231, v[10:11], off offset:-2048
	global_load_dword v232, v[10:11], off
	v_lshl_add_u64 v[10:11], v[10:11], 0, s[10:11]
	s_cmp_gt_u32 s4, 24
	s_cbranch_scc0 .Lp3_fold_wait
	global_load_dword v233, v[10:11], off offset:-2048
	global_load_dword v234, v[10:11], off
	v_lshl_add_u64 v[10:11], v[10:11], 0, s[10:11]
	s_cmp_gt_u32 s4, 25
	s_cbranch_scc0 .Lp3_fold_wait
	global_load_dword v235, v[10:11], off offset:-2048
	global_load_dword v236, v[10:11], off
	v_lshl_add_u64 v[10:11], v[10:11], 0, s[10:11]
	s_cmp_gt_u32 s4, 26
	s_cbranch_scc0 .Lp3_fold_wait
	global_load_dword v237, v[10:11], off offset:-2048
	global_load_dword v238, v[10:11], off
	v_lshl_add_u64 v[10:11], v[10:11], 0, s[10:11]
	s_cmp_gt_u32 s4, 27
	s_cbranch_scc0 .Lp3_fold_wait
	global_load_dword v239, v[10:11], off offset:-2048
	global_load_dword v240, v[10:11], off
	v_lshl_add_u64 v[10:11], v[10:11], 0, s[10:11]
	s_cmp_gt_u32 s4, 28
	s_cbranch_scc0 .Lp3_fold_wait
	global_load_dword v241, v[10:11], off offset:-2048
	global_load_dword v242, v[10:11], off
	v_lshl_add_u64 v[10:11], v[10:11], 0, s[10:11]
	s_cmp_gt_u32 s4, 29
	s_cbranch_scc0 .Lp3_fold_wait
	global_load_dword v243, v[10:11], off offset:-2048
	global_load_dword v245, v[10:11], off
	v_lshl_add_u64 v[10:11], v[10:11], 0, s[10:11]
	s_cmp_gt_u32 s4, 30
	s_cbranch_scc0 .Lp3_fold_wait
	global_load_dword v246, v[10:11], off offset:-2048
	global_load_dword v247, v[10:11], off
.Lp3_fold_wait:
	s_waitcnt vmcnt(0)
	v_fma_f32 v2, v2, v185, v186
	s_cmp_gt_u32 s4, 1
	s_cbranch_scc0 .LBB0_292
	v_fma_f32 v2, v2, v187, v188
	s_cmp_gt_u32 s4, 2
	s_cbranch_scc0 .LBB0_292
	v_fma_f32 v2, v2, v189, v190
	s_cmp_gt_u32 s4, 3
	s_cbranch_scc0 .LBB0_292
	v_fma_f32 v2, v2, v191, v192
	s_cmp_gt_u32 s4, 4
	s_cbranch_scc0 .LBB0_292
	v_fma_f32 v2, v2, v193, v194
	s_cmp_gt_u32 s4, 5
	s_cbranch_scc0 .LBB0_292
	v_fma_f32 v2, v2, v195, v196
	s_cmp_gt_u32 s4, 6
	s_cbranch_scc0 .LBB0_292
	v_fma_f32 v2, v2, v197, v198
	s_cmp_gt_u32 s4, 7
	s_cbranch_scc0 .LBB0_292
	v_fma_f32 v2, v2, v199, v200
	s_cmp_gt_u32 s4, 8
	s_cbranch_scc0 .LBB0_292
	v_fma_f32 v2, v2, v201, v202
	s_cmp_gt_u32 s4, 9
	s_cbranch_scc0 .LBB0_292
	v_fma_f32 v2, v2, v203, v204
	s_cmp_gt_u32 s4, 10
	s_cbranch_scc0 .LBB0_292
	v_fma_f32 v2, v2, v205, v206
	s_cmp_gt_u32 s4, 11
	s_cbranch_scc0 .LBB0_292
	v_fma_f32 v2, v2, v207, v208
	s_cmp_gt_u32 s4, 12
	s_cbranch_scc0 .LBB0_292
	v_fma_f32 v2, v2, v209, v210
	s_cmp_gt_u32 s4, 13
	s_cbranch_scc0 .LBB0_292
	v_fma_f32 v2, v2, v211, v212
	s_cmp_gt_u32 s4, 14
	s_cbranch_scc0 .LBB0_292
	v_fma_f32 v2, v2, v213, v214
	s_cmp_gt_u32 s4, 15
	s_cbranch_scc0 .LBB0_292
	v_fma_f32 v2, v2, v215, v216
	s_cmp_gt_u32 s4, 16
	s_cbranch_scc0 .LBB0_292
	v_fma_f32 v2, v2, v217, v218
	s_cmp_gt_u32 s4, 17
	s_cbranch_scc0 .LBB0_292
	v_fma_f32 v2, v2, v219, v220
	s_cmp_gt_u32 s4, 18
	s_cbranch_scc0 .LBB0_292
	v_fma_f32 v2, v2, v221, v222
	s_cmp_gt_u32 s4, 19
	s_cbranch_scc0 .LBB0_292
	v_fma_f32 v2, v2, v223, v224
	s_cmp_gt_u32 s4, 20
	s_cbranch_scc0 .LBB0_292
	v_fma_f32 v2, v2, v225, v226
	s_cmp_gt_u32 s4, 21
	s_cbranch_scc0 .LBB0_292
	v_fma_f32 v2, v2, v227, v228
	s_cmp_gt_u32 s4, 22
	s_cbranch_scc0 .LBB0_292
	v_fma_f32 v2, v2, v229, v230
	s_cmp_gt_u32 s4, 23
	s_cbranch_scc0 .LBB0_292
	v_fma_f32 v2, v2, v231, v232
	s_cmp_gt_u32 s4, 24
	s_cbranch_scc0 .LBB0_292
	v_fma_f32 v2, v2, v233, v234
	s_cmp_gt_u32 s4, 25
	s_cbranch_scc0 .LBB0_292
	v_fma_f32 v2, v2, v235, v236
	s_cmp_gt_u32 s4, 26
	s_cbranch_scc0 .LBB0_292
	v_fma_f32 v2, v2, v237, v238
	s_cmp_gt_u32 s4, 27
	s_cbranch_scc0 .LBB0_292
	v_fma_f32 v2, v2, v239, v240
	s_cmp_gt_u32 s4, 28
	s_cbranch_scc0 .LBB0_292
	v_fma_f32 v2, v2, v241, v242
	s_cmp_gt_u32 s4, 29
	s_cbranch_scc0 .LBB0_292
	v_fma_f32 v2, v2, v243, v245
	s_cmp_gt_u32 s4, 30
	s_cbranch_scc0 .LBB0_292
	v_fma_f32 v2, v2, v246, v247

	.amdhsa_kernel _Z6k_mega6Params
		.amdhsa_group_segment_fixed_size 0
		.amdhsa_private_segment_fixed_size 0
		.amdhsa_kernarg_size 432
		.amdhsa_user_sgpr_count 2
		.amdhsa_user_sgpr_dispatch_ptr 0
		.amdhsa_user_sgpr_queue_ptr 0
		.amdhsa_user_sgpr_kernarg_segment_ptr 1
		.amdhsa_user_sgpr_dispatch_id 0
		.amdhsa_user_sgpr_kernarg_preload_length 0
		.amdhsa_user_sgpr_kernarg_preload_offset 0
		.amdhsa_user_sgpr_private_segment_size 0
		.amdhsa_uses_dynamic_stack 0
		.amdhsa_enable_private_segment 0
		.amdhsa_system_sgpr_workgroup_id_x 1
		.amdhsa_system_sgpr_workgroup_id_y 0
		.amdhsa_system_sgpr_workgroup_id_z 0
		.amdhsa_system_sgpr_workgroup_info 0
		.amdhsa_system_vgpr_workitem_id 0
		.amdhsa_next_free_vgpr 248
		.amdhsa_next_free_sgpr 100
		.amdhsa_accum_offset 248
		.amdhsa_reserve_vcc 1
		.amdhsa_float_round_mode_32 0
		.amdhsa_float_round_mode_16_64 0
		.amdhsa_float_denorm_mode_32 3
		.amdhsa_float_denorm_mode_16_64 3
		.amdhsa_dx10_clamp 1
		.amdhsa_ieee_mode 1
		.amdhsa_fp16_overflow 0
		.amdhsa_tg_split 0
		.amdhsa_exception_fp_ieee_invalid_op 0
		.amdhsa_exception_fp_denorm_src 0
		.amdhsa_exception_fp_ieee_div_zero 0
		.amdhsa_exception_fp_ieee_overflow 0
		.amdhsa_exception_fp_ieee_underflow 0
		.amdhsa_exception_fp_ieee_inexact 0
		.amdhsa_exception_int_div_zero 0
	.end_amdhsa_kernel

amdhsa.kernels:
  - .agpr_count:     0
    .args:
      - .offset:         0
        .size:           176
        .value_kind:     by_value
      - .offset:         176
        .size:           4
        .value_kind:     hidden_block_count_x
      - .offset:         180
        .size:           4
        .value_kind:     hidden_block_count_y
      - .offset:         184
        .size:           4
        .value_kind:     hidden_block_count_z
      - .offset:         188
        .size:           2
        .value_kind:     hidden_group_size_x
      - .offset:         190
        .size:           2
        .value_kind:     hidden_group_size_y
      - .offset:         192
        .size:           2
        .value_kind:     hidden_group_size_z
      - .offset:         194
        .size:           2
        .value_kind:     hidden_remainder_x
      - .offset:         196
        .size:           2
        .value_kind:     hidden_remainder_y
      - .offset:         198
        .size:           2
        .value_kind:     hidden_remainder_z
      - .offset:         216
        .size:           8
        .value_kind:     hidden_global_offset_x
      - .offset:         224
        .size:           8
        .value_kind:     hidden_global_offset_y
      - .offset:         232
        .size:           8
        .value_kind:     hidden_global_offset_z
      - .offset:         240
        .size:           2
        .value_kind:     hidden_grid_dims
      - .offset:         296
        .size:           4
        .value_kind:     hidden_dynamic_lds_size
    .group_segment_fixed_size: 0
    .kernarg_segment_align: 8
    .kernarg_segment_size: 432
    .language:       OpenCL C
    .language_version:
      - 2
      - 0
    .max_flat_workgroup_size: 512
    .name:           _Z6k_mega6Params
    .private_segment_fixed_size: 0
    .sgpr_count:     106
    .sgpr_spill_count: 101
    .symbol:         _Z6k_mega6Params.kd
    .uniform_work_group_size: 1
    .uses_dynamic_stack: false
    .vgpr_count:     248
    .vgpr_spill_count: 0
    .wavefront_size: 64
